# nt (streaming) hint on the P2 and P8 GEMM output stores so they do not displace reused operand tiles in L2
# speedup vs baseline: 1.0621x; 1.0063x over previous
.LBB0_98:
	s_or_b64 exec, exec, s[4:5]
	s_ashr_i32 s4, s11, 4
	s_ashr_i32 s5, s4, 31
	v_mov_b32_e32 v129, v211
	s_and_b32 s6, s11, 15
	s_lshl_b64 s[8:9], s[4:5], 18
	s_add_u32 s8, s30, s8
	v_ashrrev_i32_e32 v0, 3, v129
	v_ashrrev_i32_e32 v1, 31, v0
	s_addc_u32 s9, s31, s9
	v_lshlrev_b64 v[2:3], 11, v[0:1]
	v_lshlrev_b32_e32 v1, 4, v129
	v_lshl_add_u64 v[4:5], s[8:9], 0, v[2:3]
	v_and_b32_e32 v208, 0x70, v1
	s_lshl_b32 s7, s6, 18
	v_readlane_b32 s11, v252, 9
	v_lshl_add_u64 v[114:115], v[4:5], 0, v[208:209]
	s_mov_b32 s8, 0x10000
	s_add_u32 s12, s11, s7
	v_readlane_b32 s7, v252, 10
	v_add_co_u32_e32 v116, vcc, s8, v114
	s_addc_u32 s13, s7, 0
	s_nop 0
	v_addc_co_u32_e32 v117, vcc, 0, v115, vcc
	s_mov_b32 s7, 0x20000
	v_add_co_u32_e32 v118, vcc, s7, v114
	s_mov_b32 s9, 0x30000
	s_nop 0
	v_addc_co_u32_e32 v119, vcc, 0, v115, vcc
	v_add_co_u32_e32 v124, vcc, s9, v114
	v_lshl_add_u64 v[2:3], s[12:13], 0, v[2:3]
	s_nop 0
	v_addc_co_u32_e32 v125, vcc, 0, v115, vcc
	v_lshl_add_u64 v[112:113], v[2:3], 0, v[208:209]
	global_load_dwordx4 v[96:99], v[114:115], off
	global_load_dwordx4 v[100:103], v[116:117], off
	global_load_dwordx4 v[104:107], v[118:119], off
	global_load_dwordx4 v[108:111], v[124:125], off
	global_load_dwordx4 v[132:135], v[112:113], off
	v_add_co_u32_e32 v120, vcc, s8, v112
	v_mul_u32_u24_e32 v0, 0xa0, v0
	s_nop 0
	v_addc_co_u32_e32 v121, vcc, 0, v113, vcc
	v_add_co_u32_e32 v122, vcc, s7, v112
	global_load_dwordx4 v[136:139], v[120:121], off
	s_nop 0
	v_addc_co_u32_e32 v123, vcc, 0, v113, vcc
	v_add_co_u32_e32 v126, vcc, s9, v112
	global_load_dwordx4 v[140:143], v[122:123], off
	s_nop 0
	v_addc_co_u32_e32 v127, vcc, 0, v113, vcc
	global_load_dwordx4 v[144:147], v[126:127], off
	global_load_dwordx4 v[32:35], v[114:115], off offset:128
	global_load_dwordx4 v[36:39], v[114:115], off offset:256
	global_load_dwordx4 v[40:43], v[116:117], off offset:128
	global_load_dwordx4 v[44:47], v[118:119], off offset:128
	global_load_dwordx4 v[48:51], v[124:125], off offset:128
	global_load_dwordx4 v[64:67], v[112:113], off offset:128
	global_load_dwordx4 v[52:55], v[116:117], off offset:256
	global_load_dwordx4 v[56:59], v[118:119], off offset:256
	global_load_dwordx4 v[60:63], v[124:125], off offset:256
	global_load_dwordx4 v[68:71], v[112:113], off offset:256
	global_load_dwordx4 v[76:79], v[120:121], off offset:128
	global_load_dwordx4 v[80:83], v[122:123], off offset:128
	global_load_dwordx4 v[84:87], v[126:127], off offset:128
	global_load_dwordx4 v[72:75], v[120:121], off offset:256
	global_load_dwordx4 v[88:91], v[122:123], off offset:256
	global_load_dwordx4 v[92:95], v[126:127], off offset:256
	v_add3_u32 v130, 0, v0, v208
	s_barrier
	global_load_dwordx4 v[0:3], v[126:127], off offset:384
	global_load_dwordx4 v[4:7], v[122:123], off offset:384
	global_load_dwordx4 v[8:11], v[120:121], off offset:384
	global_load_dwordx4 v[12:15], v[112:113], off offset:384
	global_load_dwordx4 v[16:19], v[124:125], off offset:384
	global_load_dwordx4 v[20:23], v[118:119], off offset:384
	global_load_dwordx4 v[24:27], v[116:117], off offset:384
	global_load_dwordx4 v[28:31], v[114:115], off offset:384
	s_lshl_b64 s[4:5], s[4:5], 19
	s_add_u32 s4, s20, s4
	s_addc_u32 s5, s21, s5
	s_lshl_b32 s6, s6, 8
	s_add_u32 s4, s4, s6
	s_addc_u32 s5, s5, 0
	s_waitcnt vmcnt(31)
	ds_write_b128 v130, v[96:99]
	s_waitcnt vmcnt(30)
	ds_write_b128 v130, v[100:103] offset:5120
	s_waitcnt vmcnt(29)
	ds_write_b128 v130, v[104:107] offset:10240
	s_waitcnt vmcnt(28)
	ds_write_b128 v130, v[108:111] offset:15360
	s_waitcnt vmcnt(27)
	ds_write_b128 v130, v[132:135] offset:20480
	s_waitcnt vmcnt(26)
	ds_write_b128 v130, v[136:139] offset:25600
	s_waitcnt vmcnt(25)
	ds_write_b128 v130, v[140:143] offset:30720
	s_waitcnt vmcnt(24)
	ds_write_b128 v130, v[144:147] offset:35840
	v_and_b32_e32 v96, 15, v129
	v_lshrrev_b32_e32 v97, 1, v129
	v_and_or_b32 v96, v97, s43, v96
	v_mul_u32_u24_e32 v96, 0xa0, v96
	v_and_b32_e32 v100, 48, v129
	v_add3_u32 v131, 0, v96, v100
	s_waitcnt lgkmcnt(0)
	s_barrier
	v_and_b32_e32 v101, 0x4f, v129
	ds_read_b128 v[96:99], v131
	ds_read_b128 v[184:187], v131 offset:64
	ds_read_b128 v[148:151], v131 offset:2560
	ds_read_b128 v[164:167], v131 offset:5120
	ds_read_b128 v[180:183], v131 offset:7680
	v_mul_u32_u24_e32 v101, 0x50, v101
	v_lshlrev_b32_e32 v101, 1, v101
	v_add3_u32 v129, 0, v101, v100
	v_add_u32_e32 v129, 0x5000, v129
	ds_read_b128 v[100:103], v129
	ds_read_b128 v[108:111], v129 offset:2560
	ds_read_b128 v[136:139], v129 offset:5120
	ds_read_b128 v[196:199], v129 offset:5184
	ds_read_b128 v[144:147], v129 offset:7680
	ds_read_b128 v[200:203], v129 offset:7744
	s_waitcnt lgkmcnt(5)
	v_mfma_f32_16x16x32_bf16 v[104:107], v[96:99], v[100:103], 0
	ds_read_b128 v[188:191], v129 offset:2624
	s_waitcnt lgkmcnt(5)
	v_mfma_f32_16x16x32_bf16 v[132:135], v[96:99], v[108:111], 0
	s_waitcnt lgkmcnt(4)
	v_mfma_f32_16x16x32_bf16 v[140:143], v[96:99], v[136:139], 0
	s_waitcnt lgkmcnt(2)
	v_mfma_f32_16x16x32_bf16 v[96:99], v[96:99], v[144:147], 0
	v_mfma_f32_16x16x32_bf16 v[152:155], v[148:151], v[100:103], 0
	v_mfma_f32_16x16x32_bf16 v[156:159], v[148:151], v[108:111], 0
	v_mfma_f32_16x16x32_bf16 v[160:163], v[148:151], v[136:139], 0
	v_mfma_f32_16x16x32_bf16 v[148:151], v[148:151], v[144:147], 0
	v_mfma_f32_16x16x32_bf16 v[168:171], v[164:167], v[100:103], 0
	v_mfma_f32_16x16x32_bf16 v[172:175], v[164:167], v[108:111], 0
	v_mfma_f32_16x16x32_bf16 v[176:179], v[164:167], v[136:139], 0
	v_mfma_f32_16x16x32_bf16 v[164:167], v[164:167], v[144:147], 0
	v_mfma_f32_16x16x32_bf16 v[100:103], v[180:183], v[100:103], 0
	v_mfma_f32_16x16x32_bf16 v[108:111], v[180:183], v[108:111], 0
	v_mfma_f32_16x16x32_bf16 v[136:139], v[180:183], v[136:139], 0
	v_mfma_f32_16x16x32_bf16 v[144:147], v[180:183], v[144:147], 0
	ds_read_b128 v[180:183], v129 offset:64
	s_waitcnt lgkmcnt(1)
	v_mfma_f32_16x16x32_bf16 v[192:195], v[184:187], v[188:191], v[132:135]
	s_nop 2
	ds_read_b128 v[132:135], v131 offset:2624
	s_waitcnt lgkmcnt(1)
	v_mfma_f32_16x16x32_bf16 v[104:107], v[184:187], v[180:183], v[104:107]
	v_mfma_f32_16x16x32_bf16 v[140:143], v[184:187], v[196:199], v[140:143]
	v_mfma_f32_16x16x32_bf16 v[96:99], v[184:187], v[200:203], v[96:99]
	ds_read_b128 v[184:187], v131 offset:7744
	s_waitcnt lgkmcnt(1)
	v_mfma_f32_16x16x32_bf16 v[152:155], v[132:135], v[180:183], v[152:155]
	v_mfma_f32_16x16x32_bf16 v[156:159], v[132:135], v[188:191], v[156:159]
	v_mfma_f32_16x16x32_bf16 v[160:163], v[132:135], v[196:199], v[160:163]
	v_mfma_f32_16x16x32_bf16 v[148:151], v[132:135], v[200:203], v[148:151]
	ds_read_b128 v[132:135], v131 offset:5184
	s_waitcnt lgkmcnt(0)
	v_mfma_f32_16x16x32_bf16 v[168:171], v[132:135], v[180:183], v[168:171]
	v_mfma_f32_16x16x32_bf16 v[172:175], v[132:135], v[188:191], v[172:175]
	v_mfma_f32_16x16x32_bf16 v[176:179], v[132:135], v[196:199], v[176:179]
	v_mfma_f32_16x16x32_bf16 v[164:167], v[132:135], v[200:203], v[164:167]
	v_add_u32_e32 v132, 0xf000, v130
	s_waitcnt vmcnt(23)
	ds_write_b128 v130, v[32:35] offset:40960
	s_waitcnt vmcnt(21)
	ds_write_b128 v130, v[40:43] offset:46080
	s_waitcnt vmcnt(20)
	ds_write_b128 v130, v[44:47] offset:51200
	s_waitcnt vmcnt(19)
	ds_write_b128 v130, v[48:51] offset:56320
	s_waitcnt vmcnt(18)
	ds_write_b128 v130, v[64:67] offset:61440
	s_waitcnt vmcnt(13)
	ds_write_b128 v132, v[76:79] offset:5120
	s_waitcnt vmcnt(12)
	ds_write_b128 v132, v[80:83] offset:10240
	s_waitcnt vmcnt(11)
	ds_write_b128 v132, v[84:87] offset:15360
	global_load_dwordx4 v[32:35], v[114:115], off offset:512
	global_load_dwordx4 v[40:43], v[116:117], off offset:512
	global_load_dwordx4 v[44:47], v[118:119], off offset:512
	global_load_dwordx4 v[48:51], v[124:125], off offset:512
	global_load_dwordx4 v[64:67], v[112:113], off offset:512
	global_load_dwordx4 v[76:79], v[120:121], off offset:512
	global_load_dwordx4 v[80:83], v[122:123], off offset:512
	global_load_dwordx4 v[84:87], v[126:127], off offset:512
	v_mfma_f32_16x16x32_bf16 v[100:103], v[184:187], v[180:183], v[100:103]
	s_waitcnt lgkmcnt(0)
	s_barrier
	ds_read_b128 v[180:183], v131 offset:40960
	ds_read_b128 v[204:207], v131 offset:48704
	v_mfma_f32_16x16x32_bf16 v[108:111], v[184:187], v[188:191], v[108:111]
	ds_read_b128 v[188:191], v129 offset:43520
	v_mfma_f32_16x16x32_bf16 v[134:137], v[184:187], v[196:199], v[136:139]
	ds_read_b128 v[196:199], v129 offset:46080
	v_mfma_f32_16x16x32_bf16 v[144:147], v[184:187], v[200:203], v[144:147]
	ds_read_b128 v[184:187], v129 offset:40960
	ds_read_b128 v[200:203], v129 offset:48640
	s_waitcnt lgkmcnt(1)
	v_mfma_f32_16x16x32_bf16 v[104:107], v[180:183], v[184:187], v[104:107]
	v_mfma_f32_16x16x32_bf16 v[192:195], v[180:183], v[188:191], v[192:195]
	v_mfma_f32_16x16x32_bf16 v[138:141], v[180:183], v[196:199], v[140:143]
	s_waitcnt lgkmcnt(0)
	v_mfma_f32_16x16x32_bf16 v[96:99], v[180:183], v[200:203], v[96:99]
	ds_read_b128 v[180:183], v131 offset:43520
	s_waitcnt lgkmcnt(0)
	v_mfma_f32_16x16x32_bf16 v[152:155], v[180:183], v[184:187], v[152:155]
	v_mfma_f32_16x16x32_bf16 v[156:159], v[180:183], v[188:191], v[156:159]
	v_mfma_f32_16x16x32_bf16 v[160:163], v[180:183], v[196:199], v[160:163]
	v_mfma_f32_16x16x32_bf16 v[148:151], v[180:183], v[200:203], v[148:151]
	ds_read_b128 v[180:183], v131 offset:46080
	s_waitcnt lgkmcnt(0)
	v_mfma_f32_16x16x32_bf16 v[168:171], v[180:183], v[184:187], v[168:171]
	v_mfma_f32_16x16x32_bf16 v[172:175], v[180:183], v[188:191], v[172:175]
	v_mfma_f32_16x16x32_bf16 v[176:179], v[180:183], v[196:199], v[176:179]
	v_mfma_f32_16x16x32_bf16 v[164:167], v[180:183], v[200:203], v[164:167]
	ds_read_b128 v[180:183], v131 offset:48640
	s_waitcnt lgkmcnt(0)
	v_mfma_f32_16x16x32_bf16 v[100:103], v[180:183], v[184:187], v[100:103]
	ds_read_b128 v[184:187], v131 offset:41024
	v_mfma_f32_16x16x32_bf16 v[108:111], v[180:183], v[188:191], v[108:111]
	ds_read_b128 v[188:191], v129 offset:43584
	v_mfma_f32_16x16x32_bf16 v[134:137], v[180:183], v[196:199], v[134:137]
	ds_read_b128 v[196:199], v129 offset:46144
	v_mfma_f32_16x16x32_bf16 v[142:145], v[180:183], v[200:203], v[144:147]
	ds_read_b128 v[180:183], v129 offset:41024
	ds_read_b128 v[200:203], v129 offset:48704
	s_waitcnt lgkmcnt(1)
	v_mfma_f32_16x16x32_bf16 v[104:107], v[184:187], v[180:183], v[104:107]
	v_mfma_f32_16x16x32_bf16 v[192:195], v[184:187], v[188:191], v[192:195]
	v_mfma_f32_16x16x32_bf16 v[138:141], v[184:187], v[196:199], v[138:141]
	s_waitcnt lgkmcnt(0)
	v_mfma_f32_16x16x32_bf16 v[184:187], v[184:187], v[200:203], v[96:99]
	s_nop 2
	ds_read_b128 v[96:99], v131 offset:43584
	s_waitcnt lgkmcnt(0)
	v_mfma_f32_16x16x32_bf16 v[152:155], v[96:99], v[180:183], v[152:155]
	v_mfma_f32_16x16x32_bf16 v[156:159], v[96:99], v[188:191], v[156:159]
	v_mfma_f32_16x16x32_bf16 v[160:163], v[96:99], v[196:199], v[160:163]
	v_mfma_f32_16x16x32_bf16 v[146:149], v[96:99], v[200:203], v[148:151]
	ds_read_b128 v[96:99], v131 offset:46144
	ds_write_b128 v130, v[36:39]
	ds_write_b128 v130, v[52:55] offset:5120
	ds_write_b128 v130, v[56:59] offset:10240
	ds_write_b128 v130, v[60:63] offset:15360
	ds_write_b128 v130, v[68:71] offset:20480
	s_waitcnt vmcnt(18)
	ds_write_b128 v130, v[72:75] offset:25600
	s_waitcnt vmcnt(17)
	ds_write_b128 v130, v[88:91] offset:30720
	s_waitcnt vmcnt(16)
	ds_write_b128 v130, v[92:95] offset:35840
	s_waitcnt lgkmcnt(8)
	v_mfma_f32_16x16x32_bf16 v[168:171], v[96:99], v[180:183], v[168:171]
	v_mfma_f32_16x16x32_bf16 v[172:175], v[96:99], v[188:191], v[172:175]
	v_mfma_f32_16x16x32_bf16 v[176:179], v[96:99], v[196:199], v[176:179]
	v_mfma_f32_16x16x32_bf16 v[164:167], v[96:99], v[200:203], v[164:167]
	global_load_dwordx4 v[36:39], v[114:115], off offset:640
	global_load_dwordx4 v[52:55], v[116:117], off offset:640
	global_load_dwordx4 v[56:59], v[118:119], off offset:640
	global_load_dwordx4 v[60:63], v[124:125], off offset:640
	global_load_dwordx4 v[68:71], v[112:113], off offset:640
	global_load_dwordx4 v[88:91], v[120:121], off offset:640
	global_load_dwordx4 v[92:95], v[122:123], off offset:640
	global_load_dwordx4 v[96:99], v[126:127], off offset:640
	s_waitcnt lgkmcnt(0)
	s_barrier
	ds_read_b128 v[72:75], v131
	v_mfma_f32_16x16x32_bf16 v[100:103], v[204:207], v[180:183], v[100:103]
	ds_read_b128 v[180:183], v129
	v_mfma_f32_16x16x32_bf16 v[108:111], v[204:207], v[188:191], v[108:111]
	ds_read_b128 v[188:191], v129 offset:2560
	v_mfma_f32_16x16x32_bf16 v[134:137], v[204:207], v[196:199], v[134:137]
	ds_read_b128 v[196:199], v129 offset:5120
	v_mfma_f32_16x16x32_bf16 v[142:145], v[204:207], v[200:203], v[142:145]
	ds_read_b128 v[200:203], v129 offset:7680
	ds_read_b128 v[204:207], v131 offset:7744
	s_waitcnt lgkmcnt(4)
	v_mfma_f32_16x16x32_bf16 v[104:107], v[72:75], v[180:183], v[104:107]
	s_waitcnt lgkmcnt(3)
	v_mfma_f32_16x16x32_bf16 v[192:195], v[72:75], v[188:191], v[192:195]
	s_waitcnt lgkmcnt(2)
	v_mfma_f32_16x16x32_bf16 v[138:141], v[72:75], v[196:199], v[138:141]
	s_waitcnt lgkmcnt(1)
	v_mfma_f32_16x16x32_bf16 v[72:75], v[72:75], v[200:203], v[184:187]
	s_nop 2
	ds_read_b128 v[184:187], v131 offset:2560
	s_waitcnt lgkmcnt(0)
	v_mfma_f32_16x16x32_bf16 v[150:153], v[184:187], v[180:183], v[152:155]
	v_mfma_f32_16x16x32_bf16 v[154:157], v[184:187], v[188:191], v[156:159]
	v_mfma_f32_16x16x32_bf16 v[158:161], v[184:187], v[196:199], v[160:163]
	v_mfma_f32_16x16x32_bf16 v[146:149], v[184:187], v[200:203], v[146:149]
	ds_read_b128 v[184:187], v131 offset:5120
	s_waitcnt lgkmcnt(0)
	v_mfma_f32_16x16x32_bf16 v[168:171], v[184:187], v[180:183], v[168:171]
	v_mfma_f32_16x16x32_bf16 v[172:175], v[184:187], v[188:191], v[172:175]
	v_mfma_f32_16x16x32_bf16 v[176:179], v[184:187], v[196:199], v[176:179]
	v_mfma_f32_16x16x32_bf16 v[162:165], v[184:187], v[200:203], v[164:167]
	ds_read_b128 v[184:187], v131 offset:7680
	s_waitcnt lgkmcnt(0)
	v_mfma_f32_16x16x32_bf16 v[100:103], v[184:187], v[180:183], v[100:103]
	ds_read_b128 v[180:183], v131 offset:64
	v_mfma_f32_16x16x32_bf16 v[108:111], v[184:187], v[188:191], v[108:111]
	v_mfma_f32_16x16x32_bf16 v[134:137], v[184:187], v[196:199], v[134:137]
	ds_read_b128 v[196:199], v129 offset:5184
	v_mfma_f32_16x16x32_bf16 v[142:145], v[184:187], v[200:203], v[142:145]
	ds_read_b128 v[184:187], v129 offset:64
	ds_read_b128 v[200:203], v129 offset:7744
	s_waitcnt lgkmcnt(1)
	v_mfma_f32_16x16x32_bf16 v[188:191], v[180:183], v[184:187], v[104:107]
	s_nop 2
	ds_read_b128 v[104:107], v129 offset:2624
	s_waitcnt lgkmcnt(0)
	v_mfma_f32_16x16x32_bf16 v[192:195], v[180:183], v[104:107], v[192:195]
	v_mfma_f32_16x16x32_bf16 v[138:141], v[180:183], v[196:199], v[138:141]
	v_mfma_f32_16x16x32_bf16 v[180:183], v[180:183], v[200:203], v[72:75]
	s_nop 2
	ds_read_b128 v[72:75], v131 offset:2624
	s_waitcnt lgkmcnt(0)
	v_mfma_f32_16x16x32_bf16 v[150:153], v[72:75], v[184:187], v[150:153]
	v_mfma_f32_16x16x32_bf16 v[154:157], v[72:75], v[104:107], v[154:157]
	v_mfma_f32_16x16x32_bf16 v[158:161], v[72:75], v[196:199], v[158:161]
	v_mfma_f32_16x16x32_bf16 v[146:149], v[72:75], v[200:203], v[146:149]
	ds_read_b128 v[72:75], v131 offset:5184
	s_waitcnt vmcnt(16)
	ds_write_b128 v130, v[28:31] offset:40960
	ds_write_b128 v130, v[24:27] offset:46080
	ds_write_b128 v130, v[20:23] offset:51200
	ds_write_b128 v130, v[16:19] offset:56320
	ds_write_b128 v130, v[12:15] offset:61440
	ds_write_b128 v132, v[8:11] offset:5120
	ds_write_b128 v132, v[4:7] offset:10240
	ds_write_b128 v132, v[0:3] offset:15360
	s_waitcnt lgkmcnt(8)
	v_mfma_f32_16x16x32_bf16 v[166:169], v[72:75], v[184:187], v[168:171]
	v_mfma_f32_16x16x32_bf16 v[170:173], v[72:75], v[104:107], v[172:175]
	v_mfma_f32_16x16x32_bf16 v[174:177], v[72:75], v[196:199], v[176:179]
	v_mfma_f32_16x16x32_bf16 v[162:165], v[72:75], v[200:203], v[162:165]
	v_mfma_f32_16x16x32_bf16 v[184:187], v[204:207], v[184:187], v[100:103]
	v_mfma_f32_16x16x32_bf16 v[212:215], v[204:207], v[104:107], v[108:111]
	global_load_dwordx4 v[0:3], v[114:115], off offset:768
	global_load_dwordx4 v[12:15], v[116:117], off offset:768
	global_load_dwordx4 v[16:19], v[118:119], off offset:768
	global_load_dwordx4 v[20:23], v[124:125], off offset:768
	global_load_dwordx4 v[72:75], v[112:113], off offset:768
	global_load_dwordx4 v[100:103], v[120:121], off offset:768
	global_load_dwordx4 v[104:107], v[122:123], off offset:768
	global_load_dwordx4 v[108:111], v[126:127], off offset:768
	s_waitcnt lgkmcnt(0)
	s_barrier
	ds_read_b128 v[4:7], v131 offset:40960
	v_mfma_f32_16x16x32_bf16 v[8:11], v[204:207], v[200:203], v[142:145]
	ds_read_b128 v[24:27], v129 offset:40960
	ds_read_b128 v[200:203], v129 offset:48704
	s_nop 0
	ds_read_b128 v[142:145], v129 offset:43520
	v_mfma_f32_16x16x32_bf16 v[134:137], v[204:207], v[196:199], v[134:137]
	ds_read_b128 v[196:199], v129 offset:48640
	ds_read_b128 v[204:207], v131 offset:48704
	s_waitcnt lgkmcnt(4)
	v_mfma_f32_16x16x32_bf16 v[28:31], v[4:7], v[24:27], v[188:191]
	s_waitcnt lgkmcnt(2)
	v_mfma_f32_16x16x32_bf16 v[188:191], v[4:7], v[142:145], v[192:195]
	s_nop 2
	ds_read_b128 v[192:195], v129 offset:46080
	s_waitcnt lgkmcnt(0)
	v_mfma_f32_16x16x32_bf16 v[138:141], v[4:7], v[192:195], v[138:141]
	v_mfma_f32_16x16x32_bf16 v[4:7], v[4:7], v[196:199], v[180:183]
	s_nop 2
	ds_read_b128 v[178:181], v131 offset:43520
	s_waitcnt lgkmcnt(0)
	v_mfma_f32_16x16x32_bf16 v[150:153], v[178:181], v[24:27], v[150:153]
	v_mfma_f32_16x16x32_bf16 v[154:157], v[178:181], v[142:145], v[154:157]
	v_mfma_f32_16x16x32_bf16 v[158:161], v[178:181], v[192:195], v[158:161]
	v_mfma_f32_16x16x32_bf16 v[146:149], v[178:181], v[196:199], v[146:149]
	ds_read_b128 v[178:181], v131 offset:46080
	s_waitcnt lgkmcnt(0)
	v_mfma_f32_16x16x32_bf16 v[166:169], v[178:181], v[24:27], v[166:169]
	v_mfma_f32_16x16x32_bf16 v[170:173], v[178:181], v[142:145], v[170:173]
	v_mfma_f32_16x16x32_bf16 v[174:177], v[178:181], v[192:195], v[174:177]
	v_mfma_f32_16x16x32_bf16 v[162:165], v[178:181], v[196:199], v[162:165]
	ds_read_b128 v[178:181], v131 offset:48640
	s_waitcnt lgkmcnt(0)
	v_mfma_f32_16x16x32_bf16 v[24:27], v[178:181], v[24:27], v[184:187]
	s_nop 2
	ds_read_b128 v[182:185], v131 offset:41024
	v_mfma_f32_16x16x32_bf16 v[142:145], v[178:181], v[142:145], v[212:215]
	v_mfma_f32_16x16x32_bf16 v[134:137], v[178:181], v[192:195], v[134:137]
	v_mfma_f32_16x16x32_bf16 v[8:11], v[178:181], v[196:199], v[8:11]
	ds_read_b128 v[178:181], v129 offset:41024
	ds_read_b128 v[196:199], v129 offset:46144
	s_waitcnt lgkmcnt(1)
	v_mfma_f32_16x16x32_bf16 v[192:195], v[182:185], v[178:181], v[28:31]
	s_nop 2
	ds_read_b128 v[28:31], v129 offset:43584
	s_waitcnt lgkmcnt(0)
	v_mfma_f32_16x16x32_bf16 v[186:189], v[182:185], v[28:31], v[188:191]
	v_mfma_f32_16x16x32_bf16 v[138:141], v[182:185], v[196:199], v[138:141]
	v_mfma_f32_16x16x32_bf16 v[182:185], v[182:185], v[200:203], v[4:7]
	s_nop 2
	ds_read_b128 v[4:7], v131 offset:43584
	s_waitcnt lgkmcnt(0)
	v_mfma_f32_16x16x32_bf16 v[150:153], v[4:7], v[178:181], v[150:153]
	v_mfma_f32_16x16x32_bf16 v[154:157], v[4:7], v[28:31], v[154:157]
	v_mfma_f32_16x16x32_bf16 v[158:161], v[4:7], v[196:199], v[158:161]
	v_mfma_f32_16x16x32_bf16 v[146:149], v[4:7], v[200:203], v[146:149]
	ds_read_b128 v[4:7], v131 offset:46144
	s_waitcnt vmcnt(23)
	ds_write_b128 v130, v[32:35]
	s_waitcnt vmcnt(22)
	ds_write_b128 v130, v[40:43] offset:5120
	s_waitcnt vmcnt(21)
	ds_write_b128 v130, v[44:47] offset:10240
	s_waitcnt vmcnt(20)
	ds_write_b128 v130, v[48:51] offset:15360
	s_waitcnt vmcnt(19)
	ds_write_b128 v130, v[64:67] offset:20480
	s_waitcnt vmcnt(18)
	ds_write_b128 v130, v[76:79] offset:25600
	s_waitcnt vmcnt(17)
	ds_write_b128 v130, v[80:83] offset:30720
	s_waitcnt vmcnt(16)
	ds_write_b128 v130, v[84:87] offset:35840
	s_waitcnt lgkmcnt(8)
	v_mfma_f32_16x16x32_bf16 v[166:169], v[4:7], v[178:181], v[166:169]
	v_mfma_f32_16x16x32_bf16 v[170:173], v[4:7], v[28:31], v[170:173]
	v_mfma_f32_16x16x32_bf16 v[174:177], v[4:7], v[196:199], v[174:177]
	v_mfma_f32_16x16x32_bf16 v[162:165], v[4:7], v[200:203], v[162:165]
	v_mfma_f32_16x16x32_bf16 v[178:181], v[204:207], v[178:181], v[24:27]
	v_mfma_f32_16x16x32_bf16 v[142:145], v[204:207], v[28:31], v[142:145]
	global_load_dwordx4 v[4:7], v[114:115], off offset:896
	s_nop 0
	global_load_dwordx4 v[24:27], v[116:117], off offset:896
	global_load_dwordx4 v[28:31], v[118:119], off offset:896
	global_load_dwordx4 v[32:35], v[124:125], off offset:896
	global_load_dwordx4 v[48:51], v[112:113], off offset:896
	global_load_dwordx4 v[64:67], v[120:121], off offset:896
	global_load_dwordx4 v[76:79], v[122:123], off offset:896
	global_load_dwordx4 v[80:83], v[126:127], off offset:896
	s_waitcnt lgkmcnt(0)
	s_barrier
	ds_read_b128 v[40:43], v131
	ds_read_b128 v[44:47], v129
	v_mfma_f32_16x16x32_bf16 v[134:137], v[204:207], v[196:199], v[134:137]
	v_mfma_f32_16x16x32_bf16 v[8:11], v[204:207], v[200:203], v[8:11]
	ds_read_b128 v[198:201], v129 offset:7680
	ds_read_b128 v[202:205], v131 offset:7744
	s_waitcnt lgkmcnt(2)
	v_mfma_f32_16x16x32_bf16 v[84:87], v[40:43], v[44:47], v[192:195]
	s_nop 2
	ds_read_b128 v[190:193], v129 offset:2560
	ds_read_b128 v[194:197], v129 offset:5120
	s_waitcnt lgkmcnt(1)
	v_mfma_f32_16x16x32_bf16 v[186:189], v[40:43], v[190:193], v[186:189]
	s_waitcnt lgkmcnt(0)
	v_mfma_f32_16x16x32_bf16 v[138:141], v[40:43], v[194:197], v[138:141]
	v_mfma_f32_16x16x32_bf16 v[40:43], v[40:43], v[198:201], v[182:185]
	s_nop 2
	ds_read_b128 v[182:185], v131 offset:2560
	s_waitcnt lgkmcnt(0)
	v_mfma_f32_16x16x32_bf16 v[150:153], v[182:185], v[44:47], v[150:153]
	v_mfma_f32_16x16x32_bf16 v[154:157], v[182:185], v[190:193], v[154:157]
	v_mfma_f32_16x16x32_bf16 v[158:161], v[182:185], v[194:197], v[158:161]
	v_mfma_f32_16x16x32_bf16 v[146:149], v[182:185], v[198:201], v[146:149]
	ds_read_b128 v[182:185], v131 offset:5120
	s_waitcnt lgkmcnt(0)
	v_mfma_f32_16x16x32_bf16 v[166:169], v[182:185], v[44:47], v[166:169]
	v_mfma_f32_16x16x32_bf16 v[170:173], v[182:185], v[190:193], v[170:173]
	v_mfma_f32_16x16x32_bf16 v[174:177], v[182:185], v[194:197], v[174:177]
	v_mfma_f32_16x16x32_bf16 v[162:165], v[182:185], v[198:201], v[162:165]
	ds_read_b128 v[182:185], v131 offset:7680
	s_waitcnt lgkmcnt(0)
	v_mfma_f32_16x16x32_bf16 v[44:47], v[182:185], v[44:47], v[178:181]
	s_nop 2
	ds_read_b128 v[178:181], v131 offset:64
	v_mfma_f32_16x16x32_bf16 v[142:145], v[182:185], v[190:193], v[142:145]
	v_mfma_f32_16x16x32_bf16 v[134:137], v[182:185], v[194:197], v[134:137]
	ds_read_b128 v[194:197], v129 offset:5184
	v_mfma_f32_16x16x32_bf16 v[182:185], v[182:185], v[198:201], v[8:11]
	ds_read_b128 v[198:201], v129 offset:7744
	s_nop 1
	ds_read_b128 v[8:11], v129 offset:64
	s_waitcnt lgkmcnt(0)
	v_mfma_f32_16x16x32_bf16 v[190:193], v[178:181], v[8:11], v[84:87]
	s_nop 2
	ds_read_b128 v[84:87], v129 offset:2624
	s_waitcnt lgkmcnt(0)
	v_mfma_f32_16x16x32_bf16 v[186:189], v[178:181], v[84:87], v[186:189]
	v_mfma_f32_16x16x32_bf16 v[138:141], v[178:181], v[194:197], v[138:141]
	v_mfma_f32_16x16x32_bf16 v[178:181], v[178:181], v[198:201], v[40:43]
	s_nop 2
	ds_read_b128 v[40:43], v131 offset:2624
	s_waitcnt lgkmcnt(0)
	v_mfma_f32_16x16x32_bf16 v[150:153], v[40:43], v[8:11], v[150:153]
	v_mfma_f32_16x16x32_bf16 v[154:157], v[40:43], v[84:87], v[154:157]
	v_mfma_f32_16x16x32_bf16 v[158:161], v[40:43], v[194:197], v[158:161]
	v_mfma_f32_16x16x32_bf16 v[146:149], v[40:43], v[198:201], v[146:149]
	ds_read_b128 v[40:43], v131 offset:5184
	s_waitcnt vmcnt(23)
	ds_write_b128 v130, v[36:39] offset:40960
	s_waitcnt vmcnt(22)
	ds_write_b128 v130, v[52:55] offset:46080
	s_waitcnt vmcnt(21)
	ds_write_b128 v130, v[56:59] offset:51200
	s_waitcnt vmcnt(20)
	ds_write_b128 v130, v[60:63] offset:56320
	s_waitcnt vmcnt(19)
	ds_write_b128 v130, v[68:71] offset:61440
	s_waitcnt vmcnt(18)
	ds_write_b128 v132, v[88:91] offset:5120
	s_waitcnt vmcnt(17)
	ds_write_b128 v132, v[92:95] offset:10240
	s_waitcnt vmcnt(16)
	ds_write_b128 v132, v[96:99] offset:15360
	s_waitcnt lgkmcnt(8)
	v_mfma_f32_16x16x32_bf16 v[166:169], v[40:43], v[8:11], v[166:169]
	v_mfma_f32_16x16x32_bf16 v[170:173], v[40:43], v[84:87], v[170:173]
	v_mfma_f32_16x16x32_bf16 v[174:177], v[40:43], v[194:197], v[174:177]
	v_mfma_f32_16x16x32_bf16 v[162:165], v[40:43], v[198:201], v[162:165]
	v_mfma_f32_16x16x32_bf16 v[212:215], v[202:205], v[8:11], v[44:47]
	v_mfma_f32_16x16x32_bf16 v[142:145], v[202:205], v[84:87], v[142:145]
	global_load_dwordx4 v[8:11], v[114:115], off offset:1024
	global_load_dwordx4 v[36:39], v[116:117], off offset:1024
	global_load_dwordx4 v[40:43], v[118:119], off offset:1024
	global_load_dwordx4 v[44:47], v[124:125], off offset:1024
	global_load_dwordx4 v[52:55], v[112:113], off offset:1024
	global_load_dwordx4 v[60:63], v[120:121], off offset:1024
	global_load_dwordx4 v[68:71], v[122:123], off offset:1024
	global_load_dwordx4 v[84:87], v[126:127], off offset:1024
	s_waitcnt lgkmcnt(0)
	s_barrier
	ds_read_b128 v[56:59], v131 offset:40960
	ds_read_b128 v[92:95], v129 offset:40960
	v_mfma_f32_16x16x32_bf16 v[134:137], v[202:205], v[194:197], v[134:137]
	ds_read_b128 v[194:197], v129 offset:48640
	v_mfma_f32_16x16x32_bf16 v[88:91], v[202:205], v[198:201], v[182:185]
	ds_read_b128 v[202:205], v131 offset:48704
	ds_read_b128 v[198:201], v129 offset:48704
	s_nop 0
	ds_read_b128 v[182:185], v129 offset:43520
	s_waitcnt lgkmcnt(4)
	v_mfma_f32_16x16x32_bf16 v[96:99], v[56:59], v[92:95], v[190:193]
	s_nop 2
	ds_read_b128 v[190:193], v129 offset:46080
	s_waitcnt lgkmcnt(1)
	v_mfma_f32_16x16x32_bf16 v[186:189], v[56:59], v[182:185], v[186:189]
	s_waitcnt lgkmcnt(0)
	v_mfma_f32_16x16x32_bf16 v[138:141], v[56:59], v[190:193], v[138:141]
	v_mfma_f32_16x16x32_bf16 v[56:59], v[56:59], v[194:197], v[178:181]
	s_nop 2
	ds_read_b128 v[178:181], v131 offset:43520
	s_waitcnt lgkmcnt(0)
	v_mfma_f32_16x16x32_bf16 v[150:153], v[178:181], v[92:95], v[150:153]
	v_mfma_f32_16x16x32_bf16 v[154:157], v[178:181], v[182:185], v[154:157]
	v_mfma_f32_16x16x32_bf16 v[158:161], v[178:181], v[190:193], v[158:161]
	v_mfma_f32_16x16x32_bf16 v[146:149], v[178:181], v[194:197], v[146:149]
	ds_read_b128 v[178:181], v131 offset:46080
	s_waitcnt lgkmcnt(0)
	v_mfma_f32_16x16x32_bf16 v[166:169], v[178:181], v[92:95], v[166:169]
	v_mfma_f32_16x16x32_bf16 v[170:173], v[178:181], v[182:185], v[170:173]
	v_mfma_f32_16x16x32_bf16 v[174:177], v[178:181], v[190:193], v[174:177]
	v_mfma_f32_16x16x32_bf16 v[162:165], v[178:181], v[194:197], v[162:165]
	ds_read_b128 v[178:181], v131 offset:48640
	s_waitcnt lgkmcnt(0)
	v_mfma_f32_16x16x32_bf16 v[142:145], v[178:181], v[182:185], v[142:145]
	ds_read_b128 v[182:185], v131 offset:41024
	v_mfma_f32_16x16x32_bf16 v[92:95], v[178:181], v[92:95], v[212:215]
	v_mfma_f32_16x16x32_bf16 v[134:137], v[178:181], v[190:193], v[134:137]
	ds_read_b128 v[190:193], v129 offset:43584
	v_mfma_f32_16x16x32_bf16 v[178:181], v[178:181], v[194:197], v[88:91]
	ds_read_b128 v[194:197], v129 offset:46144
	s_nop 1
	ds_read_b128 v[88:91], v129 offset:41024
	s_waitcnt lgkmcnt(0)
	v_mfma_f32_16x16x32_bf16 v[96:99], v[182:185], v[88:91], v[96:99]
	v_mfma_f32_16x16x32_bf16 v[186:189], v[182:185], v[190:193], v[186:189]
	v_mfma_f32_16x16x32_bf16 v[138:141], v[182:185], v[194:197], v[138:141]
	v_mfma_f32_16x16x32_bf16 v[182:185], v[182:185], v[198:201], v[56:59]
	s_nop 2
	ds_read_b128 v[56:59], v131 offset:43584
	s_waitcnt lgkmcnt(0)
	v_mfma_f32_16x16x32_bf16 v[150:153], v[56:59], v[88:91], v[150:153]
	v_mfma_f32_16x16x32_bf16 v[154:157], v[56:59], v[190:193], v[154:157]
	v_mfma_f32_16x16x32_bf16 v[158:161], v[56:59], v[194:197], v[158:161]
	v_mfma_f32_16x16x32_bf16 v[146:149], v[56:59], v[198:201], v[146:149]
	ds_read_b128 v[56:59], v131 offset:46144
	s_waitcnt vmcnt(23)
	ds_write_b128 v130, v[0:3]
	s_waitcnt vmcnt(22)
	ds_write_b128 v130, v[12:15] offset:5120
	s_waitcnt vmcnt(21)
	ds_write_b128 v130, v[16:19] offset:10240
	s_waitcnt vmcnt(20)
	ds_write_b128 v130, v[20:23] offset:15360
	s_waitcnt vmcnt(19)
	ds_write_b128 v130, v[72:75] offset:20480
	s_waitcnt vmcnt(18)
	ds_write_b128 v130, v[100:103] offset:25600
	s_waitcnt vmcnt(17)
	ds_write_b128 v130, v[104:107] offset:30720
	s_waitcnt vmcnt(16)
	ds_write_b128 v130, v[108:111] offset:35840
	s_waitcnt lgkmcnt(8)
	v_mfma_f32_16x16x32_bf16 v[166:169], v[56:59], v[88:91], v[166:169]
	v_mfma_f32_16x16x32_bf16 v[170:173], v[56:59], v[190:193], v[170:173]
	v_mfma_f32_16x16x32_bf16 v[174:177], v[56:59], v[194:197], v[174:177]
	v_mfma_f32_16x16x32_bf16 v[162:165], v[56:59], v[198:201], v[162:165]
	v_mfma_f32_16x16x32_bf16 v[212:215], v[202:205], v[88:91], v[92:95]
	global_load_dwordx4 v[0:3], v[114:115], off offset:1152
	global_load_dwordx4 v[12:15], v[116:117], off offset:1152
	global_load_dwordx4 v[16:19], v[118:119], off offset:1152
	global_load_dwordx4 v[20:23], v[124:125], off offset:1152
	global_load_dwordx4 v[56:59], v[112:113], off offset:1152
	global_load_dwordx4 v[72:75], v[120:121], off offset:1152
	global_load_dwordx4 v[88:91], v[122:123], off offset:1152
	global_load_dwordx4 v[92:95], v[126:127], off offset:1152
	s_waitcnt lgkmcnt(0)
	s_barrier
	ds_read_b128 v[100:103], v131
	v_mfma_f32_16x16x32_bf16 v[142:145], v[202:205], v[190:193], v[142:145]
	ds_read_b128 v[108:111], v129
	ds_read_b128 v[190:193], v129 offset:5120
	v_mfma_f32_16x16x32_bf16 v[134:137], v[202:205], v[194:197], v[134:137]
	ds_read_b128 v[194:197], v129 offset:7680
	v_mfma_f32_16x16x32_bf16 v[104:107], v[202:205], v[198:201], v[178:181]
	ds_read_b128 v[198:201], v129 offset:7744
	s_nop 1
	ds_read_b128 v[178:181], v129 offset:2560
	s_waitcnt lgkmcnt(4)
	v_mfma_f32_16x16x32_bf16 v[96:99], v[100:103], v[108:111], v[96:99]
	s_waitcnt lgkmcnt(0)
	v_mfma_f32_16x16x32_bf16 v[186:189], v[100:103], v[178:181], v[186:189]
	v_mfma_f32_16x16x32_bf16 v[138:141], v[100:103], v[190:193], v[138:141]
	v_mfma_f32_16x16x32_bf16 v[100:103], v[100:103], v[194:197], v[182:185]
	s_nop 2
	ds_read_b128 v[182:185], v131 offset:2560
	s_waitcnt lgkmcnt(0)
	v_mfma_f32_16x16x32_bf16 v[150:153], v[182:185], v[108:111], v[150:153]
	v_mfma_f32_16x16x32_bf16 v[154:157], v[182:185], v[178:181], v[154:157]
	v_mfma_f32_16x16x32_bf16 v[158:161], v[182:185], v[190:193], v[158:161]
	v_mfma_f32_16x16x32_bf16 v[146:149], v[182:185], v[194:197], v[146:149]
	ds_read_b128 v[182:185], v131 offset:5120
	s_waitcnt lgkmcnt(0)
	v_mfma_f32_16x16x32_bf16 v[166:169], v[182:185], v[108:111], v[166:169]
	v_mfma_f32_16x16x32_bf16 v[170:173], v[182:185], v[178:181], v[170:173]
	v_mfma_f32_16x16x32_bf16 v[174:177], v[182:185], v[190:193], v[174:177]
	v_mfma_f32_16x16x32_bf16 v[162:165], v[182:185], v[194:197], v[162:165]
	ds_read_b128 v[182:185], v131 offset:7680
	s_waitcnt lgkmcnt(0)
	v_mfma_f32_16x16x32_bf16 v[142:145], v[182:185], v[178:181], v[142:145]
	ds_read_b128 v[178:181], v131 offset:64
	v_mfma_f32_16x16x32_bf16 v[108:111], v[182:185], v[108:111], v[212:215]
	v_mfma_f32_16x16x32_bf16 v[134:137], v[182:185], v[190:193], v[134:137]
	ds_read_b128 v[190:193], v129 offset:2624
	v_mfma_f32_16x16x32_bf16 v[104:107], v[182:185], v[194:197], v[104:107]
	ds_read_b128 v[182:185], v129 offset:64
	ds_read_b128 v[194:197], v129 offset:5184
	s_waitcnt lgkmcnt(1)
	v_mfma_f32_16x16x32_bf16 v[96:99], v[178:181], v[182:185], v[96:99]
	v_mfma_f32_16x16x32_bf16 v[186:189], v[178:181], v[190:193], v[186:189]
	s_waitcnt lgkmcnt(0)
	v_mfma_f32_16x16x32_bf16 v[138:141], v[178:181], v[194:197], v[138:141]
	v_mfma_f32_16x16x32_bf16 v[100:103], v[178:181], v[198:201], v[100:103]
	ds_read_b128 v[178:181], v131 offset:2624
	s_waitcnt lgkmcnt(0)
	v_mfma_f32_16x16x32_bf16 v[150:153], v[178:181], v[182:185], v[150:153]
	v_mfma_f32_16x16x32_bf16 v[154:157], v[178:181], v[190:193], v[154:157]
	v_mfma_f32_16x16x32_bf16 v[158:161], v[178:181], v[194:197], v[158:161]
	v_mfma_f32_16x16x32_bf16 v[146:149], v[178:181], v[198:201], v[146:149]
	ds_read_b128 v[178:181], v131 offset:5184
	s_waitcnt lgkmcnt(0)
	v_mfma_f32_16x16x32_bf16 v[166:169], v[178:181], v[182:185], v[166:169]
	v_mfma_f32_16x16x32_bf16 v[170:173], v[178:181], v[190:193], v[170:173]
	v_mfma_f32_16x16x32_bf16 v[174:177], v[178:181], v[194:197], v[174:177]
	v_mfma_f32_16x16x32_bf16 v[162:165], v[178:181], v[198:201], v[162:165]
	ds_read_b128 v[178:181], v131 offset:7744
	s_waitcnt vmcnt(23)
	ds_write_b128 v130, v[4:7] offset:40960
	s_waitcnt vmcnt(22)
	ds_write_b128 v130, v[24:27] offset:46080
	s_waitcnt vmcnt(21)
	ds_write_b128 v130, v[28:31] offset:51200
	s_waitcnt vmcnt(20)
	ds_write_b128 v130, v[32:35] offset:56320
	s_waitcnt vmcnt(19)
	ds_write_b128 v130, v[48:51] offset:61440
	s_waitcnt vmcnt(18)
	ds_write_b128 v132, v[64:67] offset:5120
	s_waitcnt vmcnt(17)
	ds_write_b128 v132, v[76:79] offset:10240
	s_waitcnt vmcnt(16)
	ds_write_b128 v132, v[80:83] offset:15360
	global_load_dwordx4 v[4:7], v[114:115], off offset:1280
	global_load_dwordx4 v[24:27], v[116:117], off offset:1280
	global_load_dwordx4 v[28:31], v[118:119], off offset:1280
	global_load_dwordx4 v[32:35], v[124:125], off offset:1280
	global_load_dwordx4 v[48:51], v[112:113], off offset:1280
	global_load_dwordx4 v[64:67], v[120:121], off offset:1280
	global_load_dwordx4 v[76:79], v[122:123], off offset:1280
	global_load_dwordx4 v[80:83], v[126:127], off offset:1280
	s_waitcnt lgkmcnt(8)
	v_mfma_f32_16x16x32_bf16 v[108:111], v[178:181], v[182:185], v[108:111]
	s_waitcnt lgkmcnt(0)
	s_barrier
	ds_read_b128 v[182:185], v131 offset:40960
	v_mfma_f32_16x16x32_bf16 v[142:145], v[178:181], v[190:193], v[142:145]
	ds_read_b128 v[190:193], v129 offset:43520
	v_mfma_f32_16x16x32_bf16 v[134:137], v[178:181], v[194:197], v[134:137]
	ds_read_b128 v[194:197], v129 offset:46080
	v_mfma_f32_16x16x32_bf16 v[104:107], v[178:181], v[198:201], v[104:107]
	ds_read_b128 v[178:181], v129 offset:40960
	ds_read_b128 v[198:201], v129 offset:48640
	s_waitcnt lgkmcnt(1)
	v_mfma_f32_16x16x32_bf16 v[96:99], v[182:185], v[178:181], v[96:99]
	v_mfma_f32_16x16x32_bf16 v[186:189], v[182:185], v[190:193], v[186:189]
	v_mfma_f32_16x16x32_bf16 v[138:141], v[182:185], v[194:197], v[138:141]
	s_waitcnt lgkmcnt(0)
	v_mfma_f32_16x16x32_bf16 v[100:103], v[182:185], v[198:201], v[100:103]
	ds_read_b128 v[182:185], v131 offset:43520
	s_waitcnt lgkmcnt(0)
	v_mfma_f32_16x16x32_bf16 v[150:153], v[182:185], v[178:181], v[150:153]
	v_mfma_f32_16x16x32_bf16 v[154:157], v[182:185], v[190:193], v[154:157]
	v_mfma_f32_16x16x32_bf16 v[158:161], v[182:185], v[194:197], v[158:161]
	v_mfma_f32_16x16x32_bf16 v[146:149], v[182:185], v[198:201], v[146:149]
	ds_read_b128 v[182:185], v131 offset:46080
	s_waitcnt lgkmcnt(0)
	v_mfma_f32_16x16x32_bf16 v[166:169], v[182:185], v[178:181], v[166:169]
	v_mfma_f32_16x16x32_bf16 v[170:173], v[182:185], v[190:193], v[170:173]
	v_mfma_f32_16x16x32_bf16 v[174:177], v[182:185], v[194:197], v[174:177]
	v_mfma_f32_16x16x32_bf16 v[162:165], v[182:185], v[198:201], v[162:165]
	ds_read_b128 v[182:185], v131 offset:48640
	s_waitcnt lgkmcnt(0)
	v_mfma_f32_16x16x32_bf16 v[108:111], v[182:185], v[178:181], v[108:111]
	ds_read_b128 v[178:181], v131 offset:41024
	v_mfma_f32_16x16x32_bf16 v[142:145], v[182:185], v[190:193], v[142:145]
	ds_read_b128 v[190:193], v129 offset:43584
	v_mfma_f32_16x16x32_bf16 v[134:137], v[182:185], v[194:197], v[134:137]
	ds_read_b128 v[194:197], v129 offset:46144
	v_mfma_f32_16x16x32_bf16 v[104:107], v[182:185], v[198:201], v[104:107]
	ds_read_b128 v[182:185], v129 offset:41024
	ds_read_b128 v[198:201], v129 offset:48704
	s_waitcnt lgkmcnt(1)
	v_mfma_f32_16x16x32_bf16 v[96:99], v[178:181], v[182:185], v[96:99]
	v_mfma_f32_16x16x32_bf16 v[186:189], v[178:181], v[190:193], v[186:189]
	v_mfma_f32_16x16x32_bf16 v[138:141], v[178:181], v[194:197], v[138:141]
	s_waitcnt lgkmcnt(0)
	v_mfma_f32_16x16x32_bf16 v[100:103], v[178:181], v[198:201], v[100:103]
	ds_read_b128 v[178:181], v131 offset:43584
	s_waitcnt lgkmcnt(0)
	v_mfma_f32_16x16x32_bf16 v[150:153], v[178:181], v[182:185], v[150:153]
	v_mfma_f32_16x16x32_bf16 v[154:157], v[178:181], v[190:193], v[154:157]
	v_mfma_f32_16x16x32_bf16 v[158:161], v[178:181], v[194:197], v[158:161]
	v_mfma_f32_16x16x32_bf16 v[146:149], v[178:181], v[198:201], v[146:149]
	ds_read_b128 v[178:181], v131 offset:46144
	s_waitcnt lgkmcnt(0)
	v_mfma_f32_16x16x32_bf16 v[166:169], v[178:181], v[182:185], v[166:169]
	v_mfma_f32_16x16x32_bf16 v[170:173], v[178:181], v[190:193], v[170:173]
	v_mfma_f32_16x16x32_bf16 v[174:177], v[178:181], v[194:197], v[174:177]
	v_mfma_f32_16x16x32_bf16 v[162:165], v[178:181], v[198:201], v[162:165]
	ds_read_b128 v[178:181], v131 offset:48704
	s_waitcnt vmcnt(23)
	ds_write_b128 v130, v[8:11]
	s_waitcnt vmcnt(22)
	ds_write_b128 v130, v[36:39] offset:5120
	s_waitcnt vmcnt(21)
	ds_write_b128 v130, v[40:43] offset:10240
	s_waitcnt vmcnt(20)
	ds_write_b128 v130, v[44:47] offset:15360
	s_waitcnt vmcnt(19)
	ds_write_b128 v130, v[52:55] offset:20480
	s_waitcnt vmcnt(18)
	ds_write_b128 v130, v[60:63] offset:25600
	s_waitcnt vmcnt(17)
	ds_write_b128 v130, v[68:71] offset:30720
	s_waitcnt vmcnt(16)
	ds_write_b128 v130, v[84:87] offset:35840
	global_load_dwordx4 v[8:11], v[114:115], off offset:1408
	global_load_dwordx4 v[36:39], v[116:117], off offset:1408
	global_load_dwordx4 v[40:43], v[118:119], off offset:1408
	global_load_dwordx4 v[44:47], v[124:125], off offset:1408
	global_load_dwordx4 v[52:55], v[112:113], off offset:1408
	global_load_dwordx4 v[60:63], v[120:121], off offset:1408
	global_load_dwordx4 v[68:71], v[122:123], off offset:1408
	global_load_dwordx4 v[84:87], v[126:127], off offset:1408
	s_waitcnt lgkmcnt(8)
	v_mfma_f32_16x16x32_bf16 v[108:111], v[178:181], v[182:185], v[108:111]
	s_waitcnt lgkmcnt(0)
	s_barrier
	ds_read_b128 v[182:185], v131
	v_mfma_f32_16x16x32_bf16 v[142:145], v[178:181], v[190:193], v[142:145]
	ds_read_b128 v[190:193], v129 offset:2560
	v_mfma_f32_16x16x32_bf16 v[134:137], v[178:181], v[194:197], v[134:137]
	ds_read_b128 v[194:197], v129 offset:5120
	v_mfma_f32_16x16x32_bf16 v[104:107], v[178:181], v[198:201], v[104:107]
	ds_read_b128 v[178:181], v129
	ds_read_b128 v[198:201], v129 offset:7680
	s_waitcnt lgkmcnt(1)
	v_mfma_f32_16x16x32_bf16 v[96:99], v[182:185], v[178:181], v[96:99]
	v_mfma_f32_16x16x32_bf16 v[186:189], v[182:185], v[190:193], v[186:189]
	v_mfma_f32_16x16x32_bf16 v[138:141], v[182:185], v[194:197], v[138:141]
	s_waitcnt lgkmcnt(0)
	v_mfma_f32_16x16x32_bf16 v[100:103], v[182:185], v[198:201], v[100:103]
	ds_read_b128 v[182:185], v131 offset:2560
	s_waitcnt lgkmcnt(0)
	v_mfma_f32_16x16x32_bf16 v[150:153], v[182:185], v[178:181], v[150:153]
	v_mfma_f32_16x16x32_bf16 v[154:157], v[182:185], v[190:193], v[154:157]
	v_mfma_f32_16x16x32_bf16 v[158:161], v[182:185], v[194:197], v[158:161]
	v_mfma_f32_16x16x32_bf16 v[146:149], v[182:185], v[198:201], v[146:149]
	ds_read_b128 v[182:185], v131 offset:5120
	s_waitcnt lgkmcnt(0)
	v_mfma_f32_16x16x32_bf16 v[166:169], v[182:185], v[178:181], v[166:169]
	v_mfma_f32_16x16x32_bf16 v[170:173], v[182:185], v[190:193], v[170:173]
	v_mfma_f32_16x16x32_bf16 v[174:177], v[182:185], v[194:197], v[174:177]
	v_mfma_f32_16x16x32_bf16 v[162:165], v[182:185], v[198:201], v[162:165]
	ds_read_b128 v[182:185], v131 offset:7680
	s_waitcnt lgkmcnt(0)
	v_mfma_f32_16x16x32_bf16 v[108:111], v[182:185], v[178:181], v[108:111]
	ds_read_b128 v[178:181], v131 offset:64
	v_mfma_f32_16x16x32_bf16 v[142:145], v[182:185], v[190:193], v[142:145]
	ds_read_b128 v[190:193], v129 offset:2624
	v_mfma_f32_16x16x32_bf16 v[134:137], v[182:185], v[194:197], v[134:137]
	ds_read_b128 v[194:197], v129 offset:5184
	v_mfma_f32_16x16x32_bf16 v[104:107], v[182:185], v[198:201], v[104:107]
	ds_read_b128 v[182:185], v129 offset:64
	ds_read_b128 v[198:201], v129 offset:7744
	s_waitcnt lgkmcnt(1)
	v_mfma_f32_16x16x32_bf16 v[96:99], v[178:181], v[182:185], v[96:99]
	v_mfma_f32_16x16x32_bf16 v[186:189], v[178:181], v[190:193], v[186:189]
	v_mfma_f32_16x16x32_bf16 v[138:141], v[178:181], v[194:197], v[138:141]
	s_waitcnt lgkmcnt(0)
	v_mfma_f32_16x16x32_bf16 v[100:103], v[178:181], v[198:201], v[100:103]
	ds_read_b128 v[178:181], v131 offset:2624
	s_waitcnt lgkmcnt(0)
	v_mfma_f32_16x16x32_bf16 v[150:153], v[178:181], v[182:185], v[150:153]
	v_mfma_f32_16x16x32_bf16 v[154:157], v[178:181], v[190:193], v[154:157]
	v_mfma_f32_16x16x32_bf16 v[158:161], v[178:181], v[194:197], v[158:161]
	v_mfma_f32_16x16x32_bf16 v[146:149], v[178:181], v[198:201], v[146:149]
	ds_read_b128 v[178:181], v131 offset:5184
	s_waitcnt lgkmcnt(0)
	v_mfma_f32_16x16x32_bf16 v[166:169], v[178:181], v[182:185], v[166:169]
	v_mfma_f32_16x16x32_bf16 v[170:173], v[178:181], v[190:193], v[170:173]
	v_mfma_f32_16x16x32_bf16 v[174:177], v[178:181], v[194:197], v[174:177]
	v_mfma_f32_16x16x32_bf16 v[162:165], v[178:181], v[198:201], v[162:165]
	ds_read_b128 v[178:181], v131 offset:7744
	s_waitcnt vmcnt(23)
	ds_write_b128 v130, v[0:3] offset:40960
	s_waitcnt vmcnt(22)
	ds_write_b128 v130, v[12:15] offset:46080
	s_waitcnt vmcnt(21)
	ds_write_b128 v130, v[16:19] offset:51200
	s_waitcnt vmcnt(20)
	ds_write_b128 v130, v[20:23] offset:56320
	s_waitcnt vmcnt(19)
	ds_write_b128 v130, v[56:59] offset:61440
	s_waitcnt vmcnt(18)
	ds_write_b128 v132, v[72:75] offset:5120
	s_waitcnt vmcnt(17)
	ds_write_b128 v132, v[88:91] offset:10240
	s_waitcnt vmcnt(16)
	ds_write_b128 v132, v[92:95] offset:15360
	global_load_dwordx4 v[0:3], v[114:115], off offset:1536
	global_load_dwordx4 v[12:15], v[116:117], off offset:1536
	global_load_dwordx4 v[16:19], v[118:119], off offset:1536
	global_load_dwordx4 v[20:23], v[124:125], off offset:1536
	global_load_dwordx4 v[56:59], v[112:113], off offset:1536
	global_load_dwordx4 v[72:75], v[120:121], off offset:1536
	global_load_dwordx4 v[88:91], v[122:123], off offset:1536
	global_load_dwordx4 v[92:95], v[126:127], off offset:1536
	s_waitcnt lgkmcnt(8)
	v_mfma_f32_16x16x32_bf16 v[108:111], v[178:181], v[182:185], v[108:111]
	s_waitcnt lgkmcnt(0)
	s_barrier
	ds_read_b128 v[182:185], v131 offset:40960
	v_mfma_f32_16x16x32_bf16 v[142:145], v[178:181], v[190:193], v[142:145]
	ds_read_b128 v[190:193], v129 offset:43520
	v_mfma_f32_16x16x32_bf16 v[134:137], v[178:181], v[194:197], v[134:137]
	ds_read_b128 v[194:197], v129 offset:46080
	v_mfma_f32_16x16x32_bf16 v[104:107], v[178:181], v[198:201], v[104:107]
	ds_read_b128 v[178:181], v129 offset:40960
	ds_read_b128 v[198:201], v129 offset:48640
	s_waitcnt lgkmcnt(1)
	v_mfma_f32_16x16x32_bf16 v[96:99], v[182:185], v[178:181], v[96:99]
	v_mfma_f32_16x16x32_bf16 v[186:189], v[182:185], v[190:193], v[186:189]
	v_mfma_f32_16x16x32_bf16 v[138:141], v[182:185], v[194:197], v[138:141]
	s_waitcnt lgkmcnt(0)
	v_mfma_f32_16x16x32_bf16 v[100:103], v[182:185], v[198:201], v[100:103]
	ds_read_b128 v[182:185], v131 offset:43520
	s_waitcnt lgkmcnt(0)
	v_mfma_f32_16x16x32_bf16 v[150:153], v[182:185], v[178:181], v[150:153]
	v_mfma_f32_16x16x32_bf16 v[154:157], v[182:185], v[190:193], v[154:157]
	v_mfma_f32_16x16x32_bf16 v[158:161], v[182:185], v[194:197], v[158:161]
	v_mfma_f32_16x16x32_bf16 v[146:149], v[182:185], v[198:201], v[146:149]
	ds_read_b128 v[182:185], v131 offset:46080
	s_waitcnt lgkmcnt(0)
	v_mfma_f32_16x16x32_bf16 v[166:169], v[182:185], v[178:181], v[166:169]
	v_mfma_f32_16x16x32_bf16 v[170:173], v[182:185], v[190:193], v[170:173]
	v_mfma_f32_16x16x32_bf16 v[174:177], v[182:185], v[194:197], v[174:177]
	v_mfma_f32_16x16x32_bf16 v[162:165], v[182:185], v[198:201], v[162:165]
	ds_read_b128 v[182:185], v131 offset:48640
	s_waitcnt lgkmcnt(0)
	v_mfma_f32_16x16x32_bf16 v[108:111], v[182:185], v[178:181], v[108:111]
	ds_read_b128 v[178:181], v131 offset:41024
	v_mfma_f32_16x16x32_bf16 v[142:145], v[182:185], v[190:193], v[142:145]
	ds_read_b128 v[190:193], v129 offset:43584
	v_mfma_f32_16x16x32_bf16 v[134:137], v[182:185], v[194:197], v[134:137]
	ds_read_b128 v[194:197], v129 offset:46144
	v_mfma_f32_16x16x32_bf16 v[104:107], v[182:185], v[198:201], v[104:107]
	ds_read_b128 v[182:185], v129 offset:41024
	ds_read_b128 v[198:201], v129 offset:48704
	s_waitcnt lgkmcnt(1)
	v_mfma_f32_16x16x32_bf16 v[96:99], v[178:181], v[182:185], v[96:99]
	v_mfma_f32_16x16x32_bf16 v[186:189], v[178:181], v[190:193], v[186:189]
	v_mfma_f32_16x16x32_bf16 v[138:141], v[178:181], v[194:197], v[138:141]
	s_waitcnt lgkmcnt(0)
	v_mfma_f32_16x16x32_bf16 v[100:103], v[178:181], v[198:201], v[100:103]
	ds_read_b128 v[178:181], v131 offset:43584
	s_waitcnt lgkmcnt(0)
	v_mfma_f32_16x16x32_bf16 v[150:153], v[178:181], v[182:185], v[150:153]
	v_mfma_f32_16x16x32_bf16 v[154:157], v[178:181], v[190:193], v[154:157]
	v_mfma_f32_16x16x32_bf16 v[158:161], v[178:181], v[194:197], v[158:161]
	v_mfma_f32_16x16x32_bf16 v[146:149], v[178:181], v[198:201], v[146:149]
	ds_read_b128 v[178:181], v131 offset:46144
	s_waitcnt lgkmcnt(0)
	v_mfma_f32_16x16x32_bf16 v[166:169], v[178:181], v[182:185], v[166:169]
	v_mfma_f32_16x16x32_bf16 v[170:173], v[178:181], v[190:193], v[170:173]
	v_mfma_f32_16x16x32_bf16 v[174:177], v[178:181], v[194:197], v[174:177]
	v_mfma_f32_16x16x32_bf16 v[162:165], v[178:181], v[198:201], v[162:165]
	ds_read_b128 v[178:181], v131 offset:48704
	s_waitcnt vmcnt(23)
	ds_write_b128 v130, v[4:7]
	s_waitcnt vmcnt(22)
	ds_write_b128 v130, v[24:27] offset:5120
	s_waitcnt vmcnt(21)
	ds_write_b128 v130, v[28:31] offset:10240
	s_waitcnt vmcnt(20)
	ds_write_b128 v130, v[32:35] offset:15360
	s_waitcnt vmcnt(19)
	ds_write_b128 v130, v[48:51] offset:20480
	s_waitcnt vmcnt(18)
	ds_write_b128 v130, v[64:67] offset:25600
	s_waitcnt vmcnt(17)
	ds_write_b128 v130, v[76:79] offset:30720
	s_waitcnt vmcnt(16)
	ds_write_b128 v130, v[80:83] offset:35840
	global_load_dwordx4 v[4:7], v[114:115], off offset:1664
	global_load_dwordx4 v[24:27], v[116:117], off offset:1664
	global_load_dwordx4 v[28:31], v[118:119], off offset:1664
	global_load_dwordx4 v[32:35], v[124:125], off offset:1664
	global_load_dwordx4 v[48:51], v[112:113], off offset:1664
	global_load_dwordx4 v[64:67], v[120:121], off offset:1664
	global_load_dwordx4 v[76:79], v[122:123], off offset:1664
	global_load_dwordx4 v[80:83], v[126:127], off offset:1664
	s_waitcnt lgkmcnt(8)
	v_mfma_f32_16x16x32_bf16 v[108:111], v[178:181], v[182:185], v[108:111]
	s_waitcnt lgkmcnt(0)
	s_barrier
	ds_read_b128 v[182:185], v131
	v_mfma_f32_16x16x32_bf16 v[142:145], v[178:181], v[190:193], v[142:145]
	ds_read_b128 v[190:193], v129 offset:2560
	v_mfma_f32_16x16x32_bf16 v[134:137], v[178:181], v[194:197], v[134:137]
	ds_read_b128 v[194:197], v129 offset:5120
	v_mfma_f32_16x16x32_bf16 v[104:107], v[178:181], v[198:201], v[104:107]
	ds_read_b128 v[178:181], v129
	ds_read_b128 v[198:201], v129 offset:7680
	s_waitcnt lgkmcnt(1)
	v_mfma_f32_16x16x32_bf16 v[96:99], v[182:185], v[178:181], v[96:99]
	v_mfma_f32_16x16x32_bf16 v[186:189], v[182:185], v[190:193], v[186:189]
	v_mfma_f32_16x16x32_bf16 v[138:141], v[182:185], v[194:197], v[138:141]
	s_waitcnt lgkmcnt(0)
	v_mfma_f32_16x16x32_bf16 v[100:103], v[182:185], v[198:201], v[100:103]
	ds_read_b128 v[182:185], v131 offset:2560
	s_waitcnt lgkmcnt(0)
	v_mfma_f32_16x16x32_bf16 v[150:153], v[182:185], v[178:181], v[150:153]
	v_mfma_f32_16x16x32_bf16 v[154:157], v[182:185], v[190:193], v[154:157]
	v_mfma_f32_16x16x32_bf16 v[158:161], v[182:185], v[194:197], v[158:161]
	v_mfma_f32_16x16x32_bf16 v[146:149], v[182:185], v[198:201], v[146:149]
	ds_read_b128 v[182:185], v131 offset:5120
	s_waitcnt lgkmcnt(0)
	v_mfma_f32_16x16x32_bf16 v[166:169], v[182:185], v[178:181], v[166:169]
	v_mfma_f32_16x16x32_bf16 v[170:173], v[182:185], v[190:193], v[170:173]
	v_mfma_f32_16x16x32_bf16 v[174:177], v[182:185], v[194:197], v[174:177]
	v_mfma_f32_16x16x32_bf16 v[162:165], v[182:185], v[198:201], v[162:165]
	ds_read_b128 v[182:185], v131 offset:7680
	s_waitcnt lgkmcnt(0)
	v_mfma_f32_16x16x32_bf16 v[108:111], v[182:185], v[178:181], v[108:111]
	ds_read_b128 v[178:181], v131 offset:64
	v_mfma_f32_16x16x32_bf16 v[142:145], v[182:185], v[190:193], v[142:145]
	ds_read_b128 v[190:193], v129 offset:2624
	v_mfma_f32_16x16x32_bf16 v[134:137], v[182:185], v[194:197], v[134:137]
	ds_read_b128 v[194:197], v129 offset:5184
	v_mfma_f32_16x16x32_bf16 v[104:107], v[182:185], v[198:201], v[104:107]
	ds_read_b128 v[182:185], v129 offset:64
	ds_read_b128 v[198:201], v129 offset:7744
	s_waitcnt lgkmcnt(1)
	v_mfma_f32_16x16x32_bf16 v[96:99], v[178:181], v[182:185], v[96:99]
	v_mfma_f32_16x16x32_bf16 v[186:189], v[178:181], v[190:193], v[186:189]
	v_mfma_f32_16x16x32_bf16 v[138:141], v[178:181], v[194:197], v[138:141]
	s_waitcnt lgkmcnt(0)
	v_mfma_f32_16x16x32_bf16 v[100:103], v[178:181], v[198:201], v[100:103]
	ds_read_b128 v[178:181], v131 offset:2624
	s_waitcnt lgkmcnt(0)
	v_mfma_f32_16x16x32_bf16 v[150:153], v[178:181], v[182:185], v[150:153]
	v_mfma_f32_16x16x32_bf16 v[154:157], v[178:181], v[190:193], v[154:157]
	v_mfma_f32_16x16x32_bf16 v[158:161], v[178:181], v[194:197], v[158:161]
	v_mfma_f32_16x16x32_bf16 v[146:149], v[178:181], v[198:201], v[146:149]
	ds_read_b128 v[178:181], v131 offset:5184
	s_waitcnt lgkmcnt(0)
	v_mfma_f32_16x16x32_bf16 v[166:169], v[178:181], v[182:185], v[166:169]
	v_mfma_f32_16x16x32_bf16 v[170:173], v[178:181], v[190:193], v[170:173]
	v_mfma_f32_16x16x32_bf16 v[174:177], v[178:181], v[194:197], v[174:177]
	v_mfma_f32_16x16x32_bf16 v[162:165], v[178:181], v[198:201], v[162:165]
	ds_read_b128 v[178:181], v131 offset:7744
	s_waitcnt vmcnt(23)
	ds_write_b128 v130, v[8:11] offset:40960
	s_waitcnt vmcnt(22)
	ds_write_b128 v130, v[36:39] offset:46080
	s_waitcnt vmcnt(21)
	ds_write_b128 v130, v[40:43] offset:51200
	s_waitcnt vmcnt(20)
	ds_write_b128 v130, v[44:47] offset:56320
	s_waitcnt vmcnt(19)
	ds_write_b128 v130, v[52:55] offset:61440
	s_waitcnt vmcnt(18)
	ds_write_b128 v132, v[60:63] offset:5120
	s_waitcnt vmcnt(17)
	ds_write_b128 v132, v[68:71] offset:10240
	s_waitcnt vmcnt(16)
	ds_write_b128 v132, v[84:87] offset:15360
	global_load_dwordx4 v[8:11], v[114:115], off offset:1792
	global_load_dwordx4 v[44:47], v[116:117], off offset:1792
	global_load_dwordx4 v[36:39], v[118:119], off offset:1792
	global_load_dwordx4 v[40:43], v[124:125], off offset:1792
	global_load_dwordx4 v[52:55], v[112:113], off offset:1792
	global_load_dwordx4 v[60:63], v[120:121], off offset:1792
	global_load_dwordx4 v[68:71], v[122:123], off offset:1792
	global_load_dwordx4 v[84:87], v[126:127], off offset:1792
	s_waitcnt lgkmcnt(8)
	v_mfma_f32_16x16x32_bf16 v[108:111], v[178:181], v[182:185], v[108:111]
	s_waitcnt lgkmcnt(0)
	s_barrier
	ds_read_b128 v[182:185], v131 offset:40960
	v_mfma_f32_16x16x32_bf16 v[142:145], v[178:181], v[190:193], v[142:145]
	ds_read_b128 v[190:193], v129 offset:43520
	v_mfma_f32_16x16x32_bf16 v[134:137], v[178:181], v[194:197], v[134:137]
	ds_read_b128 v[194:197], v129 offset:46080
	v_mfma_f32_16x16x32_bf16 v[104:107], v[178:181], v[198:201], v[104:107]
	ds_read_b128 v[178:181], v129 offset:40960
	ds_read_b128 v[198:201], v129 offset:48640
	s_waitcnt lgkmcnt(1)
	v_mfma_f32_16x16x32_bf16 v[96:99], v[182:185], v[178:181], v[96:99]
	v_mfma_f32_16x16x32_bf16 v[186:189], v[182:185], v[190:193], v[186:189]
	v_mfma_f32_16x16x32_bf16 v[138:141], v[182:185], v[194:197], v[138:141]
	s_waitcnt lgkmcnt(0)
	v_mfma_f32_16x16x32_bf16 v[100:103], v[182:185], v[198:201], v[100:103]
	ds_read_b128 v[182:185], v131 offset:43520
	s_waitcnt lgkmcnt(0)
	v_mfma_f32_16x16x32_bf16 v[150:153], v[182:185], v[178:181], v[150:153]
	v_mfma_f32_16x16x32_bf16 v[154:157], v[182:185], v[190:193], v[154:157]
	v_mfma_f32_16x16x32_bf16 v[158:161], v[182:185], v[194:197], v[158:161]
	v_mfma_f32_16x16x32_bf16 v[146:149], v[182:185], v[198:201], v[146:149]
	ds_read_b128 v[182:185], v131 offset:46080
	s_waitcnt lgkmcnt(0)
	v_mfma_f32_16x16x32_bf16 v[166:169], v[182:185], v[178:181], v[166:169]
	v_mfma_f32_16x16x32_bf16 v[170:173], v[182:185], v[190:193], v[170:173]
	v_mfma_f32_16x16x32_bf16 v[174:177], v[182:185], v[194:197], v[174:177]
	v_mfma_f32_16x16x32_bf16 v[162:165], v[182:185], v[198:201], v[162:165]
	ds_read_b128 v[182:185], v131 offset:48640
	s_waitcnt lgkmcnt(0)
	v_mfma_f32_16x16x32_bf16 v[108:111], v[182:185], v[178:181], v[108:111]
	ds_read_b128 v[178:181], v131 offset:41024
	v_mfma_f32_16x16x32_bf16 v[142:145], v[182:185], v[190:193], v[142:145]
	ds_read_b128 v[190:193], v129 offset:43584
	v_mfma_f32_16x16x32_bf16 v[134:137], v[182:185], v[194:197], v[134:137]
	ds_read_b128 v[194:197], v129 offset:46144
	v_mfma_f32_16x16x32_bf16 v[104:107], v[182:185], v[198:201], v[104:107]
	ds_read_b128 v[182:185], v129 offset:41024
	ds_read_b128 v[198:201], v129 offset:48704
	s_waitcnt lgkmcnt(1)
	v_mfma_f32_16x16x32_bf16 v[96:99], v[178:181], v[182:185], v[96:99]
	v_mfma_f32_16x16x32_bf16 v[186:189], v[178:181], v[190:193], v[186:189]
	v_mfma_f32_16x16x32_bf16 v[138:141], v[178:181], v[194:197], v[138:141]
	s_waitcnt lgkmcnt(0)
	v_mfma_f32_16x16x32_bf16 v[100:103], v[178:181], v[198:201], v[100:103]
	ds_read_b128 v[178:181], v131 offset:43584
	s_waitcnt lgkmcnt(0)
	v_mfma_f32_16x16x32_bf16 v[150:153], v[178:181], v[182:185], v[150:153]
	v_mfma_f32_16x16x32_bf16 v[154:157], v[178:181], v[190:193], v[154:157]
	v_mfma_f32_16x16x32_bf16 v[158:161], v[178:181], v[194:197], v[158:161]
	v_mfma_f32_16x16x32_bf16 v[146:149], v[178:181], v[198:201], v[146:149]
	ds_read_b128 v[178:181], v131 offset:46144
	s_waitcnt lgkmcnt(0)
	v_mfma_f32_16x16x32_bf16 v[166:169], v[178:181], v[182:185], v[166:169]
	v_mfma_f32_16x16x32_bf16 v[170:173], v[178:181], v[190:193], v[170:173]
	v_mfma_f32_16x16x32_bf16 v[174:177], v[178:181], v[194:197], v[174:177]
	v_mfma_f32_16x16x32_bf16 v[162:165], v[178:181], v[198:201], v[162:165]
	ds_read_b128 v[178:181], v131 offset:48704
	s_waitcnt vmcnt(23)
	ds_write_b128 v130, v[0:3]
	s_waitcnt vmcnt(22)
	ds_write_b128 v130, v[12:15] offset:5120
	s_waitcnt vmcnt(21)
	ds_write_b128 v130, v[16:19] offset:10240
	s_waitcnt vmcnt(20)
	ds_write_b128 v130, v[20:23] offset:15360
	s_waitcnt vmcnt(19)
	ds_write_b128 v130, v[56:59] offset:20480
	s_waitcnt vmcnt(18)
	ds_write_b128 v130, v[72:75] offset:25600
	s_waitcnt vmcnt(17)
	ds_write_b128 v130, v[88:91] offset:30720
	s_waitcnt vmcnt(16)
	ds_write_b128 v130, v[92:95] offset:35840
	global_load_dwordx4 v[0:3], v[114:115], off offset:1920
	global_load_dwordx4 v[20:23], v[116:117], off offset:1920
	global_load_dwordx4 v[12:15], v[118:119], off offset:1920
	global_load_dwordx4 v[16:19], v[124:125], off offset:1920
	global_load_dwordx4 v[56:59], v[112:113], off offset:1920
	global_load_dwordx4 v[72:75], v[120:121], off offset:1920
	global_load_dwordx4 v[88:91], v[122:123], off offset:1920
	global_load_dwordx4 v[92:95], v[126:127], off offset:1920
	s_waitcnt lgkmcnt(0)
	s_barrier
	ds_read_b128 v[112:115], v131
	v_mfma_f32_16x16x32_bf16 v[108:111], v[178:181], v[182:185], v[108:111]
	ds_read_b128 v[116:119], v129
	ds_read_b128 v[120:123], v129 offset:2560
	ds_read_b128 v[182:185], v129 offset:7680
	v_mfma_f32_16x16x32_bf16 v[142:145], v[178:181], v[190:193], v[142:145]
	v_mfma_f32_16x16x32_bf16 v[134:137], v[178:181], v[194:197], v[134:137]
	v_mfma_f32_16x16x32_bf16 v[104:107], v[178:181], v[198:201], v[104:107]
	ds_read_b128 v[178:181], v129 offset:5120
	s_waitcnt lgkmcnt(3)
	v_mfma_f32_16x16x32_bf16 v[96:99], v[112:115], v[116:119], v[96:99]
	s_waitcnt lgkmcnt(2)
	v_mfma_f32_16x16x32_bf16 v[124:127], v[112:115], v[120:123], v[186:189]
	s_waitcnt lgkmcnt(0)
	v_mfma_f32_16x16x32_bf16 v[138:141], v[112:115], v[178:181], v[138:141]
	v_mfma_f32_16x16x32_bf16 v[100:103], v[112:115], v[182:185], v[100:103]
	ds_read_b128 v[112:115], v131 offset:2560
	s_waitcnt lgkmcnt(0)
	v_mfma_f32_16x16x32_bf16 v[150:153], v[112:115], v[116:119], v[150:153]
	v_mfma_f32_16x16x32_bf16 v[154:157], v[112:115], v[120:123], v[154:157]
	v_mfma_f32_16x16x32_bf16 v[158:161], v[112:115], v[178:181], v[158:161]
	v_mfma_f32_16x16x32_bf16 v[112:115], v[112:115], v[182:185], v[146:149]
	s_nop 2
	ds_read_b128 v[146:149], v131 offset:5120
	s_waitcnt lgkmcnt(0)
	v_mfma_f32_16x16x32_bf16 v[166:169], v[146:149], v[116:119], v[166:169]
	v_mfma_f32_16x16x32_bf16 v[170:173], v[146:149], v[120:123], v[170:173]
	v_mfma_f32_16x16x32_bf16 v[174:177], v[146:149], v[178:181], v[174:177]
	v_mfma_f32_16x16x32_bf16 v[146:149], v[146:149], v[182:185], v[162:165]
	s_nop 2
	ds_read_b128 v[162:165], v131 offset:7680
	s_waitcnt lgkmcnt(0)
	v_mfma_f32_16x16x32_bf16 v[108:111], v[162:165], v[116:119], v[108:111]
	v_mfma_f32_16x16x32_bf16 v[116:119], v[162:165], v[120:123], v[142:145]
	v_mfma_f32_16x16x32_bf16 v[120:123], v[162:165], v[178:181], v[134:137]
	s_nop 1
	ds_read_b128 v[142:145], v129 offset:64
	ds_read_b128 v[178:181], v129 offset:5184
	ds_read_b128 v[134:137], v131 offset:64
	v_mfma_f32_16x16x32_bf16 v[104:107], v[162:165], v[182:185], v[104:107]
	ds_read_b128 v[162:165], v129 offset:2624
	ds_read_b128 v[182:185], v129 offset:7744
	s_waitcnt lgkmcnt(2)
	v_mfma_f32_16x16x32_bf16 v[96:99], v[134:137], v[142:145], v[96:99]
	s_waitcnt lgkmcnt(1)
	v_mfma_f32_16x16x32_bf16 v[124:127], v[134:137], v[162:165], v[124:127]
	v_mfma_f32_16x16x32_bf16 v[138:141], v[134:137], v[178:181], v[138:141]
	s_waitcnt lgkmcnt(0)
	v_mfma_f32_16x16x32_bf16 v[100:103], v[134:137], v[182:185], v[100:103]
	ds_read_b128 v[134:137], v131 offset:2624
	s_waitcnt lgkmcnt(0)
	v_mfma_f32_16x16x32_bf16 v[150:153], v[134:137], v[142:145], v[150:153]
	v_mfma_f32_16x16x32_bf16 v[154:157], v[134:137], v[162:165], v[154:157]
	v_mfma_f32_16x16x32_bf16 v[158:161], v[134:137], v[178:181], v[158:161]
	v_mfma_f32_16x16x32_bf16 v[112:115], v[134:137], v[182:185], v[112:115]
	ds_read_b128 v[134:137], v131 offset:5184
	s_waitcnt lgkmcnt(0)
	v_mfma_f32_16x16x32_bf16 v[166:169], v[134:137], v[142:145], v[166:169]
	v_mfma_f32_16x16x32_bf16 v[170:173], v[134:137], v[162:165], v[170:173]
	v_mfma_f32_16x16x32_bf16 v[174:177], v[134:137], v[178:181], v[174:177]
	v_mfma_f32_16x16x32_bf16 v[134:137], v[134:137], v[182:185], v[146:149]
	s_nop 2
	ds_read_b128 v[146:149], v131 offset:7744
	s_waitcnt vmcnt(23)
	ds_write_b128 v130, v[4:7] offset:40960
	s_waitcnt vmcnt(22)
	ds_write_b128 v130, v[24:27] offset:46080
	s_waitcnt vmcnt(21)
	ds_write_b128 v130, v[28:31] offset:51200
	s_waitcnt vmcnt(20)
	ds_write_b128 v130, v[32:35] offset:56320
	s_waitcnt vmcnt(19)
	ds_write_b128 v130, v[48:51] offset:61440
	s_waitcnt vmcnt(18)
	ds_write_b128 v132, v[64:67] offset:5120
	s_waitcnt vmcnt(17)
	ds_write_b128 v132, v[76:79] offset:10240
	s_waitcnt vmcnt(16)
	ds_write_b128 v132, v[80:83] offset:15360
	s_waitcnt lgkmcnt(0)
	s_barrier
	ds_read_b128 v[4:7], v131 offset:40960
	ds_read_b128 v[28:31], v129 offset:40960
	ds_read_b128 v[48:51], v129 offset:43520
	s_waitcnt lgkmcnt(1)
	v_mfma_f32_16x16x32_bf16 v[32:35], v[4:7], v[28:31], v[96:99]
	ds_read_b128 v[76:79], v129 offset:46080
	s_nop 1
	ds_read_b128 v[96:99], v129 offset:48640
	s_waitcnt lgkmcnt(2)
	v_mfma_f32_16x16x32_bf16 v[64:67], v[4:7], v[48:51], v[124:127]
	s_waitcnt lgkmcnt(1)
	v_mfma_f32_16x16x32_bf16 v[80:83], v[4:7], v[76:79], v[138:141]
	s_waitcnt lgkmcnt(0)
	v_mfma_f32_16x16x32_bf16 v[4:7], v[4:7], v[96:99], v[100:103]
	s_nop 2
	ds_read_b128 v[100:103], v131 offset:43520
	v_mfma_f32_16x16x32_bf16 v[24:27], v[146:149], v[182:185], v[104:107]
	s_waitcnt lgkmcnt(0)
	v_mfma_f32_16x16x32_bf16 v[104:107], v[100:103], v[28:31], v[150:153]
	v_mfma_f32_16x16x32_bf16 v[124:127], v[100:103], v[48:51], v[154:157]
	v_mfma_f32_16x16x32_bf16 v[138:141], v[100:103], v[76:79], v[158:161]
	s_nop 1
	ds_read_b128 v[154:157], v131 offset:48704
	v_mfma_f32_16x16x32_bf16 v[100:103], v[100:103], v[96:99], v[112:115]
	s_nop 2
	ds_read_b128 v[112:115], v131 offset:46080
	v_mfma_f32_16x16x32_bf16 v[108:111], v[146:149], v[142:145], v[108:111]
	v_mfma_f32_16x16x32_bf16 v[116:119], v[146:149], v[162:165], v[116:119]
	v_mfma_f32_16x16x32_bf16 v[120:123], v[146:149], v[178:181], v[120:123]
	s_waitcnt lgkmcnt(0)
	v_mfma_f32_16x16x32_bf16 v[142:145], v[112:115], v[28:31], v[166:169]
	v_mfma_f32_16x16x32_bf16 v[146:149], v[112:115], v[48:51], v[170:173]
	v_mfma_f32_16x16x32_bf16 v[150:153], v[112:115], v[76:79], v[174:177]
	v_mfma_f32_16x16x32_bf16 v[112:115], v[112:115], v[96:99], v[134:137]
	s_nop 2
	ds_read_b128 v[134:137], v131 offset:48640
	s_waitcnt lgkmcnt(0)
	v_mfma_f32_16x16x32_bf16 v[28:31], v[134:137], v[28:31], v[108:111]
	s_nop 2
	ds_read_b128 v[108:111], v131 offset:41024
	v_mfma_f32_16x16x32_bf16 v[48:51], v[134:137], v[48:51], v[116:119]
	v_mfma_f32_16x16x32_bf16 v[76:79], v[134:137], v[76:79], v[120:123]
	s_nop 1
	ds_read_b128 v[116:119], v129 offset:43584
	v_mfma_f32_16x16x32_bf16 v[24:27], v[134:137], v[96:99], v[24:27]
	ds_read_b128 v[96:99], v129 offset:41024
	ds_read_b128 v[120:123], v129 offset:46144
	ds_read_b128 v[134:137], v129 offset:48704
	s_waitcnt lgkmcnt(2)
	v_mfma_f32_16x16x32_bf16 v[32:35], v[108:111], v[96:99], v[32:35]
	v_mfma_f32_16x16x32_bf16 v[64:67], v[108:111], v[116:119], v[64:67]
	s_waitcnt lgkmcnt(1)
	v_mfma_f32_16x16x32_bf16 v[80:83], v[108:111], v[120:123], v[80:83]
	s_waitcnt lgkmcnt(0)
	v_mfma_f32_16x16x32_bf16 v[4:7], v[108:111], v[134:137], v[4:7]
	ds_read_b128 v[108:111], v131 offset:43584
	s_waitcnt lgkmcnt(0)
	v_mfma_f32_16x16x32_bf16 v[104:107], v[108:111], v[96:99], v[104:107]
	v_mfma_f32_16x16x32_bf16 v[124:127], v[108:111], v[116:119], v[124:127]
	v_mfma_f32_16x16x32_bf16 v[138:141], v[108:111], v[120:123], v[138:141]
	v_mfma_f32_16x16x32_bf16 v[100:103], v[108:111], v[134:137], v[100:103]
	ds_read_b128 v[108:111], v131 offset:46144
	s_waitcnt vmcnt(15)
	ds_write_b128 v130, v[8:11]
	s_waitcnt vmcnt(14)
	ds_write_b128 v130, v[44:47] offset:5120
	s_waitcnt vmcnt(13)
	ds_write_b128 v130, v[36:39] offset:10240
	s_waitcnt vmcnt(12)
	ds_write_b128 v130, v[40:43] offset:15360
	s_waitcnt vmcnt(11)
	ds_write_b128 v130, v[52:55] offset:20480
	s_waitcnt vmcnt(10)
	ds_write_b128 v130, v[60:63] offset:25600
	s_waitcnt vmcnt(9)
	ds_write_b128 v130, v[68:71] offset:30720
	s_waitcnt vmcnt(8)
	ds_write_b128 v130, v[84:87] offset:35840
	s_waitcnt lgkmcnt(0)
	s_barrier
	ds_read_b128 v[44:47], v131
	v_mfma_f32_16x16x32_bf16 v[36:39], v[154:157], v[116:119], v[48:51]
	ds_read_b128 v[52:55], v129 offset:2560
	s_nop 1
	ds_read_b128 v[48:51], v129
	v_mfma_f32_16x16x32_bf16 v[146:149], v[108:111], v[116:119], v[146:149]
	ds_read_b128 v[116:119], v131 offset:7744
	v_mfma_f32_16x16x32_bf16 v[40:43], v[154:157], v[120:123], v[76:79]
	s_waitcnt lgkmcnt(2)
	v_mfma_f32_16x16x32_bf16 v[60:63], v[44:47], v[52:55], v[64:67]
	s_nop 0
	ds_read_b128 v[76:79], v129 offset:7680
	s_nop 0
	ds_read_b128 v[64:67], v129 offset:5120
	s_waitcnt lgkmcnt(3)
	v_mfma_f32_16x16x32_bf16 v[32:35], v[44:47], v[48:51], v[32:35]
	s_waitcnt lgkmcnt(0)
	v_mfma_f32_16x16x32_bf16 v[68:71], v[44:47], v[64:67], v[80:83]
	v_mfma_f32_16x16x32_bf16 v[4:7], v[44:47], v[76:79], v[4:7]
	ds_read_b128 v[44:47], v131 offset:2560
	v_mfma_f32_16x16x32_bf16 v[142:145], v[108:111], v[96:99], v[142:145]
	v_mfma_f32_16x16x32_bf16 v[28:31], v[154:157], v[96:99], v[28:31]
	s_waitcnt lgkmcnt(0)
	v_mfma_f32_16x16x32_bf16 v[80:83], v[44:47], v[48:51], v[104:107]
	v_mfma_f32_16x16x32_bf16 v[84:87], v[44:47], v[52:55], v[124:127]
	v_mfma_f32_16x16x32_bf16 v[96:99], v[44:47], v[64:67], v[138:141]
	v_mfma_f32_16x16x32_bf16 v[44:47], v[44:47], v[76:79], v[100:103]
	s_nop 2
	ds_read_b128 v[100:103], v131 offset:5120
	v_mfma_f32_16x16x32_bf16 v[150:153], v[108:111], v[120:123], v[150:153]
	v_mfma_f32_16x16x32_bf16 v[8:11], v[108:111], v[134:137], v[112:115]
	s_waitcnt lgkmcnt(0)
	v_mfma_f32_16x16x32_bf16 v[104:107], v[100:103], v[48:51], v[142:145]
	v_mfma_f32_16x16x32_bf16 v[108:111], v[100:103], v[52:55], v[146:149]
	v_mfma_f32_16x16x32_bf16 v[112:115], v[100:103], v[64:67], v[150:153]
	v_mfma_f32_16x16x32_bf16 v[8:11], v[100:103], v[76:79], v[8:11]
	ds_read_b128 v[100:103], v131 offset:7680
	v_mfma_f32_16x16x32_bf16 v[24:27], v[154:157], v[134:137], v[24:27]
	s_waitcnt lgkmcnt(0)
	v_mfma_f32_16x16x32_bf16 v[28:31], v[100:103], v[48:51], v[28:31]
	ds_read_b128 v[48:51], v131 offset:64
	v_mfma_f32_16x16x32_bf16 v[36:39], v[100:103], v[52:55], v[36:39]
	ds_read_b128 v[52:55], v129 offset:64
	v_mfma_f32_16x16x32_bf16 v[40:43], v[100:103], v[64:67], v[40:43]
	ds_read_b128 v[64:67], v129 offset:2624
	v_mfma_f32_16x16x32_bf16 v[24:27], v[100:103], v[76:79], v[24:27]
	ds_read_b128 v[76:79], v129 offset:5184
	ds_read_b128 v[100:103], v129 offset:7744
	s_waitcnt lgkmcnt(3)
	v_mfma_f32_16x16x32_bf16 v[32:35], v[48:51], v[52:55], v[32:35]
	s_waitcnt lgkmcnt(2)
	v_mfma_f32_16x16x32_bf16 v[60:63], v[48:51], v[64:67], v[60:63]
	s_waitcnt lgkmcnt(1)
	v_mfma_f32_16x16x32_bf16 v[68:71], v[48:51], v[76:79], v[68:71]
	s_waitcnt lgkmcnt(0)
	v_mfma_f32_16x16x32_bf16 v[4:7], v[48:51], v[100:103], v[4:7]
	ds_read_b128 v[48:51], v131 offset:2624
	s_waitcnt lgkmcnt(0)
	v_mfma_f32_16x16x32_bf16 v[80:83], v[48:51], v[52:55], v[80:83]
	v_mfma_f32_16x16x32_bf16 v[84:87], v[48:51], v[64:67], v[84:87]
	v_mfma_f32_16x16x32_bf16 v[96:99], v[48:51], v[76:79], v[96:99]
	v_mfma_f32_16x16x32_bf16 v[44:47], v[48:51], v[100:103], v[44:47]
	ds_read_b128 v[48:51], v131 offset:5184
	s_waitcnt vmcnt(7)
	ds_write_b128 v130, v[0:3] offset:40960
	s_waitcnt vmcnt(6)
	ds_write_b128 v130, v[20:23] offset:46080
	s_waitcnt vmcnt(5)
	ds_write_b128 v130, v[12:15] offset:51200
	s_waitcnt vmcnt(4)
	ds_write_b128 v130, v[16:19] offset:56320
	s_waitcnt vmcnt(3)
	ds_write_b128 v130, v[56:59] offset:61440
	s_waitcnt vmcnt(2)
	ds_write_b128 v132, v[72:75] offset:5120
	s_waitcnt vmcnt(1)
	ds_write_b128 v132, v[88:91] offset:10240
	s_waitcnt vmcnt(0)
	ds_write_b128 v132, v[92:95] offset:15360
	s_waitcnt lgkmcnt(0)
	s_barrier
	ds_read_b128 v[20:23], v131 offset:40960
	v_mfma_f32_16x16x32_bf16 v[104:107], v[48:51], v[52:55], v[104:107]
	ds_read_b128 v[56:59], v129 offset:48640
	v_mfma_f32_16x16x32_bf16 v[108:111], v[48:51], v[64:67], v[108:111]
	v_mfma_f32_16x16x32_bf16 v[112:115], v[48:51], v[76:79], v[112:115]
	v_mfma_f32_16x16x32_bf16 v[0:3], v[48:51], v[100:103], v[8:11]
	ds_read_b128 v[48:51], v129 offset:46080
	v_mfma_f32_16x16x32_bf16 v[8:11], v[116:119], v[52:55], v[28:31]
	v_mfma_f32_16x16x32_bf16 v[12:15], v[116:119], v[64:67], v[36:39]
	s_nop 1
	ds_read_b128 v[28:31], v129 offset:40960
	ds_read_b128 v[36:39], v129 offset:43520
	v_mfma_f32_16x16x32_bf16 v[16:19], v[116:119], v[76:79], v[40:43]
	s_waitcnt lgkmcnt(1)
	v_mfma_f32_16x16x32_bf16 v[32:35], v[20:23], v[28:31], v[32:35]
	s_waitcnt lgkmcnt(0)
	v_mfma_f32_16x16x32_bf16 v[40:43], v[20:23], v[36:39], v[60:63]
	v_mfma_f32_16x16x32_bf16 v[52:55], v[20:23], v[48:51], v[68:71]
	v_mfma_f32_16x16x32_bf16 v[4:7], v[20:23], v[56:59], v[4:7]
	ds_read_b128 v[20:23], v131 offset:43520
	s_waitcnt lgkmcnt(0)
	v_mfma_f32_16x16x32_bf16 v[60:63], v[20:23], v[28:31], v[80:83]
	v_mfma_f32_16x16x32_bf16 v[64:67], v[20:23], v[36:39], v[84:87]
	v_mfma_f32_16x16x32_bf16 v[68:71], v[20:23], v[48:51], v[96:99]
	v_mfma_f32_16x16x32_bf16 v[20:23], v[20:23], v[56:59], v[44:47]
	s_nop 2
	ds_read_b128 v[44:47], v131 offset:46080
	s_waitcnt lgkmcnt(0)
	v_mfma_f32_16x16x32_bf16 v[72:75], v[44:47], v[28:31], v[104:107]
	v_mfma_f32_16x16x32_bf16 v[76:79], v[44:47], v[36:39], v[108:111]
	v_mfma_f32_16x16x32_bf16 v[80:83], v[44:47], v[48:51], v[112:115]
	v_mfma_f32_16x16x32_bf16 v[0:3], v[44:47], v[56:59], v[0:3]
	ds_read_b128 v[44:47], v131 offset:48640
	ds_read_b128 v[84:87], v131 offset:41024
	ds_read_b128 v[88:91], v131 offset:43584
	v_mfma_f32_16x16x32_bf16 v[24:27], v[116:119], v[100:103], v[24:27]
	s_waitcnt lgkmcnt(2)
	v_mfma_f32_16x16x32_bf16 v[8:11], v[44:47], v[28:31], v[8:11]
	ds_read_b128 v[28:31], v131 offset:46144
	ds_read_b128 v[92:95], v131 offset:48704
	ds_read_b128 v[96:99], v129 offset:41024
	v_mfma_f32_16x16x32_bf16 v[12:15], v[44:47], v[36:39], v[12:15]
	ds_read_b128 v[36:39], v129 offset:43584
	ds_read_b128 v[100:103], v129 offset:46144
	ds_read_b128 v[104:107], v129 offset:48704
	s_waitcnt lgkmcnt(0)
	s_barrier
	v_mfma_f32_16x16x32_bf16 v[16:19], v[44:47], v[48:51], v[16:19]
	v_mfma_f32_16x16x32_bf16 v[24:27], v[44:47], v[56:59], v[24:27]
	v_mov_b32_e32 v44, v211
	s_nop 0
	v_lshrrev_b32_e32 v46, 2, v44
	v_mfma_f32_16x16x32_bf16 v[32:35], v[84:87], v[96:99], v[32:35]
	v_lshrrev_b32_e32 v45, 1, v44
	v_and_b32_e32 v46, 12, v46
	v_and_b32_e32 v44, 0x4f, v44
	v_mfma_f32_16x16x32_bf16 v[40:43], v[84:87], v[36:39], v[40:43]
	v_and_or_b32 v48, v45, s43, v46
	v_lshlrev_b32_e32 v49, 2, v44
	v_mul_lo_u32 v48, v48, s22
	v_mfma_f32_16x16x32_bf16 v[44:47], v[84:87], v[100:103], v[52:55]
	v_mfma_f32_16x16x32_bf16 v[4:7], v[84:87], v[104:107], v[4:7]
	s_nop 1
	v_add3_u32 v52, 0, v49, v48
	ds_write2_b32 v52, v32, v40 offset1:16
	v_add_u32_e32 v40, 0x400, v52
	ds_write2_b32 v52, v33, v41 offset0:132 offset1:148
	ds_write2_b32 v40, v34, v42 offset0:8 offset1:24
	v_mfma_f32_16x16x32_bf16 v[48:51], v[88:91], v[96:99], v[60:63]
	ds_write2_b32 v40, v35, v43 offset0:140 offset1:156
	ds_write2_b32 v52, v44, v4 offset0:32 offset1:48
	ds_write2_b32 v52, v45, v5 offset0:164 offset1:180
	ds_write2_b32 v40, v46, v6 offset0:40 offset1:56
	ds_write2_b32 v40, v47, v7 offset0:172 offset1:188
	v_add_u32_e32 v40, 0x2000, v52
	v_mfma_f32_16x16x32_bf16 v[32:35], v[88:91], v[36:39], v[64:67]
	v_add_u32_e32 v41, 0x2400, v52
	s_nop 6
	ds_write2_b32 v40, v48, v32 offset0:64 offset1:80
	ds_write2_b32 v40, v49, v33 offset0:196 offset1:212
	v_mfma_f32_16x16x32_bf16 v[4:7], v[88:91], v[100:103], v[68:71]
	v_mfma_f32_16x16x32_bf16 v[20:23], v[88:91], v[104:107], v[20:23]
	ds_write2_b32 v41, v50, v34 offset0:72 offset1:88
	ds_write2_b32 v41, v51, v35 offset0:204 offset1:220
	s_nop 5
	ds_write2_b32 v40, v4, v20 offset0:96 offset1:112
	ds_write2_b32 v40, v5, v21 offset0:228 offset1:244
	ds_write2_b32 v41, v6, v22 offset0:104 offset1:120
	ds_write2_b32 v41, v7, v23 offset0:236 offset1:252
	v_mfma_f32_16x16x32_bf16 v[32:35], v[28:31], v[96:99], v[72:75]
	v_add_u32_e32 v40, 0x4000, v52
	v_mfma_f32_16x16x32_bf16 v[4:7], v[28:31], v[36:39], v[76:79]
	v_mfma_f32_16x16x32_bf16 v[20:23], v[28:31], v[100:103], v[80:83]
	v_mfma_f32_16x16x32_bf16 v[0:3], v[28:31], v[104:107], v[0:3]
	s_nop 5
	ds_write2_b32 v40, v32, v4 offset0:128 offset1:144
	v_add_u32_e32 v32, 0x4400, v52
	ds_write2_b32 v32, v33, v5 offset0:4 offset1:20
	ds_write2_b32 v32, v34, v6 offset0:136 offset1:152
	v_add_u32_e32 v33, 0x4800, v52
	ds_write2_b32 v33, v35, v7 offset0:12 offset1:28
	ds_write2_b32 v40, v20, v0 offset0:160 offset1:176
	ds_write2_b32 v32, v21, v1 offset0:36 offset1:52
	v_mfma_f32_16x16x32_bf16 v[4:7], v[92:95], v[96:99], v[8:11]
	ds_write2_b32 v32, v22, v2 offset0:168 offset1:184
	ds_write2_b32 v33, v23, v3 offset0:44 offset1:60
	v_add_u32_e32 v20, 0x6000, v52
	v_mfma_f32_16x16x32_bf16 v[0:3], v[92:95], v[36:39], v[12:15]
	v_mfma_f32_16x16x32_bf16 v[8:11], v[92:95], v[100:103], v[16:19]
	s_nop 6
	ds_write2_b32 v20, v4, v0 offset0:192 offset1:208
	v_add_u32_e32 v4, 0x6400, v52
	ds_write2_b32 v4, v5, v1 offset0:68 offset1:84
	v_add_u32_e32 v5, 0x6800, v52
	ds_write2_b32 v4, v6, v2 offset0:200 offset1:216
	ds_write2_b32 v5, v7, v3 offset0:76 offset1:92
	v_mfma_f32_16x16x32_bf16 v[0:3], v[92:95], v[104:107], v[24:27]
	s_nop 7
	ds_write2_b32 v20, v8, v0 offset0:224 offset1:240
	ds_write2_b32 v4, v9, v1 offset0:100 offset1:116
	ds_write2_b32 v4, v10, v2 offset0:232 offset1:248
	ds_write2_b32 v5, v11, v3 offset0:108 offset1:124
	v_mov_b32_e32 v0, v211
	s_waitcnt lgkmcnt(0)
	s_barrier
	s_nop 0
	v_lshlrev_b32_e32 v1, 3, v0
	v_and_b32_e32 v9, 0x78, v1
	v_ashrrev_i32_e32 v8, 4, v0
	v_lshlrev_b32_e32 v0, 2, v9
	v_mul_lo_u32 v1, v8, s22
	v_add3_u32 v16, 0, v0, v1
	ds_read_b128 v[0:3], v16
	ds_read_b128 v[4:7], v16 offset:16
	v_lshlrev_b32_e32 v208, 1, v9
	v_ashrrev_i32_e32 v9, 31, v8
	v_lshlrev_b64 v[14:15], 12, v[8:9]
	s_waitcnt lgkmcnt(1)
	v_cvt_pk_bf16_f32 v0, v0, v1
	v_cvt_pk_bf16_f32 v1, v2, v3
	s_waitcnt lgkmcnt(0)
	v_cvt_pk_bf16_f32 v2, v4, v5
	v_cvt_pk_bf16_f32 v3, v6, v7
	ds_read_b128 v[4:7], v16 offset:8448
	ds_read_b128 v[8:11], v16 offset:8464
	v_lshl_add_u64 v[12:13], s[4:5], 0, v[208:209]
	v_lshl_add_u64 v[12:13], v[12:13], 0, v[14:15]
	global_store_dwordx4 v[12:13], v[0:3], off nt
	v_add_co_u32_e32 v14, vcc, s8, v12
	s_waitcnt lgkmcnt(1)
	v_cvt_pk_bf16_f32 v0, v4, v5
	v_cvt_pk_bf16_f32 v1, v6, v7
	s_waitcnt lgkmcnt(0)
	v_cvt_pk_bf16_f32 v2, v8, v9
	v_cvt_pk_bf16_f32 v3, v10, v11
	ds_read_b128 v[4:7], v16 offset:16896
	ds_read_b128 v[8:11], v16 offset:16912
	v_addc_co_u32_e32 v15, vcc, 0, v13, vcc
	global_store_dwordx4 v[14:15], v[0:3], off nt
	v_add_co_u32_e32 v14, vcc, s7, v12
	s_waitcnt lgkmcnt(1)
	v_cvt_pk_bf16_f32 v0, v4, v5
	v_cvt_pk_bf16_f32 v1, v6, v7
	s_waitcnt lgkmcnt(0)
	v_cvt_pk_bf16_f32 v2, v8, v9
	v_cvt_pk_bf16_f32 v3, v10, v11
	ds_read_b128 v[4:7], v16 offset:25344
	ds_read_b128 v[8:11], v16 offset:25360
	v_addc_co_u32_e32 v15, vcc, 0, v13, vcc
	global_store_dwordx4 v[14:15], v[0:3], off nt
	v_add_co_u32_e32 v14, vcc, s9, v12
	s_waitcnt lgkmcnt(1)
	v_cvt_pk_bf16_f32 v0, v4, v5
	v_cvt_pk_bf16_f32 v1, v6, v7
	s_waitcnt lgkmcnt(0)
	v_cvt_pk_bf16_f32 v2, v8, v9
	v_cvt_pk_bf16_f32 v3, v10, v11
	ds_read_b128 v[4:7], v16 offset:33792
	ds_read_b128 v[8:11], v16 offset:33808
	v_addc_co_u32_e32 v15, vcc, 0, v13, vcc
	global_store_dwordx4 v[14:15], v[0:3], off nt
	s_mov_b32 s4, 0x40000
	v_add_co_u32_e32 v14, vcc, s4, v12
	s_waitcnt lgkmcnt(1)
	v_cvt_pk_bf16_f32 v0, v4, v5
	v_cvt_pk_bf16_f32 v1, v6, v7
	s_waitcnt lgkmcnt(0)
	v_cvt_pk_bf16_f32 v2, v8, v9
	v_cvt_pk_bf16_f32 v3, v10, v11
	ds_read_b128 v[4:7], v16 offset:42240
	ds_read_b128 v[8:11], v16 offset:42256
	v_addc_co_u32_e32 v15, vcc, 0, v13, vcc
	global_store_dwordx4 v[14:15], v[0:3], off nt
	s_mov_b32 s4, 0x50000
	v_add_co_u32_e32 v14, vcc, s4, v12
	s_waitcnt lgkmcnt(1)
	v_cvt_pk_bf16_f32 v0, v4, v5
	v_cvt_pk_bf16_f32 v1, v6, v7
	s_waitcnt lgkmcnt(0)
	v_cvt_pk_bf16_f32 v2, v8, v9
	v_cvt_pk_bf16_f32 v3, v10, v11
	ds_read_b128 v[4:7], v16 offset:50688
	ds_read_b128 v[8:11], v16 offset:50704
	v_addc_co_u32_e32 v15, vcc, 0, v13, vcc
	global_store_dwordx4 v[14:15], v[0:3], off nt
	s_mov_b32 s4, 0x60000
	v_add_co_u32_e32 v14, vcc, s4, v12
	s_waitcnt lgkmcnt(1)
	v_cvt_pk_bf16_f32 v0, v4, v5
	v_cvt_pk_bf16_f32 v1, v6, v7
	s_waitcnt lgkmcnt(0)
	v_cvt_pk_bf16_f32 v2, v8, v9
	v_cvt_pk_bf16_f32 v3, v10, v11
	ds_read_b128 v[4:7], v16 offset:59136
	ds_read_b128 v[8:11], v16 offset:59152
	v_addc_co_u32_e32 v15, vcc, 0, v13, vcc
	global_store_dwordx4 v[14:15], v[0:3], off nt
	s_waitcnt lgkmcnt(1)
	s_nop 0
	v_cvt_pk_bf16_f32 v0, v4, v5
	v_add_co_u32_e32 v4, vcc, 0x70000, v12
	v_cvt_pk_bf16_f32 v1, v6, v7
	s_waitcnt lgkmcnt(0)
	v_cvt_pk_bf16_f32 v2, v8, v9
	v_cvt_pk_bf16_f32 v3, v10, v11
	v_addc_co_u32_e32 v5, vcc, 0, v13, vcc
	global_store_dwordx4 v[4:5], v[0:3], off nt
	s_barrier
	s_and_saveexec_b64 s[4:5], s[36:37]
	s_cbranch_execz .LBB0_93
	v_readlane_b32 s6, v253, 62
	s_nop 1
	v_mov_b32_e32 v0, s6
	ds_write_b32 v0, v128
	s_branch .LBB0_93

.LBB0_313:
	s_mul_hi_i32 s0, s2, 0x2aaaaaab
	s_lshr_b32 s1, s0, 31
	s_ashr_i32 s0, s0, 3
	s_add_i32 s0, s0, s1
	s_mul_i32 s1, s0, 0xffffffd0
	s_add_i32 s4, s2, s1
	s_ashr_i32 s1, s0, 31
	v_mov_b32_e32 v98, v211
	s_lshl_b64 s[6:7], s[0:1], 18
	s_add_u32 s6, s30, s6
	v_ashrrev_i32_e32 v96, 3, v98
	v_ashrrev_i32_e32 v97, 31, v96
	s_addc_u32 s7, s31, s7
	v_lshlrev_b64 v[0:1], 11, v[96:97]
	v_lshlrev_b32_e32 v4, 4, v98
	v_lshl_add_u64 v[2:3], s[6:7], 0, v[0:1]
	v_and_b32_e32 v208, 0x70, v4
	v_lshl_add_u64 v[134:135], v[2:3], 0, v[208:209]
	v_add_co_u32_e32 v128, vcc, s9, v134
	s_ashr_i32 s5, s4, 31
	s_nop 0
	v_addc_co_u32_e32 v129, vcc, 0, v135, vcc
	s_lshl_b64 s[4:5], s[4:5], 18
	v_add_co_u32_e32 v130, vcc, s8, v134
	s_add_u32 s4, s46, s4
	s_nop 0
	v_addc_co_u32_e32 v131, vcc, 0, v135, vcc
	s_addc_u32 s5, s47, s5
	v_add_co_u32_e32 v132, vcc, s10, v134
	v_lshl_add_u64 v[0:1], s[4:5], 0, v[0:1]
	s_nop 0
	v_addc_co_u32_e32 v133, vcc, 0, v135, vcc
	v_lshl_add_u64 v[120:121], v[0:1], 0, v[208:209]
	global_load_dwordx4 v[0:3], v[134:135], off
	global_load_dwordx4 v[4:7], v[128:129], off
	global_load_dwordx4 v[8:11], v[130:131], off
	global_load_dwordx4 v[12:15], v[132:133], off
	global_load_dwordx4 v[16:19], v[120:121], off
	v_add_co_u32_e32 v122, vcc, s9, v120
	v_mul_u32_u24_e32 v96, 0xa0, v96
	s_nop 0
	v_addc_co_u32_e32 v123, vcc, 0, v121, vcc
	v_add_co_u32_e32 v124, vcc, s8, v120
	global_load_dwordx4 v[20:23], v[122:123], off
	s_nop 0
	v_addc_co_u32_e32 v125, vcc, 0, v121, vcc
	global_load_dwordx4 v[24:27], v[124:125], off
	v_add_co_u32_e32 v126, vcc, s10, v120
	v_add3_u32 v136, 0, v96, v208
	s_nop 0
	v_addc_co_u32_e32 v127, vcc, 0, v121, vcc
	global_load_dwordx4 v[28:31], v[126:127], off
	global_load_dwordx4 v[92:95], v[134:135], off offset:128
	global_load_dwordx4 v[80:83], v[128:129], off offset:128
	global_load_dwordx4 v[84:87], v[130:131], off offset:128
	global_load_dwordx4 v[88:91], v[132:133], off offset:128
	global_load_dwordx4 v[68:71], v[120:121], off offset:128
	global_load_dwordx4 v[72:75], v[122:123], off offset:128
	global_load_dwordx4 v[76:79], v[124:125], off offset:128
	global_load_dwordx4 v[64:67], v[126:127], off offset:128
	global_load_dwordx4 v[60:63], v[134:135], off offset:256
	global_load_dwordx4 v[48:51], v[128:129], off offset:256
	global_load_dwordx4 v[52:55], v[130:131], off offset:256
	global_load_dwordx4 v[56:59], v[132:133], off offset:256
	global_load_dwordx4 v[36:39], v[120:121], off offset:256
	global_load_dwordx4 v[40:43], v[122:123], off offset:256
	global_load_dwordx4 v[44:47], v[124:125], off offset:256
	global_load_dwordx4 v[32:35], v[126:127], off offset:256
	s_barrier
	v_and_b32_e32 v96, 15, v98
	v_lshrrev_b32_e32 v97, 1, v98
	v_and_or_b32 v96, v97, s43, v96
	v_mul_u32_u24_e32 v96, 0xa0, v96
	v_and_b32_e32 v97, 48, v98
	v_add3_u32 v137, 0, v96, v97
	v_and_b32_e32 v96, 0x4f, v98
	v_mul_u32_u24_e32 v96, 0x50, v96
	v_lshlrev_b32_e32 v96, 1, v96
	v_add3_u32 v138, 0, v96, v97
	v_add_u32_e32 v138, 0x5000, v138
	v_add_u32_e32 v139, 0xf000, v136
	s_mul_hi_i32 s4, s0, 0x180000
	s_mul_i32 s5, s0, 0x180000
	s_mulk_i32 s0, 0xe800
	s_add_i32 s0, s3, s0
	s_ashr_i32 s1, s0, 31
	s_add_u32 s5, s20, s5
	s_addc_u32 s4, s21, s4
	s_lshl_b64 s[0:1], s[0:1], 1
	s_add_u32 s0, s5, s0
	s_addc_u32 s1, s4, s1
	s_add_i32 s2, s2, s26
	s_add_i32 s3, s3, s18
	s_cmpk_gt_i32 s2, 0x32ff
	s_waitcnt vmcnt(23)
	ds_write_b128 v136, v[0:3]
	s_waitcnt vmcnt(22)
	ds_write_b128 v136, v[4:7] offset:5120
	s_waitcnt vmcnt(21)
	ds_write_b128 v136, v[8:11] offset:10240
	s_waitcnt vmcnt(20)
	ds_write_b128 v136, v[12:15] offset:15360
	s_waitcnt vmcnt(19)
	ds_write_b128 v136, v[16:19] offset:20480
	s_waitcnt vmcnt(18)
	ds_write_b128 v136, v[20:23] offset:25600
	s_waitcnt vmcnt(17)
	ds_write_b128 v136, v[24:27] offset:30720
	s_waitcnt vmcnt(16)
	ds_write_b128 v136, v[28:31] offset:35840
	global_load_dwordx4 v[0:3], v[126:127], off offset:384
	global_load_dwordx4 v[4:7], v[124:125], off offset:384
	global_load_dwordx4 v[8:11], v[122:123], off offset:384
	global_load_dwordx4 v[12:15], v[120:121], off offset:384
	global_load_dwordx4 v[16:19], v[132:133], off offset:384
	global_load_dwordx4 v[20:23], v[130:131], off offset:384
	global_load_dwordx4 v[24:27], v[128:129], off offset:384
	global_load_dwordx4 v[28:31], v[134:135], off offset:384
	s_waitcnt lgkmcnt(0)
	s_barrier
	ds_read_b128 v[96:99], v137
	ds_read_b128 v[100:103], v137 offset:2560
	ds_read_b128 v[104:107], v137 offset:5120
	ds_read_b128 v[108:111], v137 offset:7680
	ds_read_b128 v[112:115], v138
	ds_read_b128 v[116:119], v138 offset:2560
	ds_read_b128 v[140:143], v138 offset:5120
	ds_read_b128 v[144:147], v138 offset:7680
	s_waitcnt lgkmcnt(3)
	v_mfma_f32_16x16x32_bf16 v[148:151], v[96:99], v[112:115], 0
	s_waitcnt lgkmcnt(2)
	v_mfma_f32_16x16x32_bf16 v[152:155], v[96:99], v[116:119], 0
	s_waitcnt lgkmcnt(1)
	v_mfma_f32_16x16x32_bf16 v[156:159], v[96:99], v[140:143], 0
	s_waitcnt lgkmcnt(0)
	v_mfma_f32_16x16x32_bf16 v[96:99], v[96:99], v[144:147], 0
	ds_read_b128 v[184:187], v137 offset:2624
	ds_read_b128 v[188:191], v137 offset:5184
	ds_read_b128 v[192:195], v137 offset:7744
	ds_read_b128 v[196:199], v138 offset:64
	ds_read_b128 v[200:203], v138 offset:2624
	ds_read_b128 v[204:207], v138 offset:5184
	ds_read_b128 v[212:215], v138 offset:7744
	v_mfma_f32_16x16x32_bf16 v[160:163], v[100:103], v[112:115], 0
	v_mfma_f32_16x16x32_bf16 v[164:167], v[100:103], v[116:119], 0
	v_mfma_f32_16x16x32_bf16 v[168:171], v[100:103], v[140:143], 0
	v_mfma_f32_16x16x32_bf16 v[100:103], v[100:103], v[144:147], 0
	v_mfma_f32_16x16x32_bf16 v[172:175], v[104:107], v[112:115], 0
	v_mfma_f32_16x16x32_bf16 v[176:179], v[104:107], v[116:119], 0
	v_mfma_f32_16x16x32_bf16 v[180:183], v[104:107], v[140:143], 0
	v_mfma_f32_16x16x32_bf16 v[104:107], v[104:107], v[144:147], 0
	v_mfma_f32_16x16x32_bf16 v[112:115], v[108:111], v[112:115], 0
	v_mfma_f32_16x16x32_bf16 v[116:119], v[108:111], v[116:119], 0
	v_mfma_f32_16x16x32_bf16 v[140:143], v[108:111], v[140:143], 0
	v_mfma_f32_16x16x32_bf16 v[108:111], v[108:111], v[144:147], 0
	ds_read_b128 v[144:147], v137 offset:64
	s_waitcnt vmcnt(23)
	ds_write_b128 v136, v[92:95] offset:40960
	s_waitcnt vmcnt(22)
	ds_write_b128 v136, v[80:83] offset:46080
	s_waitcnt vmcnt(21)
	ds_write_b128 v136, v[84:87] offset:51200
	s_waitcnt vmcnt(20)
	ds_write_b128 v136, v[88:91] offset:56320
	s_waitcnt vmcnt(19)
	ds_write_b128 v136, v[68:71] offset:61440
	s_waitcnt vmcnt(18)
	ds_write_b128 v139, v[72:75] offset:5120
	s_waitcnt vmcnt(17)
	ds_write_b128 v139, v[76:79] offset:10240
	s_waitcnt vmcnt(16)
	ds_write_b128 v139, v[64:67] offset:15360
	s_waitcnt lgkmcnt(8)
	v_mfma_f32_16x16x32_bf16 v[148:151], v[144:147], v[196:199], v[148:151]
	s_waitcnt lgkmcnt(10)
	v_mfma_f32_16x16x32_bf16 v[152:155], v[144:147], v[200:203], v[152:155]
	s_waitcnt lgkmcnt(9)
	v_mfma_f32_16x16x32_bf16 v[156:159], v[144:147], v[204:207], v[156:159]
	s_waitcnt lgkmcnt(8)
	v_mfma_f32_16x16x32_bf16 v[144:147], v[144:147], v[212:215], v[96:99]
	v_mfma_f32_16x16x32_bf16 v[160:163], v[184:187], v[196:199], v[160:163]
	v_mfma_f32_16x16x32_bf16 v[164:167], v[184:187], v[200:203], v[164:167]
	v_mfma_f32_16x16x32_bf16 v[168:171], v[184:187], v[204:207], v[168:171]
	v_mfma_f32_16x16x32_bf16 v[184:187], v[184:187], v[212:215], v[100:103]
	v_mfma_f32_16x16x32_bf16 v[172:175], v[188:191], v[196:199], v[172:175]
	v_mfma_f32_16x16x32_bf16 v[176:179], v[188:191], v[200:203], v[176:179]
	v_mfma_f32_16x16x32_bf16 v[180:183], v[188:191], v[204:207], v[180:183]
	v_mfma_f32_16x16x32_bf16 v[188:191], v[188:191], v[212:215], v[104:107]
	v_mfma_f32_16x16x32_bf16 v[196:199], v[192:195], v[196:199], v[112:115]
	v_mfma_f32_16x16x32_bf16 v[116:119], v[192:195], v[200:203], v[116:119]
	v_mfma_f32_16x16x32_bf16 v[140:143], v[192:195], v[204:207], v[140:143]
	v_mfma_f32_16x16x32_bf16 v[192:195], v[192:195], v[212:215], v[108:111]
	global_load_dwordx4 v[68:71], v[134:135], off offset:512
	global_load_dwordx4 v[88:91], v[128:129], off offset:512
	global_load_dwordx4 v[92:95], v[130:131], off offset:512
	global_load_dwordx4 v[96:99], v[132:133], off offset:512
	global_load_dwordx4 v[100:103], v[120:121], off offset:512
	global_load_dwordx4 v[104:107], v[122:123], off offset:512
	global_load_dwordx4 v[108:111], v[124:125], off offset:512
	global_load_dwordx4 v[112:115], v[126:127], off offset:512
	s_waitcnt lgkmcnt(0)
	s_barrier
	ds_read_b128 v[64:67], v137 offset:40960
	ds_read_b128 v[72:75], v137 offset:43520
	ds_read_b128 v[76:79], v137 offset:46080
	ds_read_b128 v[80:83], v137 offset:48640
	ds_read_b128 v[84:87], v138 offset:40960
	ds_read_b128 v[200:203], v138 offset:43520
	ds_read_b128 v[204:207], v138 offset:46080
	ds_read_b128 v[212:215], v138 offset:48640
	s_waitcnt lgkmcnt(3)
	v_mfma_f32_16x16x32_bf16 v[148:151], v[64:67], v[84:87], v[148:151]
	s_waitcnt lgkmcnt(2)
	v_mfma_f32_16x16x32_bf16 v[152:155], v[64:67], v[200:203], v[152:155]
	s_waitcnt lgkmcnt(1)
	v_mfma_f32_16x16x32_bf16 v[156:159], v[64:67], v[204:207], v[156:159]
	s_waitcnt lgkmcnt(0)
	v_mfma_f32_16x16x32_bf16 v[64:67], v[64:67], v[212:215], v[144:147]
	v_mfma_f32_16x16x32_bf16 v[144:147], v[72:75], v[84:87], v[160:163]
	v_mfma_f32_16x16x32_bf16 v[160:163], v[72:75], v[200:203], v[164:167]
	v_mfma_f32_16x16x32_bf16 v[164:167], v[72:75], v[204:207], v[168:171]
	v_mfma_f32_16x16x32_bf16 v[72:75], v[72:75], v[212:215], v[184:187]
	ds_read_b128 v[184:187], v137 offset:43584
	v_mfma_f32_16x16x32_bf16 v[168:171], v[76:79], v[84:87], v[172:175]
	v_mfma_f32_16x16x32_bf16 v[172:175], v[76:79], v[200:203], v[176:179]
	v_mfma_f32_16x16x32_bf16 v[176:179], v[76:79], v[204:207], v[180:183]
	ds_read_b128 v[180:183], v137 offset:41024
	v_mfma_f32_16x16x32_bf16 v[76:79], v[76:79], v[212:215], v[188:191]
	ds_read_b128 v[188:191], v137 offset:46144
	v_mfma_f32_16x16x32_bf16 v[84:87], v[80:83], v[84:87], v[196:199]
	ds_read_b128 v[196:199], v138 offset:41024
	v_mfma_f32_16x16x32_bf16 v[116:119], v[80:83], v[200:203], v[116:119]
	ds_read_b128 v[200:203], v138 offset:43584
	v_mfma_f32_16x16x32_bf16 v[140:143], v[80:83], v[204:207], v[140:143]
	ds_read_b128 v[204:207], v138 offset:46144
	v_mfma_f32_16x16x32_bf16 v[80:83], v[80:83], v[212:215], v[192:195]
	ds_read_b128 v[192:195], v137 offset:48704
	ds_read_b128 v[212:215], v138 offset:48704
	s_waitcnt vmcnt(23)
	ds_write_b128 v136, v[60:63]
	s_waitcnt vmcnt(22)
	ds_write_b128 v136, v[48:51] offset:5120
	s_waitcnt vmcnt(21)
	ds_write_b128 v136, v[52:55] offset:10240
	s_waitcnt vmcnt(20)
	ds_write_b128 v136, v[56:59] offset:15360
	s_waitcnt vmcnt(19)
	ds_write_b128 v136, v[36:39] offset:20480
	s_waitcnt vmcnt(18)
	ds_write_b128 v136, v[40:43] offset:25600
	s_waitcnt vmcnt(17)
	ds_write_b128 v136, v[44:47] offset:30720
	s_waitcnt vmcnt(16)
	ds_write_b128 v136, v[32:35] offset:35840
	s_waitcnt lgkmcnt(8)
	v_mfma_f32_16x16x32_bf16 v[148:151], v[180:183], v[196:199], v[148:151]
	s_waitcnt lgkmcnt(10)
	v_mfma_f32_16x16x32_bf16 v[152:155], v[180:183], v[200:203], v[152:155]
	s_waitcnt lgkmcnt(9)
	v_mfma_f32_16x16x32_bf16 v[156:159], v[180:183], v[204:207], v[156:159]
	s_waitcnt lgkmcnt(8)
	v_mfma_f32_16x16x32_bf16 v[64:67], v[180:183], v[212:215], v[64:67]
	v_mfma_f32_16x16x32_bf16 v[144:147], v[184:187], v[196:199], v[144:147]
	v_mfma_f32_16x16x32_bf16 v[160:163], v[184:187], v[200:203], v[160:163]
	v_mfma_f32_16x16x32_bf16 v[164:167], v[184:187], v[204:207], v[164:167]
	v_mfma_f32_16x16x32_bf16 v[180:183], v[184:187], v[212:215], v[72:75]
	v_mfma_f32_16x16x32_bf16 v[168:171], v[188:191], v[196:199], v[168:171]
	v_mfma_f32_16x16x32_bf16 v[172:175], v[188:191], v[200:203], v[172:175]
	v_mfma_f32_16x16x32_bf16 v[176:179], v[188:191], v[204:207], v[176:179]
	v_mfma_f32_16x16x32_bf16 v[184:187], v[188:191], v[212:215], v[76:79]
	global_load_dwordx4 v[32:35], v[134:135], off offset:640
	global_load_dwordx4 v[36:39], v[128:129], off offset:640
	global_load_dwordx4 v[40:43], v[130:131], off offset:640
	global_load_dwordx4 v[44:47], v[132:133], off offset:640
	global_load_dwordx4 v[48:51], v[120:121], off offset:640
	global_load_dwordx4 v[72:75], v[122:123], off offset:640
	global_load_dwordx4 v[76:79], v[124:125], off offset:640
	global_load_dwordx4 v[60:63], v[126:127], off offset:640
	s_waitcnt lgkmcnt(0)
	s_barrier
	v_mfma_f32_16x16x32_bf16 v[84:87], v[192:195], v[196:199], v[84:87]
	v_mfma_f32_16x16x32_bf16 v[116:119], v[192:195], v[200:203], v[116:119]
	v_mfma_f32_16x16x32_bf16 v[140:143], v[192:195], v[204:207], v[140:143]
	v_mfma_f32_16x16x32_bf16 v[80:83], v[192:195], v[212:215], v[80:83]
	ds_read_b128 v[52:55], v137
	ds_read_b128 v[56:59], v137 offset:2560
	ds_read_b128 v[188:191], v137 offset:5120
	ds_read_b128 v[192:195], v137 offset:7680
	ds_read_b128 v[196:199], v138
	ds_read_b128 v[200:203], v138 offset:2560
	ds_read_b128 v[204:207], v138 offset:5120
	ds_read_b128 v[212:215], v138 offset:7680
	s_waitcnt lgkmcnt(3)
	v_mfma_f32_16x16x32_bf16 v[148:151], v[52:55], v[196:199], v[148:151]
	s_waitcnt lgkmcnt(2)
	v_mfma_f32_16x16x32_bf16 v[152:155], v[52:55], v[200:203], v[152:155]
	s_waitcnt lgkmcnt(1)
	v_mfma_f32_16x16x32_bf16 v[156:159], v[52:55], v[204:207], v[156:159]
	s_waitcnt lgkmcnt(0)
	v_mfma_f32_16x16x32_bf16 v[52:55], v[52:55], v[212:215], v[64:67]
	v_mfma_f32_16x16x32_bf16 v[64:67], v[56:59], v[196:199], v[144:147]
	v_mfma_f32_16x16x32_bf16 v[144:147], v[56:59], v[200:203], v[160:163]
	v_mfma_f32_16x16x32_bf16 v[160:163], v[56:59], v[204:207], v[164:167]
	v_mfma_f32_16x16x32_bf16 v[56:59], v[56:59], v[212:215], v[180:183]
	ds_read_b128 v[180:183], v137 offset:64
	v_mfma_f32_16x16x32_bf16 v[164:167], v[188:191], v[196:199], v[168:171]
	v_mfma_f32_16x16x32_bf16 v[168:171], v[188:191], v[200:203], v[172:175]
	v_mfma_f32_16x16x32_bf16 v[172:175], v[188:191], v[204:207], v[176:179]
	v_mfma_f32_16x16x32_bf16 v[176:179], v[188:191], v[212:215], v[184:187]
	ds_read_b128 v[184:187], v137 offset:2624
	ds_read_b128 v[188:191], v137 offset:5184
	v_mfma_f32_16x16x32_bf16 v[84:87], v[192:195], v[196:199], v[84:87]
	ds_read_b128 v[196:199], v138 offset:64
	v_mfma_f32_16x16x32_bf16 v[116:119], v[192:195], v[200:203], v[116:119]
	ds_read_b128 v[200:203], v138 offset:2624
	v_mfma_f32_16x16x32_bf16 v[140:143], v[192:195], v[204:207], v[140:143]
	ds_read_b128 v[204:207], v138 offset:5184
	v_mfma_f32_16x16x32_bf16 v[80:83], v[192:195], v[212:215], v[80:83]
	ds_read_b128 v[192:195], v137 offset:7744
	ds_read_b128 v[212:215], v138 offset:7744
	s_waitcnt vmcnt(16)
	ds_write_b128 v136, v[28:31] offset:40960
	ds_write_b128 v136, v[24:27] offset:46080
	ds_write_b128 v136, v[20:23] offset:51200
	ds_write_b128 v136, v[16:19] offset:56320
	ds_write_b128 v136, v[12:15] offset:61440
	ds_write_b128 v139, v[8:11] offset:5120
	ds_write_b128 v139, v[4:7] offset:10240
	ds_write_b128 v139, v[0:3] offset:15360
	s_waitcnt lgkmcnt(8)
	v_mfma_f32_16x16x32_bf16 v[148:151], v[180:183], v[196:199], v[148:151]
	s_waitcnt lgkmcnt(10)
	v_mfma_f32_16x16x32_bf16 v[152:155], v[180:183], v[200:203], v[152:155]
	s_waitcnt lgkmcnt(9)
	v_mfma_f32_16x16x32_bf16 v[156:159], v[180:183], v[204:207], v[156:159]
	s_waitcnt lgkmcnt(8)
	v_mfma_f32_16x16x32_bf16 v[180:183], v[180:183], v[212:215], v[52:55]
	v_mfma_f32_16x16x32_bf16 v[224:227], v[184:187], v[196:199], v[64:67]
	v_mfma_f32_16x16x32_bf16 v[144:147], v[184:187], v[200:203], v[144:147]
	v_mfma_f32_16x16x32_bf16 v[160:163], v[184:187], v[204:207], v[160:163]
	v_mfma_f32_16x16x32_bf16 v[56:59], v[184:187], v[212:215], v[56:59]
	v_mfma_f32_16x16x32_bf16 v[164:167], v[188:191], v[196:199], v[164:167]
	v_mfma_f32_16x16x32_bf16 v[168:171], v[188:191], v[200:203], v[168:171]
	v_mfma_f32_16x16x32_bf16 v[172:175], v[188:191], v[204:207], v[172:175]
	v_mfma_f32_16x16x32_bf16 v[176:179], v[188:191], v[212:215], v[176:179]
	v_mfma_f32_16x16x32_bf16 v[184:187], v[192:195], v[196:199], v[84:87]
	v_mfma_f32_16x16x32_bf16 v[188:191], v[192:195], v[212:215], v[80:83]
	global_load_dwordx4 v[4:7], v[134:135], off offset:768
	global_load_dwordx4 v[8:11], v[128:129], off offset:768
	global_load_dwordx4 v[16:19], v[130:131], off offset:768
	global_load_dwordx4 v[24:27], v[132:133], off offset:768
	global_load_dwordx4 v[52:55], v[120:121], off offset:768
	global_load_dwordx4 v[80:83], v[122:123], off offset:768
	global_load_dwordx4 v[84:87], v[124:125], off offset:768
	global_load_dwordx4 v[64:67], v[126:127], off offset:768
	s_waitcnt lgkmcnt(0)
	s_barrier
	v_mfma_f32_16x16x32_bf16 v[116:119], v[192:195], v[200:203], v[116:119]
	v_mfma_f32_16x16x32_bf16 v[140:143], v[192:195], v[204:207], v[140:143]
	ds_read_b128 v[0:3], v137 offset:40960
	ds_read_b128 v[12:15], v137 offset:43520
	ds_read_b128 v[20:23], v137 offset:46080
	ds_read_b128 v[28:31], v137 offset:48640
	ds_read_b128 v[192:195], v138 offset:40960
	ds_read_b128 v[196:199], v138 offset:43520
	ds_read_b128 v[200:203], v138 offset:46080
	ds_read_b128 v[204:207], v138 offset:48640
	s_waitcnt lgkmcnt(3)
	v_mfma_f32_16x16x32_bf16 v[148:151], v[0:3], v[192:195], v[148:151]
	s_waitcnt lgkmcnt(2)
	v_mfma_f32_16x16x32_bf16 v[152:155], v[0:3], v[196:199], v[152:155]
	s_waitcnt lgkmcnt(1)
	v_mfma_f32_16x16x32_bf16 v[156:159], v[0:3], v[200:203], v[156:159]
	s_waitcnt lgkmcnt(0)
	v_mfma_f32_16x16x32_bf16 v[0:3], v[0:3], v[204:207], v[180:183]
	ds_read_b128 v[212:215], v138 offset:48704
	v_mfma_f32_16x16x32_bf16 v[180:183], v[12:15], v[192:195], v[224:227]
	v_mfma_f32_16x16x32_bf16 v[144:147], v[12:15], v[196:199], v[144:147]
	v_mfma_f32_16x16x32_bf16 v[160:163], v[12:15], v[200:203], v[160:163]
	v_mfma_f32_16x16x32_bf16 v[12:15], v[12:15], v[204:207], v[56:59]
	v_mfma_f32_16x16x32_bf16 v[56:59], v[20:23], v[192:195], v[164:167]
	v_mfma_f32_16x16x32_bf16 v[164:167], v[20:23], v[196:199], v[168:171]
	v_mfma_f32_16x16x32_bf16 v[168:171], v[20:23], v[200:203], v[172:175]
	v_mfma_f32_16x16x32_bf16 v[20:23], v[20:23], v[204:207], v[176:179]
	ds_read_b128 v[176:179], v137 offset:41024
	v_mfma_f32_16x16x32_bf16 v[172:175], v[28:31], v[192:195], v[184:187]
	ds_read_b128 v[184:187], v137 offset:43584
	ds_read_b128 v[192:195], v137 offset:48704
	v_mfma_f32_16x16x32_bf16 v[116:119], v[28:31], v[196:199], v[116:119]
	ds_read_b128 v[196:199], v138 offset:41024
	v_mfma_f32_16x16x32_bf16 v[140:143], v[28:31], v[200:203], v[140:143]
	ds_read_b128 v[200:203], v138 offset:43584
	v_mfma_f32_16x16x32_bf16 v[28:31], v[28:31], v[204:207], v[188:191]
	ds_read_b128 v[188:191], v137 offset:46144
	ds_read_b128 v[204:207], v138 offset:46144
	s_nop 0
	s_waitcnt vmcnt(23)
	ds_write_b128 v136, v[68:71]
	s_waitcnt vmcnt(22)
	ds_write_b128 v136, v[88:91] offset:5120
	s_waitcnt vmcnt(21)
	ds_write_b128 v136, v[92:95] offset:10240
	s_waitcnt vmcnt(20)
	ds_write_b128 v136, v[96:99] offset:15360
	s_waitcnt vmcnt(19)
	ds_write_b128 v136, v[100:103] offset:20480
	s_waitcnt vmcnt(18)
	ds_write_b128 v136, v[104:107] offset:25600
	s_waitcnt vmcnt(17)
	ds_write_b128 v136, v[108:111] offset:30720
	s_waitcnt vmcnt(16)
	ds_write_b128 v136, v[112:115] offset:35840
	s_waitcnt lgkmcnt(8)
	v_mfma_f32_16x16x32_bf16 v[148:151], v[176:179], v[196:199], v[148:151]
	s_waitcnt lgkmcnt(10)
	v_mfma_f32_16x16x32_bf16 v[152:155], v[176:179], v[200:203], v[152:155]
	s_waitcnt lgkmcnt(9)
	v_mfma_f32_16x16x32_bf16 v[156:159], v[176:179], v[204:207], v[156:159]
	s_waitcnt lgkmcnt(8)
	v_mfma_f32_16x16x32_bf16 v[176:179], v[176:179], v[212:215], v[0:3]
	v_mfma_f32_16x16x32_bf16 v[180:183], v[184:187], v[196:199], v[180:183]
	v_mfma_f32_16x16x32_bf16 v[144:147], v[184:187], v[200:203], v[144:147]
	v_mfma_f32_16x16x32_bf16 v[160:163], v[184:187], v[204:207], v[160:163]
	v_mfma_f32_16x16x32_bf16 v[184:187], v[184:187], v[212:215], v[12:15]
	v_mfma_f32_16x16x32_bf16 v[224:227], v[188:191], v[196:199], v[56:59]
	v_mfma_f32_16x16x32_bf16 v[164:167], v[188:191], v[200:203], v[164:167]
	v_mfma_f32_16x16x32_bf16 v[168:171], v[188:191], v[204:207], v[168:171]
	v_mfma_f32_16x16x32_bf16 v[188:191], v[188:191], v[212:215], v[20:23]
	v_mfma_f32_16x16x32_bf16 v[172:175], v[192:195], v[196:199], v[172:175]
	v_mfma_f32_16x16x32_bf16 v[116:119], v[192:195], v[200:203], v[116:119]
	v_mfma_f32_16x16x32_bf16 v[140:143], v[192:195], v[204:207], v[140:143]
	v_mfma_f32_16x16x32_bf16 v[192:195], v[192:195], v[212:215], v[28:31]
	global_load_dwordx4 v[0:3], v[134:135], off offset:896
	global_load_dwordx4 v[12:15], v[128:129], off offset:896
	global_load_dwordx4 v[20:23], v[130:131], off offset:896
	global_load_dwordx4 v[28:31], v[132:133], off offset:896
	global_load_dwordx4 v[56:59], v[120:121], off offset:896
	global_load_dwordx4 v[88:91], v[122:123], off offset:896
	global_load_dwordx4 v[92:95], v[124:125], off offset:896
	global_load_dwordx4 v[68:71], v[126:127], off offset:896
	s_waitcnt lgkmcnt(0)
	s_barrier
	ds_read_b128 v[96:99], v137
	ds_read_b128 v[100:103], v137 offset:2560
	ds_read_b128 v[104:107], v137 offset:5120
	ds_read_b128 v[108:111], v137 offset:7680
	ds_read_b128 v[112:115], v138
	ds_read_b128 v[196:199], v138 offset:2560
	ds_read_b128 v[200:203], v138 offset:5120
	ds_read_b128 v[204:207], v138 offset:7680
	s_waitcnt lgkmcnt(3)
	v_mfma_f32_16x16x32_bf16 v[148:151], v[96:99], v[112:115], v[148:151]
	s_waitcnt lgkmcnt(2)
	v_mfma_f32_16x16x32_bf16 v[152:155], v[96:99], v[196:199], v[152:155]
	s_waitcnt lgkmcnt(1)
	v_mfma_f32_16x16x32_bf16 v[156:159], v[96:99], v[200:203], v[156:159]
	s_waitcnt lgkmcnt(0)
	v_mfma_f32_16x16x32_bf16 v[96:99], v[96:99], v[204:207], v[176:179]
	ds_read_b128 v[212:215], v138 offset:7744
	v_mfma_f32_16x16x32_bf16 v[176:179], v[100:103], v[112:115], v[180:183]
	v_mfma_f32_16x16x32_bf16 v[144:147], v[100:103], v[196:199], v[144:147]
	v_mfma_f32_16x16x32_bf16 v[160:163], v[100:103], v[200:203], v[160:163]
	v_mfma_f32_16x16x32_bf16 v[100:103], v[100:103], v[204:207], v[184:187]
	ds_read_b128 v[184:187], v137 offset:2624
	v_mfma_f32_16x16x32_bf16 v[180:183], v[104:107], v[112:115], v[224:227]
	v_mfma_f32_16x16x32_bf16 v[164:167], v[104:107], v[196:199], v[164:167]
	v_mfma_f32_16x16x32_bf16 v[168:171], v[104:107], v[200:203], v[168:171]
	v_mfma_f32_16x16x32_bf16 v[104:107], v[104:107], v[204:207], v[188:191]
	ds_read_b128 v[188:191], v137 offset:5184
	v_mfma_f32_16x16x32_bf16 v[112:115], v[108:111], v[112:115], v[172:175]
	ds_read_b128 v[172:175], v137 offset:64
	v_mfma_f32_16x16x32_bf16 v[116:119], v[108:111], v[196:199], v[116:119]
	ds_read_b128 v[196:199], v138 offset:64
	v_mfma_f32_16x16x32_bf16 v[140:143], v[108:111], v[200:203], v[140:143]
	ds_read_b128 v[200:203], v138 offset:2624
	v_mfma_f32_16x16x32_bf16 v[108:111], v[108:111], v[204:207], v[192:195]
	ds_read_b128 v[192:195], v137 offset:7744
	ds_read_b128 v[204:207], v138 offset:5184
	s_waitcnt vmcnt(23)
	ds_write_b128 v136, v[32:35] offset:40960
	s_waitcnt vmcnt(22)
	ds_write_b128 v136, v[36:39] offset:46080
	s_waitcnt vmcnt(21)
	ds_write_b128 v136, v[40:43] offset:51200
	s_waitcnt vmcnt(20)
	ds_write_b128 v136, v[44:47] offset:56320
	s_waitcnt vmcnt(19)
	ds_write_b128 v136, v[48:51] offset:61440
	s_waitcnt vmcnt(18)
	ds_write_b128 v139, v[72:75] offset:5120
	s_waitcnt vmcnt(17)
	ds_write_b128 v139, v[76:79] offset:10240
	s_waitcnt vmcnt(16)
	ds_write_b128 v139, v[60:63] offset:15360
	s_waitcnt lgkmcnt(8)
	v_mfma_f32_16x16x32_bf16 v[148:151], v[172:175], v[196:199], v[148:151]
	s_waitcnt lgkmcnt(10)
	v_mfma_f32_16x16x32_bf16 v[152:155], v[172:175], v[200:203], v[152:155]
	s_waitcnt lgkmcnt(9)
	v_mfma_f32_16x16x32_bf16 v[156:159], v[172:175], v[204:207], v[156:159]
	s_waitcnt lgkmcnt(8)
	v_mfma_f32_16x16x32_bf16 v[172:175], v[172:175], v[212:215], v[96:99]
	v_mfma_f32_16x16x32_bf16 v[176:179], v[184:187], v[196:199], v[176:179]
	v_mfma_f32_16x16x32_bf16 v[144:147], v[184:187], v[200:203], v[144:147]
	v_mfma_f32_16x16x32_bf16 v[160:163], v[184:187], v[204:207], v[160:163]
	v_mfma_f32_16x16x32_bf16 v[184:187], v[184:187], v[212:215], v[100:103]
	v_mfma_f32_16x16x32_bf16 v[180:183], v[188:191], v[196:199], v[180:183]
	v_mfma_f32_16x16x32_bf16 v[164:167], v[188:191], v[200:203], v[164:167]
	v_mfma_f32_16x16x32_bf16 v[168:171], v[188:191], v[204:207], v[168:171]
	v_mfma_f32_16x16x32_bf16 v[188:191], v[188:191], v[212:215], v[104:107]
	v_mfma_f32_16x16x32_bf16 v[196:199], v[192:195], v[196:199], v[112:115]
	v_mfma_f32_16x16x32_bf16 v[200:203], v[192:195], v[200:203], v[116:119]
	v_mfma_f32_16x16x32_bf16 v[140:143], v[192:195], v[204:207], v[140:143]
	v_mfma_f32_16x16x32_bf16 v[192:195], v[192:195], v[212:215], v[108:111]
	global_load_dwordx4 v[32:35], v[134:135], off offset:1024
	global_load_dwordx4 v[44:47], v[128:129], off offset:1024
	global_load_dwordx4 v[96:99], v[130:131], off offset:1024
	global_load_dwordx4 v[100:103], v[132:133], off offset:1024
	global_load_dwordx4 v[104:107], v[120:121], off offset:1024
	global_load_dwordx4 v[108:111], v[122:123], off offset:1024
	global_load_dwordx4 v[112:115], v[124:125], off offset:1024
	global_load_dwordx4 v[116:119], v[126:127], off offset:1024
	s_waitcnt lgkmcnt(0)
	s_barrier
	ds_read_b128 v[36:39], v137 offset:40960
	ds_read_b128 v[40:43], v137 offset:43520
	ds_read_b128 v[48:51], v137 offset:46080
	ds_read_b128 v[60:63], v137 offset:48640
	ds_read_b128 v[72:75], v138 offset:40960
	ds_read_b128 v[76:79], v138 offset:43520
	ds_read_b128 v[204:207], v138 offset:46080
	ds_read_b128 v[212:215], v138 offset:48640
	s_waitcnt lgkmcnt(3)
	v_mfma_f32_16x16x32_bf16 v[148:151], v[36:39], v[72:75], v[148:151]
	s_waitcnt lgkmcnt(2)
	v_mfma_f32_16x16x32_bf16 v[152:155], v[36:39], v[76:79], v[152:155]
	s_waitcnt lgkmcnt(1)
	v_mfma_f32_16x16x32_bf16 v[156:159], v[36:39], v[204:207], v[156:159]
	s_waitcnt lgkmcnt(0)
	v_mfma_f32_16x16x32_bf16 v[36:39], v[36:39], v[212:215], v[172:175]
	v_mfma_f32_16x16x32_bf16 v[172:175], v[40:43], v[72:75], v[176:179]
	v_mfma_f32_16x16x32_bf16 v[144:147], v[40:43], v[76:79], v[144:147]
	v_mfma_f32_16x16x32_bf16 v[160:163], v[40:43], v[204:207], v[160:163]
	v_mfma_f32_16x16x32_bf16 v[40:43], v[40:43], v[212:215], v[184:187]
	ds_read_b128 v[184:187], v137 offset:43584
	v_mfma_f32_16x16x32_bf16 v[176:179], v[48:51], v[72:75], v[180:183]
	ds_read_b128 v[180:183], v137 offset:41024
	v_mfma_f32_16x16x32_bf16 v[164:167], v[48:51], v[76:79], v[164:167]
	v_mfma_f32_16x16x32_bf16 v[168:171], v[48:51], v[204:207], v[168:171]
	v_mfma_f32_16x16x32_bf16 v[48:51], v[48:51], v[212:215], v[188:191]
	ds_read_b128 v[188:191], v137 offset:46144
	v_mfma_f32_16x16x32_bf16 v[72:75], v[60:63], v[72:75], v[196:199]
	ds_read_b128 v[196:199], v138 offset:41024
	v_mfma_f32_16x16x32_bf16 v[76:79], v[60:63], v[76:79], v[200:203]
	ds_read_b128 v[200:203], v138 offset:43584
	v_mfma_f32_16x16x32_bf16 v[140:143], v[60:63], v[204:207], v[140:143]
	ds_read_b128 v[204:207], v138 offset:46144
	v_mfma_f32_16x16x32_bf16 v[60:63], v[60:63], v[212:215], v[192:195]
	ds_read_b128 v[192:195], v137 offset:48704
	ds_read_b128 v[212:215], v138 offset:48704
	s_waitcnt vmcnt(23)
	ds_write_b128 v136, v[4:7]
	s_waitcnt vmcnt(22)
	ds_write_b128 v136, v[8:11] offset:5120
	s_waitcnt vmcnt(21)
	ds_write_b128 v136, v[16:19] offset:10240
	s_waitcnt vmcnt(20)
	ds_write_b128 v136, v[24:27] offset:15360
	s_waitcnt vmcnt(19)
	ds_write_b128 v136, v[52:55] offset:20480
	s_waitcnt vmcnt(18)
	ds_write_b128 v136, v[80:83] offset:25600
	s_waitcnt vmcnt(17)
	ds_write_b128 v136, v[84:87] offset:30720
	s_waitcnt vmcnt(16)
	ds_write_b128 v136, v[64:67] offset:35840
	s_waitcnt lgkmcnt(8)
	v_mfma_f32_16x16x32_bf16 v[148:151], v[180:183], v[196:199], v[148:151]
	s_waitcnt lgkmcnt(10)
	v_mfma_f32_16x16x32_bf16 v[152:155], v[180:183], v[200:203], v[152:155]
	s_waitcnt lgkmcnt(9)
	v_mfma_f32_16x16x32_bf16 v[156:159], v[180:183], v[204:207], v[156:159]
	s_waitcnt lgkmcnt(8)
	v_mfma_f32_16x16x32_bf16 v[180:183], v[180:183], v[212:215], v[36:39]
	v_mfma_f32_16x16x32_bf16 v[172:175], v[184:187], v[196:199], v[172:175]
	v_mfma_f32_16x16x32_bf16 v[144:147], v[184:187], v[200:203], v[144:147]
	v_mfma_f32_16x16x32_bf16 v[160:163], v[184:187], v[204:207], v[160:163]
	v_mfma_f32_16x16x32_bf16 v[40:43], v[184:187], v[212:215], v[40:43]
	v_mfma_f32_16x16x32_bf16 v[176:179], v[188:191], v[196:199], v[176:179]
	v_mfma_f32_16x16x32_bf16 v[164:167], v[188:191], v[200:203], v[164:167]
	v_mfma_f32_16x16x32_bf16 v[168:171], v[188:191], v[204:207], v[168:171]
	v_mfma_f32_16x16x32_bf16 v[184:187], v[188:191], v[212:215], v[48:51]
	v_mfma_f32_16x16x32_bf16 v[188:191], v[192:195], v[196:199], v[72:75]
	v_mfma_f32_16x16x32_bf16 v[196:199], v[192:195], v[200:203], v[76:79]
	v_mfma_f32_16x16x32_bf16 v[140:143], v[192:195], v[204:207], v[140:143]
	v_mfma_f32_16x16x32_bf16 v[192:195], v[192:195], v[212:215], v[60:63]
	global_load_dwordx4 v[4:7], v[134:135], off offset:1152
	global_load_dwordx4 v[8:11], v[128:129], off offset:1152
	global_load_dwordx4 v[24:27], v[130:131], off offset:1152
	global_load_dwordx4 v[36:39], v[132:133], off offset:1152
	global_load_dwordx4 v[48:51], v[120:121], off offset:1152
	global_load_dwordx4 v[72:75], v[122:123], off offset:1152
	global_load_dwordx4 v[76:79], v[124:125], off offset:1152
	global_load_dwordx4 v[60:63], v[126:127], off offset:1152
	s_waitcnt lgkmcnt(0)
	s_barrier
	ds_read_b128 v[16:19], v137
	ds_read_b128 v[52:55], v137 offset:2560
	ds_read_b128 v[64:67], v137 offset:5120
	ds_read_b128 v[80:83], v137 offset:7680
	ds_read_b128 v[84:87], v138
	ds_read_b128 v[200:203], v138 offset:2560
	ds_read_b128 v[204:207], v138 offset:5120
	ds_read_b128 v[212:215], v138 offset:7680
	s_waitcnt lgkmcnt(3)
	v_mfma_f32_16x16x32_bf16 v[148:151], v[16:19], v[84:87], v[148:151]
	s_waitcnt lgkmcnt(2)
	v_mfma_f32_16x16x32_bf16 v[152:155], v[16:19], v[200:203], v[152:155]
	s_waitcnt lgkmcnt(1)
	v_mfma_f32_16x16x32_bf16 v[156:159], v[16:19], v[204:207], v[156:159]
	s_waitcnt lgkmcnt(0)
	v_mfma_f32_16x16x32_bf16 v[16:19], v[16:19], v[212:215], v[180:183]
	ds_read_b128 v[180:183], v137 offset:64
	v_mfma_f32_16x16x32_bf16 v[172:175], v[52:55], v[84:87], v[172:175]
	v_mfma_f32_16x16x32_bf16 v[144:147], v[52:55], v[200:203], v[144:147]
	v_mfma_f32_16x16x32_bf16 v[160:163], v[52:55], v[204:207], v[160:163]
	v_mfma_f32_16x16x32_bf16 v[40:43], v[52:55], v[212:215], v[40:43]
	v_mfma_f32_16x16x32_bf16 v[52:55], v[64:67], v[84:87], v[176:179]
	v_mfma_f32_16x16x32_bf16 v[164:167], v[64:67], v[200:203], v[164:167]
	v_mfma_f32_16x16x32_bf16 v[168:171], v[64:67], v[204:207], v[168:171]
	v_mfma_f32_16x16x32_bf16 v[64:67], v[64:67], v[212:215], v[184:187]
	ds_read_b128 v[184:187], v137 offset:2624
	v_mfma_f32_16x16x32_bf16 v[84:87], v[80:83], v[84:87], v[188:191]
	ds_read_b128 v[188:191], v137 offset:5184
	v_mfma_f32_16x16x32_bf16 v[176:179], v[80:83], v[200:203], v[196:199]
	ds_read_b128 v[196:199], v138 offset:64
	ds_read_b128 v[200:203], v138 offset:2624
	v_mfma_f32_16x16x32_bf16 v[140:143], v[80:83], v[204:207], v[140:143]
	ds_read_b128 v[204:207], v138 offset:5184
	v_mfma_f32_16x16x32_bf16 v[80:83], v[80:83], v[212:215], v[192:195]
	ds_read_b128 v[192:195], v137 offset:7744
	ds_read_b128 v[212:215], v138 offset:7744
	s_waitcnt vmcnt(23)
	ds_write_b128 v136, v[0:3] offset:40960
	s_waitcnt vmcnt(22)
	ds_write_b128 v136, v[12:15] offset:46080
	s_waitcnt vmcnt(21)
	ds_write_b128 v136, v[20:23] offset:51200
	s_waitcnt vmcnt(20)
	ds_write_b128 v136, v[28:31] offset:56320
	s_waitcnt vmcnt(19)
	ds_write_b128 v136, v[56:59] offset:61440
	s_waitcnt vmcnt(18)
	ds_write_b128 v139, v[88:91] offset:5120
	s_waitcnt vmcnt(17)
	ds_write_b128 v139, v[92:95] offset:10240
	s_waitcnt vmcnt(16)
	ds_write_b128 v139, v[68:71] offset:15360
	s_waitcnt lgkmcnt(8)
	v_mfma_f32_16x16x32_bf16 v[148:151], v[180:183], v[196:199], v[148:151]
	s_waitcnt lgkmcnt(10)
	v_mfma_f32_16x16x32_bf16 v[152:155], v[180:183], v[200:203], v[152:155]
	s_waitcnt lgkmcnt(9)
	v_mfma_f32_16x16x32_bf16 v[156:159], v[180:183], v[204:207], v[156:159]
	s_waitcnt lgkmcnt(8)
	v_mfma_f32_16x16x32_bf16 v[180:183], v[180:183], v[212:215], v[16:19]
	v_mfma_f32_16x16x32_bf16 v[172:175], v[184:187], v[196:199], v[172:175]
	v_mfma_f32_16x16x32_bf16 v[144:147], v[184:187], v[200:203], v[144:147]
	v_mfma_f32_16x16x32_bf16 v[160:163], v[184:187], v[204:207], v[160:163]
	v_mfma_f32_16x16x32_bf16 v[184:187], v[184:187], v[212:215], v[40:43]
	v_mfma_f32_16x16x32_bf16 v[224:227], v[188:191], v[196:199], v[52:55]
	v_mfma_f32_16x16x32_bf16 v[164:167], v[188:191], v[200:203], v[164:167]
	v_mfma_f32_16x16x32_bf16 v[168:171], v[188:191], v[204:207], v[168:171]
	v_mfma_f32_16x16x32_bf16 v[188:191], v[188:191], v[212:215], v[64:67]
	v_mfma_f32_16x16x32_bf16 v[196:199], v[192:195], v[196:199], v[84:87]
	v_mfma_f32_16x16x32_bf16 v[176:179], v[192:195], v[200:203], v[176:179]
	v_mfma_f32_16x16x32_bf16 v[140:143], v[192:195], v[204:207], v[140:143]
	v_mfma_f32_16x16x32_bf16 v[192:195], v[192:195], v[212:215], v[80:83]
	global_load_dwordx4 v[12:15], v[134:135], off offset:1280
	global_load_dwordx4 v[16:19], v[128:129], off offset:1280
	global_load_dwordx4 v[28:31], v[130:131], off offset:1280
	global_load_dwordx4 v[40:43], v[132:133], off offset:1280
	global_load_dwordx4 v[52:55], v[120:121], off offset:1280
	global_load_dwordx4 v[80:83], v[122:123], off offset:1280
	global_load_dwordx4 v[84:87], v[124:125], off offset:1280
	global_load_dwordx4 v[64:67], v[126:127], off offset:1280
	s_waitcnt lgkmcnt(0)
	s_barrier
	ds_read_b128 v[0:3], v137 offset:40960
	ds_read_b128 v[20:23], v137 offset:43520
	ds_read_b128 v[56:59], v137 offset:46080
	ds_read_b128 v[68:71], v137 offset:48640
	ds_read_b128 v[88:91], v138 offset:40960
	ds_read_b128 v[92:95], v138 offset:43520
	ds_read_b128 v[200:203], v138 offset:46080
	ds_read_b128 v[204:207], v138 offset:48640
	s_waitcnt lgkmcnt(3)
	v_mfma_f32_16x16x32_bf16 v[148:151], v[0:3], v[88:91], v[148:151]
	s_waitcnt lgkmcnt(2)
	v_mfma_f32_16x16x32_bf16 v[152:155], v[0:3], v[92:95], v[152:155]
	s_waitcnt lgkmcnt(1)
	v_mfma_f32_16x16x32_bf16 v[156:159], v[0:3], v[200:203], v[156:159]
	s_waitcnt lgkmcnt(0)
	v_mfma_f32_16x16x32_bf16 v[0:3], v[0:3], v[204:207], v[180:183]
	ds_read_b128 v[212:215], v138 offset:48704
	v_mfma_f32_16x16x32_bf16 v[172:175], v[20:23], v[88:91], v[172:175]
	v_mfma_f32_16x16x32_bf16 v[144:147], v[20:23], v[92:95], v[144:147]
	v_mfma_f32_16x16x32_bf16 v[160:163], v[20:23], v[200:203], v[160:163]
	v_mfma_f32_16x16x32_bf16 v[20:23], v[20:23], v[204:207], v[184:187]
	ds_read_b128 v[184:187], v137 offset:43584
	v_mfma_f32_16x16x32_bf16 v[180:183], v[56:59], v[88:91], v[224:227]
	v_mfma_f32_16x16x32_bf16 v[164:167], v[56:59], v[92:95], v[164:167]
	v_mfma_f32_16x16x32_bf16 v[168:171], v[56:59], v[200:203], v[168:171]
	v_mfma_f32_16x16x32_bf16 v[56:59], v[56:59], v[204:207], v[188:191]
	ds_read_b128 v[188:191], v137 offset:46144
	v_mfma_f32_16x16x32_bf16 v[88:91], v[68:71], v[88:91], v[196:199]
	ds_read_b128 v[196:199], v138 offset:41024
	v_mfma_f32_16x16x32_bf16 v[92:95], v[68:71], v[92:95], v[176:179]
	ds_read_b128 v[176:179], v137 offset:41024
	v_mfma_f32_16x16x32_bf16 v[140:143], v[68:71], v[200:203], v[140:143]
	ds_read_b128 v[200:203], v138 offset:43584
	v_mfma_f32_16x16x32_bf16 v[68:71], v[68:71], v[204:207], v[192:195]
	ds_read_b128 v[192:195], v137 offset:48704
	ds_read_b128 v[204:207], v138 offset:46144
	s_nop 0
	s_waitcnt vmcnt(23)
	ds_write_b128 v136, v[32:35]
	s_waitcnt vmcnt(22)
	ds_write_b128 v136, v[44:47] offset:5120
	s_waitcnt vmcnt(21)
	ds_write_b128 v136, v[96:99] offset:10240
	s_waitcnt vmcnt(20)
	ds_write_b128 v136, v[100:103] offset:15360
	s_waitcnt vmcnt(19)
	ds_write_b128 v136, v[104:107] offset:20480
	s_waitcnt vmcnt(18)
	ds_write_b128 v136, v[108:111] offset:25600
	s_waitcnt vmcnt(17)
	ds_write_b128 v136, v[112:115] offset:30720
	s_waitcnt vmcnt(16)
	ds_write_b128 v136, v[116:119] offset:35840
	s_waitcnt lgkmcnt(8)
	v_mfma_f32_16x16x32_bf16 v[148:151], v[176:179], v[196:199], v[148:151]
	s_waitcnt lgkmcnt(10)
	v_mfma_f32_16x16x32_bf16 v[152:155], v[176:179], v[200:203], v[152:155]
	s_waitcnt lgkmcnt(9)
	v_mfma_f32_16x16x32_bf16 v[156:159], v[176:179], v[204:207], v[156:159]
	s_waitcnt lgkmcnt(8)
	v_mfma_f32_16x16x32_bf16 v[176:179], v[176:179], v[212:215], v[0:3]
	v_mfma_f32_16x16x32_bf16 v[172:175], v[184:187], v[196:199], v[172:175]
	v_mfma_f32_16x16x32_bf16 v[144:147], v[184:187], v[200:203], v[144:147]
	v_mfma_f32_16x16x32_bf16 v[160:163], v[184:187], v[204:207], v[160:163]
	v_mfma_f32_16x16x32_bf16 v[184:187], v[184:187], v[212:215], v[20:23]
	v_mfma_f32_16x16x32_bf16 v[180:183], v[188:191], v[196:199], v[180:183]
	v_mfma_f32_16x16x32_bf16 v[164:167], v[188:191], v[200:203], v[164:167]
	v_mfma_f32_16x16x32_bf16 v[168:171], v[188:191], v[204:207], v[168:171]
	v_mfma_f32_16x16x32_bf16 v[188:191], v[188:191], v[212:215], v[56:59]
	v_mfma_f32_16x16x32_bf16 v[196:199], v[192:195], v[196:199], v[88:91]
	v_mfma_f32_16x16x32_bf16 v[200:203], v[192:195], v[200:203], v[92:95]
	v_mfma_f32_16x16x32_bf16 v[140:143], v[192:195], v[204:207], v[140:143]
	v_mfma_f32_16x16x32_bf16 v[192:195], v[192:195], v[212:215], v[68:71]
	global_load_dwordx4 v[0:3], v[134:135], off offset:1408
	global_load_dwordx4 v[20:23], v[128:129], off offset:1408
	global_load_dwordx4 v[32:35], v[130:131], off offset:1408
	global_load_dwordx4 v[44:47], v[132:133], off offset:1408
	global_load_dwordx4 v[56:59], v[120:121], off offset:1408
	global_load_dwordx4 v[88:91], v[122:123], off offset:1408
	global_load_dwordx4 v[92:95], v[124:125], off offset:1408
	global_load_dwordx4 v[68:71], v[126:127], off offset:1408
	s_waitcnt lgkmcnt(0)
	s_barrier
	ds_read_b128 v[96:99], v137
	ds_read_b128 v[100:103], v137 offset:2560
	ds_read_b128 v[104:107], v137 offset:5120
	ds_read_b128 v[108:111], v137 offset:7680
	ds_read_b128 v[112:115], v138
	ds_read_b128 v[116:119], v138 offset:2560
	ds_read_b128 v[204:207], v138 offset:5120
	ds_read_b128 v[212:215], v138 offset:7680
	s_waitcnt lgkmcnt(3)
	v_mfma_f32_16x16x32_bf16 v[148:151], v[96:99], v[112:115], v[148:151]
	s_waitcnt lgkmcnt(2)
	v_mfma_f32_16x16x32_bf16 v[152:155], v[96:99], v[116:119], v[152:155]
	s_waitcnt lgkmcnt(1)
	v_mfma_f32_16x16x32_bf16 v[156:159], v[96:99], v[204:207], v[156:159]
	s_waitcnt lgkmcnt(0)
	v_mfma_f32_16x16x32_bf16 v[96:99], v[96:99], v[212:215], v[176:179]
	v_mfma_f32_16x16x32_bf16 v[172:175], v[100:103], v[112:115], v[172:175]
	v_mfma_f32_16x16x32_bf16 v[144:147], v[100:103], v[116:119], v[144:147]
	v_mfma_f32_16x16x32_bf16 v[160:163], v[100:103], v[204:207], v[160:163]
	v_mfma_f32_16x16x32_bf16 v[100:103], v[100:103], v[212:215], v[184:187]
	ds_read_b128 v[184:187], v137 offset:2624
	v_mfma_f32_16x16x32_bf16 v[176:179], v[104:107], v[112:115], v[180:183]
	ds_read_b128 v[180:183], v137 offset:64
	v_mfma_f32_16x16x32_bf16 v[164:167], v[104:107], v[116:119], v[164:167]
	v_mfma_f32_16x16x32_bf16 v[168:171], v[104:107], v[204:207], v[168:171]
	v_mfma_f32_16x16x32_bf16 v[104:107], v[104:107], v[212:215], v[188:191]
	ds_read_b128 v[188:191], v137 offset:5184
	v_mfma_f32_16x16x32_bf16 v[112:115], v[108:111], v[112:115], v[196:199]
	ds_read_b128 v[196:199], v138 offset:64
	v_mfma_f32_16x16x32_bf16 v[116:119], v[108:111], v[116:119], v[200:203]
	ds_read_b128 v[200:203], v138 offset:2624
	v_mfma_f32_16x16x32_bf16 v[140:143], v[108:111], v[204:207], v[140:143]
	ds_read_b128 v[204:207], v138 offset:5184
	v_mfma_f32_16x16x32_bf16 v[108:111], v[108:111], v[212:215], v[192:195]
	ds_read_b128 v[192:195], v137 offset:7744
	ds_read_b128 v[212:215], v138 offset:7744
	s_waitcnt vmcnt(23)
	ds_write_b128 v136, v[4:7] offset:40960
	s_waitcnt vmcnt(22)
	ds_write_b128 v136, v[8:11] offset:46080
	s_waitcnt vmcnt(21)
	ds_write_b128 v136, v[24:27] offset:51200
	s_waitcnt vmcnt(20)
	ds_write_b128 v136, v[36:39] offset:56320
	s_waitcnt vmcnt(19)
	ds_write_b128 v136, v[48:51] offset:61440
	s_waitcnt vmcnt(18)
	ds_write_b128 v139, v[72:75] offset:5120
	s_waitcnt vmcnt(17)
	ds_write_b128 v139, v[76:79] offset:10240
	s_waitcnt vmcnt(16)
	ds_write_b128 v139, v[60:63] offset:15360
	s_waitcnt lgkmcnt(8)
	v_mfma_f32_16x16x32_bf16 v[148:151], v[180:183], v[196:199], v[148:151]
	s_waitcnt lgkmcnt(10)
	v_mfma_f32_16x16x32_bf16 v[152:155], v[180:183], v[200:203], v[152:155]
	s_waitcnt lgkmcnt(9)
	v_mfma_f32_16x16x32_bf16 v[156:159], v[180:183], v[204:207], v[156:159]
	s_waitcnt lgkmcnt(8)
	v_mfma_f32_16x16x32_bf16 v[180:183], v[180:183], v[212:215], v[96:99]
	v_mfma_f32_16x16x32_bf16 v[172:175], v[184:187], v[196:199], v[172:175]
	v_mfma_f32_16x16x32_bf16 v[144:147], v[184:187], v[200:203], v[144:147]
	v_mfma_f32_16x16x32_bf16 v[160:163], v[184:187], v[204:207], v[160:163]
	v_mfma_f32_16x16x32_bf16 v[184:187], v[184:187], v[212:215], v[100:103]
	v_mfma_f32_16x16x32_bf16 v[176:179], v[188:191], v[196:199], v[176:179]
	v_mfma_f32_16x16x32_bf16 v[164:167], v[188:191], v[200:203], v[164:167]
	v_mfma_f32_16x16x32_bf16 v[168:171], v[188:191], v[204:207], v[168:171]
	v_mfma_f32_16x16x32_bf16 v[188:191], v[188:191], v[212:215], v[104:107]
	v_mfma_f32_16x16x32_bf16 v[196:199], v[192:195], v[196:199], v[112:115]
	v_mfma_f32_16x16x32_bf16 v[116:119], v[192:195], v[200:203], v[116:119]
	v_mfma_f32_16x16x32_bf16 v[140:143], v[192:195], v[204:207], v[140:143]
	v_mfma_f32_16x16x32_bf16 v[192:195], v[192:195], v[212:215], v[108:111]
	global_load_dwordx4 v[60:63], v[134:135], off offset:1536
	global_load_dwordx4 v[72:75], v[128:129], off offset:1536
	global_load_dwordx4 v[76:79], v[130:131], off offset:1536
	global_load_dwordx4 v[96:99], v[132:133], off offset:1536
	global_load_dwordx4 v[100:103], v[120:121], off offset:1536
	global_load_dwordx4 v[104:107], v[122:123], off offset:1536
	global_load_dwordx4 v[108:111], v[124:125], off offset:1536
	global_load_dwordx4 v[112:115], v[126:127], off offset:1536
	s_waitcnt lgkmcnt(0)
	s_barrier
	ds_read_b128 v[4:7], v137 offset:40960
	ds_read_b128 v[8:11], v137 offset:43520
	ds_read_b128 v[24:27], v137 offset:46080
	ds_read_b128 v[36:39], v137 offset:48640
	ds_read_b128 v[48:51], v138 offset:40960
	ds_read_b128 v[200:203], v138 offset:43520
	ds_read_b128 v[204:207], v138 offset:46080
	ds_read_b128 v[212:215], v138 offset:48640
	s_waitcnt lgkmcnt(3)
	v_mfma_f32_16x16x32_bf16 v[148:151], v[4:7], v[48:51], v[148:151]
	s_waitcnt lgkmcnt(2)
	v_mfma_f32_16x16x32_bf16 v[152:155], v[4:7], v[200:203], v[152:155]
	s_waitcnt lgkmcnt(1)
	v_mfma_f32_16x16x32_bf16 v[156:159], v[4:7], v[204:207], v[156:159]
	s_waitcnt lgkmcnt(0)
	v_mfma_f32_16x16x32_bf16 v[4:7], v[4:7], v[212:215], v[180:183]
	ds_read_b128 v[180:183], v137 offset:41024
	v_mfma_f32_16x16x32_bf16 v[172:175], v[8:11], v[48:51], v[172:175]
	v_mfma_f32_16x16x32_bf16 v[144:147], v[8:11], v[200:203], v[144:147]
	v_mfma_f32_16x16x32_bf16 v[160:163], v[8:11], v[204:207], v[160:163]
	v_mfma_f32_16x16x32_bf16 v[8:11], v[8:11], v[212:215], v[184:187]
	ds_read_b128 v[184:187], v137 offset:43584
	v_mfma_f32_16x16x32_bf16 v[176:179], v[24:27], v[48:51], v[176:179]
	v_mfma_f32_16x16x32_bf16 v[164:167], v[24:27], v[200:203], v[164:167]
	v_mfma_f32_16x16x32_bf16 v[168:171], v[24:27], v[204:207], v[168:171]
	v_mfma_f32_16x16x32_bf16 v[24:27], v[24:27], v[212:215], v[188:191]
	ds_read_b128 v[188:191], v137 offset:46144
	v_mfma_f32_16x16x32_bf16 v[48:51], v[36:39], v[48:51], v[196:199]
	ds_read_b128 v[196:199], v138 offset:41024
	v_mfma_f32_16x16x32_bf16 v[116:119], v[36:39], v[200:203], v[116:119]
	ds_read_b128 v[200:203], v138 offset:43584
	v_mfma_f32_16x16x32_bf16 v[140:143], v[36:39], v[204:207], v[140:143]
	ds_read_b128 v[204:207], v138 offset:46144
	v_mfma_f32_16x16x32_bf16 v[36:39], v[36:39], v[212:215], v[192:195]
	ds_read_b128 v[192:195], v137 offset:48704
	ds_read_b128 v[212:215], v138 offset:48704
	s_waitcnt vmcnt(23)
	ds_write_b128 v136, v[12:15]
	s_waitcnt vmcnt(22)
	ds_write_b128 v136, v[16:19] offset:5120
	s_waitcnt vmcnt(21)
	ds_write_b128 v136, v[28:31] offset:10240
	s_waitcnt vmcnt(20)
	ds_write_b128 v136, v[40:43] offset:15360
	s_waitcnt vmcnt(19)
	ds_write_b128 v136, v[52:55] offset:20480
	s_waitcnt vmcnt(18)
	ds_write_b128 v136, v[80:83] offset:25600
	s_waitcnt vmcnt(17)
	ds_write_b128 v136, v[84:87] offset:30720
	s_waitcnt vmcnt(16)
	ds_write_b128 v136, v[64:67] offset:35840
	s_waitcnt lgkmcnt(8)
	v_mfma_f32_16x16x32_bf16 v[148:151], v[180:183], v[196:199], v[148:151]
	s_waitcnt lgkmcnt(10)
	v_mfma_f32_16x16x32_bf16 v[152:155], v[180:183], v[200:203], v[152:155]
	s_waitcnt lgkmcnt(9)
	v_mfma_f32_16x16x32_bf16 v[156:159], v[180:183], v[204:207], v[156:159]
	s_waitcnt lgkmcnt(8)
	v_mfma_f32_16x16x32_bf16 v[180:183], v[180:183], v[212:215], v[4:7]
	v_mfma_f32_16x16x32_bf16 v[172:175], v[184:187], v[196:199], v[172:175]
	v_mfma_f32_16x16x32_bf16 v[144:147], v[184:187], v[200:203], v[144:147]
	v_mfma_f32_16x16x32_bf16 v[160:163], v[184:187], v[204:207], v[160:163]
	v_mfma_f32_16x16x32_bf16 v[184:187], v[184:187], v[212:215], v[8:11]
	v_mfma_f32_16x16x32_bf16 v[176:179], v[188:191], v[196:199], v[176:179]
	v_mfma_f32_16x16x32_bf16 v[164:167], v[188:191], v[200:203], v[164:167]
	v_mfma_f32_16x16x32_bf16 v[168:171], v[188:191], v[204:207], v[168:171]
	v_mfma_f32_16x16x32_bf16 v[188:191], v[188:191], v[212:215], v[24:27]
	v_mfma_f32_16x16x32_bf16 v[48:51], v[192:195], v[196:199], v[48:51]
	v_mfma_f32_16x16x32_bf16 v[116:119], v[192:195], v[200:203], v[116:119]
	v_mfma_f32_16x16x32_bf16 v[140:143], v[192:195], v[204:207], v[140:143]
	v_mfma_f32_16x16x32_bf16 v[192:195], v[192:195], v[212:215], v[36:39]
	global_load_dwordx4 v[4:7], v[134:135], off offset:1664
	global_load_dwordx4 v[12:15], v[128:129], off offset:1664
	global_load_dwordx4 v[8:11], v[130:131], off offset:1664
	global_load_dwordx4 v[16:19], v[132:133], off offset:1664
	global_load_dwordx4 v[24:27], v[120:121], off offset:1664
	global_load_dwordx4 v[28:31], v[122:123], off offset:1664
	global_load_dwordx4 v[36:39], v[124:125], off offset:1664
	global_load_dwordx4 v[40:43], v[126:127], off offset:1664
	s_waitcnt lgkmcnt(0)
	s_barrier
	ds_read_b128 v[52:55], v137
	ds_read_b128 v[64:67], v137 offset:2560
	ds_read_b128 v[80:83], v137 offset:5120
	ds_read_b128 v[84:87], v137 offset:7680
	ds_read_b128 v[196:199], v138
	ds_read_b128 v[200:203], v138 offset:2560
	ds_read_b128 v[204:207], v138 offset:5120
	ds_read_b128 v[212:215], v138 offset:7680
	s_waitcnt lgkmcnt(3)
	v_mfma_f32_16x16x32_bf16 v[148:151], v[52:55], v[196:199], v[148:151]
	s_waitcnt lgkmcnt(2)
	v_mfma_f32_16x16x32_bf16 v[152:155], v[52:55], v[200:203], v[152:155]
	s_waitcnt lgkmcnt(1)
	v_mfma_f32_16x16x32_bf16 v[156:159], v[52:55], v[204:207], v[156:159]
	s_waitcnt lgkmcnt(0)
	v_mfma_f32_16x16x32_bf16 v[52:55], v[52:55], v[212:215], v[180:183]
	ds_read_b128 v[180:183], v137 offset:64
	v_mfma_f32_16x16x32_bf16 v[172:175], v[64:67], v[196:199], v[172:175]
	v_mfma_f32_16x16x32_bf16 v[144:147], v[64:67], v[200:203], v[144:147]
	v_mfma_f32_16x16x32_bf16 v[160:163], v[64:67], v[204:207], v[160:163]
	v_mfma_f32_16x16x32_bf16 v[64:67], v[64:67], v[212:215], v[184:187]
	ds_read_b128 v[184:187], v137 offset:2624
	v_mfma_f32_16x16x32_bf16 v[176:179], v[80:83], v[196:199], v[176:179]
	v_mfma_f32_16x16x32_bf16 v[164:167], v[80:83], v[200:203], v[164:167]
	v_mfma_f32_16x16x32_bf16 v[168:171], v[80:83], v[204:207], v[168:171]
	v_mfma_f32_16x16x32_bf16 v[80:83], v[80:83], v[212:215], v[188:191]
	ds_read_b128 v[188:191], v137 offset:5184
	v_mfma_f32_16x16x32_bf16 v[48:51], v[84:87], v[196:199], v[48:51]
	ds_read_b128 v[196:199], v138 offset:64
	v_mfma_f32_16x16x32_bf16 v[116:119], v[84:87], v[200:203], v[116:119]
	ds_read_b128 v[200:203], v138 offset:2624
	v_mfma_f32_16x16x32_bf16 v[140:143], v[84:87], v[204:207], v[140:143]
	ds_read_b128 v[204:207], v138 offset:5184
	v_mfma_f32_16x16x32_bf16 v[84:87], v[84:87], v[212:215], v[192:195]
	ds_read_b128 v[192:195], v137 offset:7744
	ds_read_b128 v[212:215], v138 offset:7744
	s_waitcnt vmcnt(23)
	ds_write_b128 v136, v[0:3] offset:40960
	s_waitcnt vmcnt(22)
	ds_write_b128 v136, v[20:23] offset:46080
	s_waitcnt vmcnt(21)
	ds_write_b128 v136, v[32:35] offset:51200
	s_waitcnt vmcnt(20)
	ds_write_b128 v136, v[44:47] offset:56320
	s_waitcnt vmcnt(19)
	ds_write_b128 v136, v[56:59] offset:61440
	s_waitcnt vmcnt(18)
	ds_write_b128 v139, v[88:91] offset:5120
	s_waitcnt vmcnt(17)
	ds_write_b128 v139, v[92:95] offset:10240
	s_waitcnt vmcnt(16)
	ds_write_b128 v139, v[68:71] offset:15360
	s_waitcnt lgkmcnt(8)
	v_mfma_f32_16x16x32_bf16 v[148:151], v[180:183], v[196:199], v[148:151]
	s_waitcnt lgkmcnt(10)
	v_mfma_f32_16x16x32_bf16 v[152:155], v[180:183], v[200:203], v[152:155]
	s_waitcnt lgkmcnt(9)
	v_mfma_f32_16x16x32_bf16 v[156:159], v[180:183], v[204:207], v[156:159]
	s_waitcnt lgkmcnt(8)
	v_mfma_f32_16x16x32_bf16 v[180:183], v[180:183], v[212:215], v[52:55]
	v_mfma_f32_16x16x32_bf16 v[172:175], v[184:187], v[196:199], v[172:175]
	v_mfma_f32_16x16x32_bf16 v[144:147], v[184:187], v[200:203], v[144:147]
	v_mfma_f32_16x16x32_bf16 v[160:163], v[184:187], v[204:207], v[160:163]
	v_mfma_f32_16x16x32_bf16 v[184:187], v[184:187], v[212:215], v[64:67]
	v_mfma_f32_16x16x32_bf16 v[176:179], v[188:191], v[196:199], v[176:179]
	v_mfma_f32_16x16x32_bf16 v[164:167], v[188:191], v[200:203], v[164:167]
	v_mfma_f32_16x16x32_bf16 v[168:171], v[188:191], v[204:207], v[168:171]
	v_mfma_f32_16x16x32_bf16 v[80:83], v[188:191], v[212:215], v[80:83]
	v_mfma_f32_16x16x32_bf16 v[188:191], v[192:195], v[196:199], v[48:51]
	global_load_dwordx4 v[20:23], v[134:135], off offset:1792
	s_nop 1
	global_load_dwordx4 v[48:51], v[128:129], off offset:1792
	global_load_dwordx4 v[32:35], v[130:131], off offset:1792
	global_load_dwordx4 v[44:47], v[132:133], off offset:1792
	global_load_dwordx4 v[52:55], v[120:121], off offset:1792
	global_load_dwordx4 v[56:59], v[122:123], off offset:1792
	global_load_dwordx4 v[64:67], v[124:125], off offset:1792
	global_load_dwordx4 v[68:71], v[126:127], off offset:1792
	s_waitcnt lgkmcnt(0)
	s_barrier
	v_mfma_f32_16x16x32_bf16 v[116:119], v[192:195], v[200:203], v[116:119]
	v_mfma_f32_16x16x32_bf16 v[140:143], v[192:195], v[204:207], v[140:143]
	v_mfma_f32_16x16x32_bf16 v[84:87], v[192:195], v[212:215], v[84:87]
	ds_read_b128 v[0:3], v137 offset:40960
	ds_read_b128 v[88:91], v137 offset:43520
	ds_read_b128 v[92:95], v137 offset:46080
	ds_read_b128 v[192:195], v137 offset:48640
	ds_read_b128 v[196:199], v138 offset:40960
	ds_read_b128 v[200:203], v138 offset:43520
	ds_read_b128 v[204:207], v138 offset:46080
	ds_read_b128 v[212:215], v138 offset:48640
	s_waitcnt lgkmcnt(3)
	v_mfma_f32_16x16x32_bf16 v[148:151], v[0:3], v[196:199], v[148:151]
	s_waitcnt lgkmcnt(2)
	v_mfma_f32_16x16x32_bf16 v[152:155], v[0:3], v[200:203], v[152:155]
	s_waitcnt lgkmcnt(1)
	v_mfma_f32_16x16x32_bf16 v[156:159], v[0:3], v[204:207], v[156:159]
	s_waitcnt lgkmcnt(0)
	v_mfma_f32_16x16x32_bf16 v[0:3], v[0:3], v[212:215], v[180:183]
	ds_read_b128 v[180:183], v137 offset:41024
	v_mfma_f32_16x16x32_bf16 v[172:175], v[88:91], v[196:199], v[172:175]
	v_mfma_f32_16x16x32_bf16 v[144:147], v[88:91], v[200:203], v[144:147]
	v_mfma_f32_16x16x32_bf16 v[160:163], v[88:91], v[204:207], v[160:163]
	v_mfma_f32_16x16x32_bf16 v[88:91], v[88:91], v[212:215], v[184:187]
	ds_read_b128 v[184:187], v137 offset:43584
	v_mfma_f32_16x16x32_bf16 v[176:179], v[92:95], v[196:199], v[176:179]
	v_mfma_f32_16x16x32_bf16 v[164:167], v[92:95], v[200:203], v[164:167]
	v_mfma_f32_16x16x32_bf16 v[168:171], v[92:95], v[204:207], v[168:171]
	v_mfma_f32_16x16x32_bf16 v[80:83], v[92:95], v[212:215], v[80:83]
	v_mfma_f32_16x16x32_bf16 v[92:95], v[192:195], v[196:199], v[188:191]
	ds_read_b128 v[188:191], v137 offset:46144
	ds_read_b128 v[196:199], v138 offset:41024
	v_mfma_f32_16x16x32_bf16 v[116:119], v[192:195], v[200:203], v[116:119]
	ds_read_b128 v[200:203], v138 offset:43584
	v_mfma_f32_16x16x32_bf16 v[140:143], v[192:195], v[204:207], v[140:143]
	ds_read_b128 v[204:207], v138 offset:46144
	v_mfma_f32_16x16x32_bf16 v[84:87], v[192:195], v[212:215], v[84:87]
	ds_read_b128 v[192:195], v137 offset:48704
	ds_read_b128 v[212:215], v138 offset:48704
	s_waitcnt vmcnt(23)
	ds_write_b128 v136, v[60:63]
	s_waitcnt vmcnt(22)
	ds_write_b128 v136, v[72:75] offset:5120
	s_waitcnt vmcnt(21)
	ds_write_b128 v136, v[76:79] offset:10240
	s_waitcnt vmcnt(20)
	ds_write_b128 v136, v[96:99] offset:15360
	s_waitcnt vmcnt(19)
	ds_write_b128 v136, v[100:103] offset:20480
	s_waitcnt vmcnt(18)
	ds_write_b128 v136, v[104:107] offset:25600
	s_waitcnt vmcnt(17)
	ds_write_b128 v136, v[108:111] offset:30720
	s_waitcnt vmcnt(16)
	ds_write_b128 v136, v[112:115] offset:35840
	s_waitcnt lgkmcnt(8)
	v_mfma_f32_16x16x32_bf16 v[148:151], v[180:183], v[196:199], v[148:151]
	s_waitcnt lgkmcnt(10)
	v_mfma_f32_16x16x32_bf16 v[152:155], v[180:183], v[200:203], v[152:155]
	s_waitcnt lgkmcnt(9)
	v_mfma_f32_16x16x32_bf16 v[156:159], v[180:183], v[204:207], v[156:159]
	s_waitcnt lgkmcnt(8)
	v_mfma_f32_16x16x32_bf16 v[180:183], v[180:183], v[212:215], v[0:3]
	v_mfma_f32_16x16x32_bf16 v[172:175], v[184:187], v[196:199], v[172:175]
	v_mfma_f32_16x16x32_bf16 v[144:147], v[184:187], v[200:203], v[144:147]
	v_mfma_f32_16x16x32_bf16 v[160:163], v[184:187], v[204:207], v[160:163]
	v_mfma_f32_16x16x32_bf16 v[184:187], v[184:187], v[212:215], v[88:91]
	v_mfma_f32_16x16x32_bf16 v[176:179], v[188:191], v[196:199], v[176:179]
	v_mfma_f32_16x16x32_bf16 v[164:167], v[188:191], v[200:203], v[164:167]
	v_mfma_f32_16x16x32_bf16 v[168:171], v[188:191], v[204:207], v[168:171]
	v_mfma_f32_16x16x32_bf16 v[188:191], v[188:191], v[212:215], v[80:83]
	v_mfma_f32_16x16x32_bf16 v[196:199], v[192:195], v[196:199], v[92:95]
	v_mfma_f32_16x16x32_bf16 v[116:119], v[192:195], v[200:203], v[116:119]
	v_mfma_f32_16x16x32_bf16 v[140:143], v[192:195], v[204:207], v[140:143]
	v_mfma_f32_16x16x32_bf16 v[192:195], v[192:195], v[212:215], v[84:87]
	global_load_dwordx4 v[0:3], v[134:135], off offset:1920
	global_load_dwordx4 v[76:79], v[128:129], off offset:1920
	global_load_dwordx4 v[60:63], v[130:131], off offset:1920
	global_load_dwordx4 v[72:75], v[132:133], off offset:1920
	global_load_dwordx4 v[80:83], v[120:121], off offset:1920
	global_load_dwordx4 v[84:87], v[122:123], off offset:1920
	global_load_dwordx4 v[88:91], v[124:125], off offset:1920
	global_load_dwordx4 v[92:95], v[126:127], off offset:1920
	s_waitcnt lgkmcnt(0)
	s_barrier
	ds_read_b128 v[96:99], v137
	ds_read_b128 v[100:103], v137 offset:2560
	ds_read_b128 v[104:107], v137 offset:5120
	ds_read_b128 v[108:111], v137 offset:7680
	ds_read_b128 v[112:115], v138
	ds_read_b128 v[120:123], v138 offset:2560
	ds_read_b128 v[124:127], v138 offset:5120
	ds_read_b128 v[128:131], v138 offset:7680
	s_waitcnt lgkmcnt(3)
	v_mfma_f32_16x16x32_bf16 v[132:135], v[96:99], v[112:115], v[148:151]
	s_waitcnt lgkmcnt(2)
	v_mfma_f32_16x16x32_bf16 v[148:151], v[96:99], v[120:123], v[152:155]
	s_waitcnt lgkmcnt(1)
	v_mfma_f32_16x16x32_bf16 v[152:155], v[96:99], v[124:127], v[156:159]
	s_waitcnt lgkmcnt(0)
	v_mfma_f32_16x16x32_bf16 v[96:99], v[96:99], v[128:131], v[180:183]
	ds_read_b128 v[180:183], v138 offset:64
	v_mfma_f32_16x16x32_bf16 v[156:159], v[100:103], v[112:115], v[172:175]
	v_mfma_f32_16x16x32_bf16 v[144:147], v[100:103], v[120:123], v[144:147]
	v_mfma_f32_16x16x32_bf16 v[160:163], v[100:103], v[124:127], v[160:163]
	v_mfma_f32_16x16x32_bf16 v[100:103], v[100:103], v[128:131], v[184:187]
	ds_read_b128 v[184:187], v138 offset:2624
	v_mfma_f32_16x16x32_bf16 v[172:175], v[104:107], v[112:115], v[176:179]
	ds_read_b128 v[176:179], v137 offset:7744
	v_mfma_f32_16x16x32_bf16 v[164:167], v[104:107], v[120:123], v[164:167]
	v_mfma_f32_16x16x32_bf16 v[168:171], v[104:107], v[124:127], v[168:171]
	v_mfma_f32_16x16x32_bf16 v[104:107], v[104:107], v[128:131], v[188:191]
	ds_read_b128 v[188:191], v138 offset:5184
	v_mfma_f32_16x16x32_bf16 v[112:115], v[108:111], v[112:115], v[196:199]
	v_mfma_f32_16x16x32_bf16 v[116:119], v[108:111], v[120:123], v[116:119]
	v_mfma_f32_16x16x32_bf16 v[120:123], v[108:111], v[124:127], v[140:143]
	ds_read_b128 v[124:127], v137 offset:64
	ds_read_b128 v[140:143], v137 offset:5184
	v_mfma_f32_16x16x32_bf16 v[108:111], v[108:111], v[128:131], v[192:195]
	ds_read_b128 v[128:131], v137 offset:2624
	ds_read_b128 v[192:195], v138 offset:7744
	s_waitcnt vmcnt(23)
	ds_write_b128 v136, v[4:7] offset:40960
	s_waitcnt vmcnt(22)
	ds_write_b128 v136, v[12:15] offset:46080
	s_waitcnt vmcnt(21)
	ds_write_b128 v136, v[8:11] offset:51200
	s_waitcnt vmcnt(20)
	ds_write_b128 v136, v[16:19] offset:56320
	s_waitcnt vmcnt(19)
	ds_write_b128 v136, v[24:27] offset:61440
	s_waitcnt vmcnt(18)
	ds_write_b128 v139, v[28:31] offset:5120
	s_waitcnt vmcnt(17)
	ds_write_b128 v139, v[36:39] offset:10240
	s_waitcnt vmcnt(16)
	ds_write_b128 v139, v[40:43] offset:15360
	s_waitcnt lgkmcnt(8)
	s_barrier
	ds_read_b128 v[4:7], v137 offset:40960
	ds_read_b128 v[8:11], v137 offset:43520
	ds_read_b128 v[12:15], v137 offset:46080
	ds_read_b128 v[16:19], v137 offset:48640
	ds_read_b128 v[24:27], v138 offset:40960
	ds_read_b128 v[28:31], v138 offset:43520
	ds_read_b128 v[36:39], v138 offset:46080
	ds_read_b128 v[40:43], v138 offset:48640
	v_mfma_f32_16x16x32_bf16 v[132:135], v[124:127], v[180:183], v[132:135]
	v_mfma_f32_16x16x32_bf16 v[148:151], v[124:127], v[184:187], v[148:151]
	v_mfma_f32_16x16x32_bf16 v[152:155], v[124:127], v[188:191], v[152:155]
	v_mfma_f32_16x16x32_bf16 v[96:99], v[124:127], v[192:195], v[96:99]
	v_mfma_f32_16x16x32_bf16 v[124:127], v[128:131], v[180:183], v[156:159]
	v_mfma_f32_16x16x32_bf16 v[144:147], v[128:131], v[184:187], v[144:147]
	v_mfma_f32_16x16x32_bf16 v[156:159], v[128:131], v[188:191], v[160:163]
	v_mfma_f32_16x16x32_bf16 v[100:103], v[128:131], v[192:195], v[100:103]
	v_mfma_f32_16x16x32_bf16 v[128:131], v[140:143], v[180:183], v[172:175]
	v_mfma_f32_16x16x32_bf16 v[160:163], v[140:143], v[184:187], v[164:167]
	v_mfma_f32_16x16x32_bf16 v[164:167], v[140:143], v[188:191], v[168:171]
	v_mfma_f32_16x16x32_bf16 v[104:107], v[140:143], v[192:195], v[104:107]
	v_mfma_f32_16x16x32_bf16 v[112:115], v[176:179], v[180:183], v[112:115]
	v_mfma_f32_16x16x32_bf16 v[116:119], v[176:179], v[184:187], v[116:119]
	v_mfma_f32_16x16x32_bf16 v[120:123], v[176:179], v[188:191], v[120:123]
	v_mfma_f32_16x16x32_bf16 v[108:111], v[176:179], v[192:195], v[108:111]
	s_waitcnt lgkmcnt(3)
	v_mfma_f32_16x16x32_bf16 v[132:135], v[4:7], v[24:27], v[132:135]
	s_waitcnt lgkmcnt(2)
	v_mfma_f32_16x16x32_bf16 v[140:143], v[4:7], v[28:31], v[148:151]
	s_waitcnt lgkmcnt(1)
	v_mfma_f32_16x16x32_bf16 v[148:151], v[4:7], v[36:39], v[152:155]
	s_waitcnt lgkmcnt(0)
	v_mfma_f32_16x16x32_bf16 v[4:7], v[4:7], v[40:43], v[96:99]
	v_mfma_f32_16x16x32_bf16 v[96:99], v[8:11], v[24:27], v[124:127]
	v_mfma_f32_16x16x32_bf16 v[124:127], v[8:11], v[28:31], v[144:147]
	v_mfma_f32_16x16x32_bf16 v[144:147], v[8:11], v[36:39], v[156:159]
	ds_read_b128 v[156:159], v138 offset:46144
	v_mfma_f32_16x16x32_bf16 v[8:11], v[8:11], v[40:43], v[100:103]
	v_mfma_f32_16x16x32_bf16 v[100:103], v[12:15], v[24:27], v[128:131]
	v_mfma_f32_16x16x32_bf16 v[128:131], v[12:15], v[28:31], v[160:163]
	ds_read_b128 v[160:163], v138 offset:48704
	v_mfma_f32_16x16x32_bf16 v[152:155], v[12:15], v[36:39], v[164:167]
	v_mfma_f32_16x16x32_bf16 v[12:15], v[12:15], v[40:43], v[104:107]
	ds_read_b128 v[104:107], v137 offset:43584
	v_mfma_f32_16x16x32_bf16 v[24:27], v[16:19], v[24:27], v[112:115]
	ds_read_b128 v[112:115], v137 offset:48704
	v_mfma_f32_16x16x32_bf16 v[28:31], v[16:19], v[28:31], v[116:119]
	ds_read_b128 v[116:119], v138 offset:41024
	v_mfma_f32_16x16x32_bf16 v[36:39], v[16:19], v[36:39], v[120:123]
	ds_read_b128 v[120:123], v138 offset:43584
	v_mfma_f32_16x16x32_bf16 v[16:19], v[16:19], v[40:43], v[108:111]
	ds_read_b128 v[40:43], v137 offset:41024
	ds_read_b128 v[108:111], v137 offset:46144
	s_nop 0
	s_waitcnt vmcnt(15)
	ds_write_b128 v136, v[20:23]
	s_waitcnt vmcnt(14)
	ds_write_b128 v136, v[48:51] offset:5120
	s_waitcnt vmcnt(13)
	ds_write_b128 v136, v[32:35] offset:10240
	s_waitcnt vmcnt(12)
	ds_write_b128 v136, v[44:47] offset:15360
	s_waitcnt vmcnt(11)
	ds_write_b128 v136, v[52:55] offset:20480
	s_waitcnt vmcnt(10)
	ds_write_b128 v136, v[56:59] offset:25600
	s_waitcnt vmcnt(9)
	ds_write_b128 v136, v[64:67] offset:30720
	s_waitcnt vmcnt(8)
	ds_write_b128 v136, v[68:71] offset:35840
	s_waitcnt lgkmcnt(8)
	s_barrier
	ds_read_b128 v[20:23], v137
	ds_read_b128 v[32:35], v137 offset:2560
	ds_read_b128 v[44:47], v137 offset:5120
	ds_read_b128 v[48:51], v137 offset:7680
	ds_read_b128 v[52:55], v138
	ds_read_b128 v[56:59], v138 offset:2560
	ds_read_b128 v[64:67], v138 offset:5120
	ds_read_b128 v[68:71], v138 offset:7680
	v_mfma_f32_16x16x32_bf16 v[132:135], v[40:43], v[116:119], v[132:135]
	v_mfma_f32_16x16x32_bf16 v[140:143], v[40:43], v[120:123], v[140:143]
	v_mfma_f32_16x16x32_bf16 v[148:151], v[40:43], v[156:159], v[148:151]
	v_mfma_f32_16x16x32_bf16 v[4:7], v[40:43], v[160:163], v[4:7]
	v_mfma_f32_16x16x32_bf16 v[40:43], v[104:107], v[116:119], v[96:99]
	v_mfma_f32_16x16x32_bf16 v[96:99], v[104:107], v[120:123], v[124:127]
	v_mfma_f32_16x16x32_bf16 v[124:127], v[104:107], v[156:159], v[144:147]
	v_mfma_f32_16x16x32_bf16 v[8:11], v[104:107], v[160:163], v[8:11]
	v_mfma_f32_16x16x32_bf16 v[100:103], v[108:111], v[116:119], v[100:103]
	v_mfma_f32_16x16x32_bf16 v[104:107], v[108:111], v[120:123], v[128:131]
	v_mfma_f32_16x16x32_bf16 v[128:131], v[108:111], v[156:159], v[152:155]
	v_mfma_f32_16x16x32_bf16 v[12:15], v[108:111], v[160:163], v[12:15]
	v_mfma_f32_16x16x32_bf16 v[24:27], v[112:115], v[116:119], v[24:27]
	v_mfma_f32_16x16x32_bf16 v[28:31], v[112:115], v[120:123], v[28:31]
	ds_read_b128 v[120:123], v138 offset:5184
	v_mfma_f32_16x16x32_bf16 v[36:39], v[112:115], v[156:159], v[36:39]
	v_mfma_f32_16x16x32_bf16 v[16:19], v[112:115], v[160:163], v[16:19]
	s_waitcnt lgkmcnt(3)
	v_mfma_f32_16x16x32_bf16 v[108:111], v[20:23], v[52:55], v[132:135]
	s_waitcnt lgkmcnt(2)
	v_mfma_f32_16x16x32_bf16 v[112:115], v[20:23], v[56:59], v[140:143]
	s_waitcnt lgkmcnt(1)
	v_mfma_f32_16x16x32_bf16 v[116:119], v[20:23], v[64:67], v[148:151]
	s_waitcnt lgkmcnt(0)
	v_mfma_f32_16x16x32_bf16 v[4:7], v[20:23], v[68:71], v[4:7]
	v_mfma_f32_16x16x32_bf16 v[20:23], v[32:35], v[52:55], v[40:43]
	v_mfma_f32_16x16x32_bf16 v[40:43], v[32:35], v[56:59], v[96:99]
	v_mfma_f32_16x16x32_bf16 v[96:99], v[32:35], v[64:67], v[124:127]
	ds_read_b128 v[124:127], v138 offset:7744
	v_mfma_f32_16x16x32_bf16 v[8:11], v[32:35], v[68:71], v[8:11]
	v_mfma_f32_16x16x32_bf16 v[32:35], v[44:47], v[52:55], v[100:103]
	v_mfma_f32_16x16x32_bf16 v[100:103], v[44:47], v[56:59], v[104:107]
	v_mfma_f32_16x16x32_bf16 v[104:107], v[44:47], v[64:67], v[128:131]
	v_mfma_f32_16x16x32_bf16 v[12:15], v[44:47], v[68:71], v[12:15]
	ds_read_b128 v[44:47], v137 offset:64
	v_mfma_f32_16x16x32_bf16 v[24:27], v[48:51], v[52:55], v[24:27]
	ds_read_b128 v[52:55], v137 offset:5184
	v_mfma_f32_16x16x32_bf16 v[28:31], v[48:51], v[56:59], v[28:31]
	ds_read_b128 v[56:59], v137 offset:7744
	v_mfma_f32_16x16x32_bf16 v[36:39], v[48:51], v[64:67], v[36:39]
	ds_read_b128 v[64:67], v138 offset:64
	v_mfma_f32_16x16x32_bf16 v[16:19], v[48:51], v[68:71], v[16:19]
	ds_read_b128 v[48:51], v137 offset:2624
	ds_read_b128 v[68:71], v138 offset:2624
	s_waitcnt vmcnt(7)
	ds_write_b128 v136, v[0:3] offset:40960
	s_waitcnt vmcnt(6)
	ds_write_b128 v136, v[76:79] offset:46080
	s_waitcnt vmcnt(5)
	ds_write_b128 v136, v[60:63] offset:51200
	s_waitcnt vmcnt(4)
	ds_write_b128 v136, v[72:75] offset:56320
	s_waitcnt vmcnt(3)
	ds_write_b128 v136, v[80:83] offset:61440
	s_waitcnt vmcnt(2)
	ds_write_b128 v139, v[84:87] offset:5120
	s_waitcnt vmcnt(1)
	ds_write_b128 v139, v[88:91] offset:10240
	s_waitcnt vmcnt(0)
	ds_write_b128 v139, v[92:95] offset:15360
	s_waitcnt lgkmcnt(8)
	v_mfma_f32_16x16x32_bf16 v[108:111], v[44:47], v[64:67], v[108:111]
	s_barrier
	v_mfma_f32_16x16x32_bf16 v[112:115], v[44:47], v[68:71], v[112:115]
	v_mfma_f32_16x16x32_bf16 v[116:119], v[44:47], v[120:123], v[116:119]
	v_mfma_f32_16x16x32_bf16 v[4:7], v[44:47], v[124:127], v[4:7]
	v_mfma_f32_16x16x32_bf16 v[20:23], v[48:51], v[64:67], v[20:23]
	v_mfma_f32_16x16x32_bf16 v[40:43], v[48:51], v[68:71], v[40:43]
	v_mfma_f32_16x16x32_bf16 v[44:47], v[48:51], v[120:123], v[96:99]
	v_mfma_f32_16x16x32_bf16 v[8:11], v[48:51], v[124:127], v[8:11]
	v_mfma_f32_16x16x32_bf16 v[32:35], v[52:55], v[64:67], v[32:35]
	v_mfma_f32_16x16x32_bf16 v[48:51], v[52:55], v[68:71], v[100:103]
	v_mfma_f32_16x16x32_bf16 v[96:99], v[52:55], v[120:123], v[104:107]
	v_mfma_f32_16x16x32_bf16 v[12:15], v[52:55], v[124:127], v[12:15]
	v_mfma_f32_16x16x32_bf16 v[24:27], v[56:59], v[64:67], v[24:27]
	v_mfma_f32_16x16x32_bf16 v[28:31], v[56:59], v[68:71], v[28:31]
	v_mfma_f32_16x16x32_bf16 v[36:39], v[56:59], v[120:123], v[36:39]
	v_mfma_f32_16x16x32_bf16 v[16:19], v[56:59], v[124:127], v[16:19]
	ds_read_b128 v[0:3], v137 offset:40960
	ds_read_b128 v[52:55], v137 offset:43520
	ds_read_b128 v[56:59], v137 offset:46080
	ds_read_b128 v[60:63], v137 offset:48640
	ds_read_b128 v[64:67], v138 offset:40960
	ds_read_b128 v[68:71], v138 offset:43520
	ds_read_b128 v[72:75], v138 offset:46080
	ds_read_b128 v[76:79], v138 offset:48640
	s_waitcnt lgkmcnt(3)
	v_mfma_f32_16x16x32_bf16 v[80:83], v[0:3], v[64:67], v[108:111]
	s_waitcnt lgkmcnt(2)
	v_mfma_f32_16x16x32_bf16 v[84:87], v[0:3], v[68:71], v[112:115]
	s_waitcnt lgkmcnt(1)
	v_mfma_f32_16x16x32_bf16 v[88:91], v[0:3], v[72:75], v[116:119]
	s_waitcnt lgkmcnt(0)
	v_mfma_f32_16x16x32_bf16 v[0:3], v[0:3], v[76:79], v[4:7]
	ds_read_b128 v[92:95], v138 offset:48704
	v_mfma_f32_16x16x32_bf16 v[4:7], v[52:55], v[64:67], v[20:23]
	v_mfma_f32_16x16x32_bf16 v[20:23], v[52:55], v[68:71], v[40:43]
	v_mfma_f32_16x16x32_bf16 v[40:43], v[52:55], v[72:75], v[44:47]
	v_mfma_f32_16x16x32_bf16 v[8:11], v[52:55], v[76:79], v[8:11]
	ds_read_b128 v[52:55], v137 offset:41024
	v_mfma_f32_16x16x32_bf16 v[32:35], v[56:59], v[64:67], v[32:35]
	v_mfma_f32_16x16x32_bf16 v[44:47], v[56:59], v[68:71], v[48:51]
	v_mfma_f32_16x16x32_bf16 v[48:51], v[56:59], v[72:75], v[96:99]
	v_mfma_f32_16x16x32_bf16 v[12:15], v[56:59], v[76:79], v[12:15]
	ds_read_b128 v[56:59], v137 offset:43584
	v_mfma_f32_16x16x32_bf16 v[24:27], v[60:63], v[64:67], v[24:27]
	ds_read_b128 v[64:67], v137 offset:48704
	v_mfma_f32_16x16x32_bf16 v[28:31], v[60:63], v[68:71], v[28:31]
	ds_read_b128 v[68:71], v138 offset:41024
	v_mfma_f32_16x16x32_bf16 v[36:39], v[60:63], v[72:75], v[36:39]
	ds_read_b128 v[72:75], v138 offset:43584
	v_mfma_f32_16x16x32_bf16 v[16:19], v[60:63], v[76:79], v[16:19]
	ds_read_b128 v[60:63], v137 offset:46144
	ds_read_b128 v[76:79], v138 offset:46144
	s_waitcnt lgkmcnt(0)
	s_barrier
	v_mfma_f32_16x16x32_bf16 v[80:83], v[52:55], v[68:71], v[80:83]
	v_mfma_f32_16x16x32_bf16 v[84:87], v[52:55], v[72:75], v[84:87]
	v_mfma_f32_16x16x32_bf16 v[88:91], v[52:55], v[76:79], v[88:91]
	v_mfma_f32_16x16x32_bf16 v[0:3], v[52:55], v[92:95], v[0:3]
	v_mov_b32_e32 v52, v211
	s_nop 0
	v_lshrrev_b32_e32 v54, 2, v52
	v_lshrrev_b32_e32 v53, 1, v52
	v_and_b32_e32 v54, 12, v54
	v_and_or_b32 v53, v53, s43, v54
	v_and_b32_e32 v52, 0x4f, v52
	v_mfma_f32_16x16x32_bf16 v[4:7], v[56:59], v[68:71], v[4:7]
	v_lshlrev_b32_e32 v52, 2, v52
	v_mul_lo_u32 v53, v53, s22
	v_add3_u32 v52, 0, v52, v53
	v_mfma_f32_16x16x32_bf16 v[20:23], v[56:59], v[72:75], v[20:23]
	v_add_u32_e32 v53, 0x400, v52
	ds_write2_b32 v52, v80, v84 offset1:16
	ds_write2_b32 v52, v81, v85 offset0:132 offset1:148
	ds_write2_b32 v53, v82, v86 offset0:8 offset1:24
	ds_write2_b32 v53, v83, v87 offset0:140 offset1:156
	ds_write2_b32 v52, v88, v0 offset0:32 offset1:48
	ds_write2_b32 v52, v89, v1 offset0:164 offset1:180
	ds_write2_b32 v53, v90, v2 offset0:40 offset1:56
	ds_write2_b32 v53, v91, v3 offset0:172 offset1:188
	v_mfma_f32_16x16x32_bf16 v[32:35], v[60:63], v[68:71], v[32:35]
	v_add_u32_e32 v0, 0x2000, v52
	v_add_u32_e32 v1, 0x2400, v52
	ds_write2_b32 v0, v4, v20 offset0:64 offset1:80
	ds_write2_b32 v0, v5, v21 offset0:196 offset1:212
	v_mfma_f32_16x16x32_bf16 v[44:47], v[60:63], v[72:75], v[44:47]
	v_add_u32_e32 v2, 0x4800, v52
	v_mfma_f32_16x16x32_bf16 v[40:43], v[56:59], v[76:79], v[40:43]
	v_mfma_f32_16x16x32_bf16 v[8:11], v[56:59], v[92:95], v[8:11]
	ds_write2_b32 v1, v6, v22 offset0:72 offset1:88
	ds_write2_b32 v1, v7, v23 offset0:204 offset1:220
	s_nop 5
	ds_write2_b32 v0, v40, v8 offset0:96 offset1:112
	ds_write2_b32 v0, v41, v9 offset0:228 offset1:244
	ds_write2_b32 v1, v42, v10 offset0:104 offset1:120
	ds_write2_b32 v1, v43, v11 offset0:236 offset1:252
	v_add_u32_e32 v0, 0x4000, v52
	v_mfma_f32_16x16x32_bf16 v[48:51], v[60:63], v[76:79], v[48:51]
	v_add_u32_e32 v1, 0x4400, v52
	ds_write2_b32 v0, v32, v44 offset0:128 offset1:144
	ds_write2_b32 v1, v33, v45 offset0:4 offset1:20
	ds_write2_b32 v1, v34, v46 offset0:136 offset1:152
	v_mfma_f32_16x16x32_bf16 v[12:15], v[60:63], v[92:95], v[12:15]
	ds_write2_b32 v2, v35, v47 offset0:12 offset1:28
	s_nop 6
	ds_write2_b32 v0, v48, v12 offset0:160 offset1:176
	ds_write2_b32 v1, v49, v13 offset0:36 offset1:52
	ds_write2_b32 v1, v50, v14 offset0:168 offset1:184
	ds_write2_b32 v2, v51, v15 offset0:44 offset1:60
	v_mfma_f32_16x16x32_bf16 v[24:27], v[64:67], v[68:71], v[24:27]
	v_add_u32_e32 v0, 0x6000, v52
	v_add_u32_e32 v1, 0x6400, v52
	v_add_u32_e32 v2, 0x6800, v52
	v_mfma_f32_16x16x32_bf16 v[28:31], v[64:67], v[72:75], v[28:31]
	v_mfma_f32_16x16x32_bf16 v[36:39], v[64:67], v[76:79], v[36:39]
	v_mfma_f32_16x16x32_bf16 v[16:19], v[64:67], v[92:95], v[16:19]
	s_nop 5
	ds_write2_b32 v0, v24, v28 offset0:192 offset1:208
	ds_write2_b32 v1, v25, v29 offset0:68 offset1:84
	ds_write2_b32 v1, v26, v30 offset0:200 offset1:216
	ds_write2_b32 v2, v27, v31 offset0:76 offset1:92
	ds_write2_b32 v0, v36, v16 offset0:224 offset1:240
	ds_write2_b32 v1, v37, v17 offset0:100 offset1:116
	ds_write2_b32 v1, v38, v18 offset0:232 offset1:248
	ds_write2_b32 v2, v39, v19 offset0:108 offset1:124
	v_mov_b32_e32 v0, v211
	s_waitcnt lgkmcnt(0)
	s_barrier
	s_nop 0
	v_lshlrev_b32_e32 v1, 3, v0
	v_and_b32_e32 v1, 0x78, v1
	v_ashrrev_i32_e32 v10, 4, v0
	v_lshlrev_b32_e32 v0, 2, v1
	v_lshlrev_b32_e32 v208, 1, v1
	v_mul_lo_u32 v1, v10, s22
	v_add3_u32 v11, 0, v0, v1
	ds_read_b128 v[0:3], v11
	ds_read_b128 v[4:7], v11 offset:16
	v_lshl_add_u64 v[8:9], s[0:1], 0, v[208:209]
	v_add_u32_e32 v12, 16, v10
	s_waitcnt lgkmcnt(1)
	v_cvt_pk_bf16_f32 v0, v0, v1
	v_cvt_pk_bf16_f32 v1, v2, v3
	s_waitcnt lgkmcnt(0)
	v_cvt_pk_bf16_f32 v2, v4, v5
	v_cvt_pk_bf16_f32 v3, v6, v7
	v_mad_i64_i32 v[4:5], s[0:1], v10, s11, v[8:9]
	global_store_dwordx4 v[4:5], v[0:3], off nt
	ds_read_b128 v[0:3], v11 offset:8448
	ds_read_b128 v[4:7], v11 offset:8464
	s_waitcnt lgkmcnt(1)
	v_cvt_pk_bf16_f32 v0, v0, v1
	v_cvt_pk_bf16_f32 v1, v2, v3
	s_waitcnt lgkmcnt(0)
	v_cvt_pk_bf16_f32 v2, v4, v5
	v_cvt_pk_bf16_f32 v3, v6, v7
	v_mad_i64_i32 v[4:5], s[0:1], v12, s11, v[8:9]
	global_store_dwordx4 v[4:5], v[0:3], off nt
	ds_read_b128 v[0:3], v11 offset:16896
	ds_read_b128 v[4:7], v11 offset:16912
	v_add_u32_e32 v12, 32, v10
	s_waitcnt lgkmcnt(1)
	v_cvt_pk_bf16_f32 v0, v0, v1
	v_cvt_pk_bf16_f32 v1, v2, v3
	s_waitcnt lgkmcnt(0)
	v_cvt_pk_bf16_f32 v2, v4, v5
	v_cvt_pk_bf16_f32 v3, v6, v7
	v_mad_i64_i32 v[4:5], s[0:1], v12, s11, v[8:9]
	global_store_dwordx4 v[4:5], v[0:3], off nt
	ds_read_b128 v[0:3], v11 offset:25344
	ds_read_b128 v[4:7], v11 offset:25360
	v_add_u32_e32 v12, 48, v10
	s_waitcnt lgkmcnt(1)
	v_cvt_pk_bf16_f32 v0, v0, v1
	v_cvt_pk_bf16_f32 v1, v2, v3
	s_waitcnt lgkmcnt(0)
	v_cvt_pk_bf16_f32 v2, v4, v5
	v_cvt_pk_bf16_f32 v3, v6, v7
	v_mad_i64_i32 v[4:5], s[0:1], v12, s11, v[8:9]
	global_store_dwordx4 v[4:5], v[0:3], off nt
	ds_read_b128 v[0:3], v11 offset:33792
	ds_read_b128 v[4:7], v11 offset:33808
	v_add_u32_e32 v12, 64, v10
	s_waitcnt lgkmcnt(1)
	v_cvt_pk_bf16_f32 v0, v0, v1
	v_cvt_pk_bf16_f32 v1, v2, v3
	s_waitcnt lgkmcnt(0)
	v_cvt_pk_bf16_f32 v2, v4, v5
	v_cvt_pk_bf16_f32 v3, v6, v7
	v_mad_i64_i32 v[4:5], s[0:1], v12, s11, v[8:9]
	global_store_dwordx4 v[4:5], v[0:3], off nt
	ds_read_b128 v[0:3], v11 offset:42240
	ds_read_b128 v[4:7], v11 offset:42256
	v_add_u32_e32 v12, 0x50, v10
	s_waitcnt lgkmcnt(1)
	v_cvt_pk_bf16_f32 v0, v0, v1
	v_cvt_pk_bf16_f32 v1, v2, v3
	s_waitcnt lgkmcnt(0)
	v_cvt_pk_bf16_f32 v2, v4, v5
	v_cvt_pk_bf16_f32 v3, v6, v7
	v_mad_i64_i32 v[4:5], s[0:1], v12, s11, v[8:9]
	global_store_dwordx4 v[4:5], v[0:3], off nt
	ds_read_b128 v[0:3], v11 offset:50688
	ds_read_b128 v[4:7], v11 offset:50704
	v_add_u32_e32 v12, 0x60, v10
	v_add_u32_e32 v10, 0x70, v10
	s_waitcnt lgkmcnt(1)
	v_cvt_pk_bf16_f32 v0, v0, v1
	v_cvt_pk_bf16_f32 v1, v2, v3
	s_waitcnt lgkmcnt(0)
	v_cvt_pk_bf16_f32 v2, v4, v5
	v_cvt_pk_bf16_f32 v3, v6, v7
	v_mad_i64_i32 v[4:5], s[0:1], v12, s11, v[8:9]
	global_store_dwordx4 v[4:5], v[0:3], off nt
	ds_read_b128 v[0:3], v11 offset:59136
	ds_read_b128 v[4:7], v11 offset:59152
	s_waitcnt lgkmcnt(1)
	v_cvt_pk_bf16_f32 v0, v0, v1
	v_cvt_pk_bf16_f32 v1, v2, v3
	s_waitcnt lgkmcnt(0)
	v_cvt_pk_bf16_f32 v2, v4, v5
	v_cvt_pk_bf16_f32 v3, v6, v7
	v_mad_i64_i32 v[4:5], s[0:1], v10, s11, v[8:9]
	global_store_dwordx4 v[4:5], v[0:3], off nt
	s_cbranch_scc0 .LBB0_313
